# snake MFMA order + non-scaled v_mfma_f32_16x16x128_f8f6f4 (scale was 2^0, same fp8 math, 8-byte encoding)
# speedup vs baseline: 1.0101x; 1.0101x over previous
.LBB0_197:
	s_ashr_i32 s47, s46, 31
	ds_read_b128 v[18:21], v190
	ds_read_b128 v[22:25], v190 offset:1024
	ds_read_b128 v[26:29], v190 offset:2048
	ds_read_b128 v[30:33], v190 offset:3072
	ds_read_b128 v[2:5], v190 offset:16384
	ds_read_b128 v[6:9], v190 offset:17408
	ds_read_b128 v[10:13], v190 offset:18432
	ds_read_b128 v[14:17], v190 offset:19456
	s_lshl_b64 s[8:9], s[46:47], 20
	s_add_u32 s48, s22, s8
	s_addc_u32 s49, s23, s9
	s_and_b64 s[8:9], s[2:3], exec
	s_cselect_b32 s47, s49, s73
	s_cselect_b32 s70, s48, s72
	s_ashr_i32 s45, s44, 31
	s_lshl_b64 s[8:9], s[44:45], 20
	s_add_u32 s50, s27, s8
	s_addc_u32 s51, s68, s9
	s_and_b64 s[8:9], s[2:3], exec
	s_cselect_b32 s45, s51, s55
	s_cselect_b32 s71, s50, s54
	s_add_u32 s8, s72, 0x80080
	s_addc_u32 s9, s73, 0
	s_mov_b32 m0, s92
	v_lshl_add_u64 v[216:217], s[8:9], 0, v[164:165]
	ds_read_b128 v[180:183], v191
	ds_read_b128 v[184:187], v191 offset:1024
	ds_read_b128 v[192:195], v191 offset:2048
	ds_read_b128 v[196:199], v191 offset:3072
	ds_read_b128 v[200:203], v191 offset:4096
	ds_read_b128 v[204:207], v191 offset:5120
	ds_read_b128 v[208:211], v191 offset:6144
	ds_read_b128 v[212:215], v191 offset:7168
	global_load_lds_dwordx4 v[216:217], off
	v_lshl_add_u64 v[216:217], s[8:9], 0, v[168:169]
	s_mov_b32 m0, s93
	s_nop 0
	global_load_lds_dwordx4 v[216:217], off
	s_waitcnt vmcnt(8)
	s_waitcnt lgkmcnt(0)
	s_barrier
	s_setprio 1
	s_waitcnt lgkmcnt(0)
	v_mfma_f32_16x16x128_f8f6f4 v[158:161], v[18:25], v[180:187], 0
	v_mfma_f32_16x16x128_f8f6f4 v[154:157], v[26:33], v[180:187], 0
	v_mfma_f32_16x16x128_f8f6f4 v[146:149], v[26:33], v[192:199], 0
	v_mfma_f32_16x16x128_f8f6f4 v[150:153], v[18:25], v[192:199], 0
	v_mfma_f32_16x16x128_f8f6f4 v[142:145], v[18:25], v[200:207], 0
	v_mfma_f32_16x16x128_f8f6f4 v[138:141], v[26:33], v[200:207], 0
	v_mfma_f32_16x16x128_f8f6f4 v[130:133], v[26:33], v[208:215], 0
	v_mfma_f32_16x16x128_f8f6f4 v[134:137], v[18:25], v[208:215], 0
	s_setprio 0
	s_setprio 1
	v_mfma_f32_16x16x128_f8f6f4 v[102:105], v[2:9], v[208:215], 0
	v_mfma_f32_16x16x128_f8f6f4 v[98:101], v[10:17], v[208:215], 0
	v_mfma_f32_16x16x128_f8f6f4 v[106:109], v[10:17], v[200:207], 0
	v_mfma_f32_16x16x128_f8f6f4 v[110:113], v[2:9], v[200:207], 0
	v_mfma_f32_16x16x128_f8f6f4 v[118:121], v[2:9], v[192:199], 0
	v_mfma_f32_16x16x128_f8f6f4 v[114:117], v[10:17], v[192:199], 0
	v_mfma_f32_16x16x128_f8f6f4 v[122:125], v[10:17], v[180:187], 0
	v_mfma_f32_16x16x128_f8f6f4 v[126:129], v[2:9], v[180:187], 0
	s_setprio 0
	s_barrier
	v_lshl_add_u64 v[180:181], s[54:55], 0, v[166:167]
	s_mov_b32 m0, s77
	v_lshl_add_u64 v[182:183], v[180:181], 0, s[16:17]
	ds_read_b128 v[192:195], v191 offset:16384
	ds_read_b128 v[196:199], v191 offset:17408
	ds_read_b128 v[200:203], v191 offset:18432
	ds_read_b128 v[204:207], v191 offset:19456
	ds_read_b128 v[208:211], v191 offset:20480
	ds_read_b128 v[212:215], v191 offset:21504
	ds_read_b128 v[216:219], v191 offset:22528
	ds_read_b128 v[220:223], v191 offset:23552
	global_load_lds_dwordx4 v[182:183], off
	v_lshl_add_u64 v[182:183], s[54:55], 0, v[170:171]
	s_add_u32 s8, s54, 0x80100
	v_lshl_add_u64 v[184:185], v[182:183], 0, s[16:17]
	s_mov_b32 m0, s78
	s_addc_u32 s9, s55, 0
	global_load_lds_dwordx4 v[184:185], off
	v_lshl_add_u64 v[184:185], s[8:9], 0, v[166:167]
	s_mov_b32 m0, s79
	s_nop 0
	global_load_lds_dwordx4 v[184:185], off
	v_lshl_add_u64 v[184:185], s[8:9], 0, v[170:171]
	s_mov_b32 m0, s80
	s_nop 0
	global_load_lds_dwordx4 v[184:185], off
	v_lshl_add_u64 v[184:185], s[72:73], 0, v[164:165]
	v_lshl_add_u64 v[186:187], v[184:185], 0, s[16:17]
	s_mov_b32 m0, s53
	s_nop 0
	global_load_lds_dwordx4 v[186:187], off
	v_lshl_add_u64 v[186:187], s[72:73], 0, v[168:169]
	v_lshl_add_u64 v[224:225], v[186:187], 0, s[16:17]
	s_mov_b32 m0, s81
	s_nop 0
	global_load_lds_dwordx4 v[224:225], off
	s_waitcnt vmcnt(8)
	s_waitcnt lgkmcnt(0)
	s_barrier
	s_setprio 1
	s_waitcnt lgkmcnt(0)
	v_mfma_f32_16x16x128_f8f6f4 v[94:97], v[18:25], v[192:199], 0
	v_mfma_f32_16x16x128_f8f6f4 v[90:93], v[26:33], v[192:199], 0
	v_mfma_f32_16x16x128_f8f6f4 v[82:85], v[26:33], v[200:207], 0
	v_mfma_f32_16x16x128_f8f6f4 v[86:89], v[18:25], v[200:207], 0
	v_mfma_f32_16x16x128_f8f6f4 v[78:81], v[18:25], v[208:215], 0
	v_mfma_f32_16x16x128_f8f6f4 v[74:77], v[26:33], v[208:215], 0
	v_mfma_f32_16x16x128_f8f6f4 v[66:69], v[26:33], v[216:223], 0
	v_mfma_f32_16x16x128_f8f6f4 v[70:73], v[18:25], v[216:223], 0
	s_setprio 0
	s_setprio 1
	v_mfma_f32_16x16x128_f8f6f4 v[38:41], v[2:9], v[216:223], 0
	v_mfma_f32_16x16x128_f8f6f4 v[34:37], v[10:17], v[216:223], 0
	v_mfma_f32_16x16x128_f8f6f4 v[42:45], v[10:17], v[208:215], 0
	v_mfma_f32_16x16x128_f8f6f4 v[46:49], v[2:9], v[208:215], 0
	v_mfma_f32_16x16x128_f8f6f4 v[54:57], v[2:9], v[200:207], 0
	v_mfma_f32_16x16x128_f8f6f4 v[50:53], v[10:17], v[200:207], 0
	v_mfma_f32_16x16x128_f8f6f4 v[58:61], v[10:17], v[192:199], 0
	v_mfma_f32_16x16x128_f8f6f4 v[62:65], v[2:9], v[192:199], 0
	s_setprio 0
	s_barrier
	ds_read_b128 v[18:21], v190 offset:32768
	ds_read_b128 v[22:25], v190 offset:33792
	ds_read_b128 v[26:29], v190 offset:34816
	ds_read_b128 v[30:33], v190 offset:35840
	ds_read_b128 v[2:5], v190 offset:49152
	ds_read_b128 v[6:9], v190 offset:50176
	ds_read_b128 v[10:13], v190 offset:51200
	ds_read_b128 v[14:17], v190 offset:52224
	s_add_u32 s8, s72, 0x80100
	s_addc_u32 s9, s73, 0
	s_mov_b32 m0, s82
	v_lshl_add_u64 v[224:225], s[8:9], 0, v[164:165]
	ds_read_b128 v[192:195], v191 offset:32768
	ds_read_b128 v[196:199], v191 offset:33792
	ds_read_b128 v[200:203], v191 offset:34816
	ds_read_b128 v[204:207], v191 offset:35840
	ds_read_b128 v[208:211], v191 offset:36864
	ds_read_b128 v[212:215], v191 offset:37888
	ds_read_b128 v[216:219], v191 offset:38912
	ds_read_b128 v[220:223], v191 offset:39936
	global_load_lds_dwordx4 v[224:225], off
	v_lshl_add_u64 v[224:225], s[8:9], 0, v[168:169]
	s_mov_b32 m0, s83
	s_nop 0
	global_load_lds_dwordx4 v[224:225], off
	s_waitcnt vmcnt(8)
	s_waitcnt lgkmcnt(0)
	s_barrier
	s_setprio 1
	s_waitcnt lgkmcnt(0)
	v_mfma_f32_16x16x128_f8f6f4 v[158:161], v[18:25], v[192:199], v[158:161]
	v_mfma_f32_16x16x128_f8f6f4 v[154:157], v[26:33], v[192:199], v[154:157]
	v_mfma_f32_16x16x128_f8f6f4 v[146:149], v[26:33], v[200:207], v[146:149]
	v_mfma_f32_16x16x128_f8f6f4 v[150:153], v[18:25], v[200:207], v[150:153]
	v_mfma_f32_16x16x128_f8f6f4 v[142:145], v[18:25], v[208:215], v[142:145]
	v_mfma_f32_16x16x128_f8f6f4 v[138:141], v[26:33], v[208:215], v[138:141]
	v_mfma_f32_16x16x128_f8f6f4 v[130:133], v[26:33], v[216:223], v[130:133]
	v_mfma_f32_16x16x128_f8f6f4 v[134:137], v[18:25], v[216:223], v[134:137]
	s_setprio 0
	s_setprio 1
	v_mfma_f32_16x16x128_f8f6f4 v[102:105], v[2:9], v[216:223], v[102:105]
	v_mfma_f32_16x16x128_f8f6f4 v[98:101], v[10:17], v[216:223], v[98:101]
	v_mfma_f32_16x16x128_f8f6f4 v[106:109], v[10:17], v[208:215], v[106:109]
	v_mfma_f32_16x16x128_f8f6f4 v[110:113], v[2:9], v[208:215], v[110:113]
	v_mfma_f32_16x16x128_f8f6f4 v[118:121], v[2:9], v[200:207], v[118:121]
	v_mfma_f32_16x16x128_f8f6f4 v[114:117], v[10:17], v[200:207], v[114:117]
	v_mfma_f32_16x16x128_f8f6f4 v[122:125], v[10:17], v[192:199], v[122:125]
	v_mfma_f32_16x16x128_f8f6f4 v[126:129], v[2:9], v[192:199], v[126:129]
	s_setprio 0
	s_barrier
	s_mov_b32 m0, s86
	v_lshl_add_u64 v[180:181], v[180:181], 0, s[20:21]
	s_add_u32 s8, s54, 0x80180
	ds_read_b128 v[192:195], v191 offset:49152
	ds_read_b128 v[196:199], v191 offset:50176
	ds_read_b128 v[200:203], v191 offset:51200
	ds_read_b128 v[204:207], v191 offset:52224
	ds_read_b128 v[208:211], v191 offset:53248
	ds_read_b128 v[212:215], v191 offset:54272
	ds_read_b128 v[216:219], v191 offset:55296
	ds_read_b128 v[220:223], v191 offset:56320
	global_load_lds_dwordx4 v[180:181], off
	v_lshl_add_u64 v[180:181], v[182:183], 0, s[20:21]
	s_mov_b32 m0, s87
	s_addc_u32 s9, s55, 0
	global_load_lds_dwordx4 v[180:181], off
	v_lshl_add_u64 v[180:181], s[8:9], 0, v[166:167]
	s_mov_b32 m0, s90
	s_nop 0
	global_load_lds_dwordx4 v[180:181], off
	v_lshl_add_u64 v[180:181], s[8:9], 0, v[170:171]
	s_mov_b32 m0, s91
	s_nop 0
	global_load_lds_dwordx4 v[180:181], off
	v_lshl_add_u64 v[180:181], v[184:185], 0, s[20:21]
	s_mov_b32 m0, s88
	s_nop 0
	global_load_lds_dwordx4 v[180:181], off
	v_lshl_add_u64 v[180:181], v[186:187], 0, s[20:21]
	s_mov_b32 m0, s89
	s_nop 0
	global_load_lds_dwordx4 v[180:181], off
	s_waitcnt vmcnt(8)
	s_waitcnt lgkmcnt(0)
	s_barrier
	s_setprio 1
	s_waitcnt lgkmcnt(0)
	v_mfma_f32_16x16x128_f8f6f4 v[94:97], v[18:25], v[192:199], v[94:97]
	v_mfma_f32_16x16x128_f8f6f4 v[90:93], v[26:33], v[192:199], v[90:93]
	v_mfma_f32_16x16x128_f8f6f4 v[82:85], v[26:33], v[200:207], v[82:85]
	v_mfma_f32_16x16x128_f8f6f4 v[86:89], v[18:25], v[200:207], v[86:89]
	v_mfma_f32_16x16x128_f8f6f4 v[78:81], v[18:25], v[208:215], v[78:81]
	v_mfma_f32_16x16x128_f8f6f4 v[74:77], v[26:33], v[208:215], v[74:77]
	v_mfma_f32_16x16x128_f8f6f4 v[66:69], v[26:33], v[216:223], v[66:69]
	v_mfma_f32_16x16x128_f8f6f4 v[70:73], v[18:25], v[216:223], v[70:73]
	s_setprio 0
	s_setprio 1
	v_mfma_f32_16x16x128_f8f6f4 v[38:41], v[2:9], v[216:223], v[38:41]
	v_mfma_f32_16x16x128_f8f6f4 v[34:37], v[10:17], v[216:223], v[34:37]
	v_mfma_f32_16x16x128_f8f6f4 v[42:45], v[10:17], v[208:215], v[42:45]
	v_mfma_f32_16x16x128_f8f6f4 v[46:49], v[2:9], v[208:215], v[46:49]
	v_mfma_f32_16x16x128_f8f6f4 v[54:57], v[2:9], v[200:207], v[54:57]
	v_mfma_f32_16x16x128_f8f6f4 v[50:53], v[10:17], v[200:207], v[50:53]
	v_mfma_f32_16x16x128_f8f6f4 v[58:61], v[10:17], v[192:199], v[58:61]
	v_mfma_f32_16x16x128_f8f6f4 v[62:65], v[2:9], v[192:199], v[62:65]
	s_setprio 0
	s_barrier
	s_add_u32 s72, s72, 0x80180
	s_addc_u32 s73, s73, 0
	s_add_u32 s8, s54, 0x200
	s_addc_u32 s9, s55, 0
	s_mov_b32 s62, 0
.LBB0_198:
	ds_read_b128 v[2:5], v190
	ds_read_b128 v[6:9], v190 offset:1024
	ds_read_b128 v[18:21], v190 offset:2048
	ds_read_b128 v[22:25], v190 offset:3072
	ds_read_b128 v[26:29], v190 offset:16384
	ds_read_b128 v[30:33], v190 offset:17408
	ds_read_b128 v[180:183], v190 offset:18432
	ds_read_b128 v[184:187], v190 offset:19456
	s_add_u32 s54, s72, 0xfff80080
	s_addc_u32 s55, s73, -1
	s_cmp_eq_u32 s62, 28
	s_cselect_b32 s75, s47, s55
	s_cselect_b32 s74, s70, s54
	s_cselect_b32 s55, s45, s9
	s_cselect_b32 s54, s71, s8
	s_mov_b32 m0, s92
	v_lshl_add_u64 v[216:217], s[72:73], 0, v[172:173]
	ds_read_b128 v[10:13], v191
	ds_read_b128 v[14:17], v191 offset:1024
	ds_read_b128 v[192:195], v191 offset:2048
	ds_read_b128 v[196:199], v191 offset:3072
	ds_read_b128 v[200:203], v191 offset:4096
	ds_read_b128 v[204:207], v191 offset:5120
	ds_read_b128 v[208:211], v191 offset:6144
	ds_read_b128 v[212:215], v191 offset:7168
	global_load_lds_dwordx4 v[216:217], off
	v_lshl_add_u64 v[216:217], s[72:73], 0, v[174:175]
	s_mov_b32 m0, s93
	s_nop 0
	global_load_lds_dwordx4 v[216:217], off
	s_waitcnt vmcnt(8)
	s_waitcnt lgkmcnt(0)
	s_barrier
	s_setprio 1
	s_waitcnt lgkmcnt(0)
	v_mfma_f32_16x16x128_f8f6f4 v[158:161], v[2:9], v[10:17], v[158:161]
	v_mfma_f32_16x16x128_f8f6f4 v[154:157], v[18:25], v[10:17], v[154:157]
	v_mfma_f32_16x16x128_f8f6f4 v[146:149], v[18:25], v[192:199], v[146:149]
	v_mfma_f32_16x16x128_f8f6f4 v[150:153], v[2:9], v[192:199], v[150:153]
	v_mfma_f32_16x16x128_f8f6f4 v[142:145], v[2:9], v[200:207], v[142:145]
	v_mfma_f32_16x16x128_f8f6f4 v[138:141], v[18:25], v[200:207], v[138:141]
	v_mfma_f32_16x16x128_f8f6f4 v[130:133], v[18:25], v[208:215], v[130:133]
	v_mfma_f32_16x16x128_f8f6f4 v[134:137], v[2:9], v[208:215], v[134:137]
	s_setprio 0
	s_setprio 1
	v_mfma_f32_16x16x128_f8f6f4 v[102:105], v[26:33], v[208:215], v[102:105]
	v_mfma_f32_16x16x128_f8f6f4 v[98:101], v[180:187], v[208:215], v[98:101]
	v_mfma_f32_16x16x128_f8f6f4 v[106:109], v[180:187], v[200:207], v[106:109]
	v_mfma_f32_16x16x128_f8f6f4 v[110:113], v[26:33], v[200:207], v[110:113]
	v_mfma_f32_16x16x128_f8f6f4 v[118:121], v[26:33], v[192:199], v[118:121]
	v_mfma_f32_16x16x128_f8f6f4 v[114:117], v[180:187], v[192:199], v[114:117]
	v_mfma_f32_16x16x128_f8f6f4 v[122:125], v[180:187], v[10:17], v[122:125]
	v_mfma_f32_16x16x128_f8f6f4 v[126:129], v[26:33], v[10:17], v[126:129]
	s_setprio 0
	s_barrier
	s_mov_b32 m0, s77
	v_lshl_add_u64 v[10:11], s[54:55], 0, v[166:167]
	s_add_u32 vcc_lo, s54, 0x80000
	ds_read_b128 v[192:195], v191 offset:16384
	ds_read_b128 v[196:199], v191 offset:17408
	ds_read_b128 v[200:203], v191 offset:18432
	ds_read_b128 v[204:207], v191 offset:19456
	ds_read_b128 v[208:211], v191 offset:20480
	ds_read_b128 v[212:215], v191 offset:21504
	ds_read_b128 v[216:219], v191 offset:22528
	ds_read_b128 v[220:223], v191 offset:23552
	global_load_lds_dwordx4 v[10:11], off
	v_lshl_add_u64 v[12:13], s[54:55], 0, v[170:171]
	s_mov_b32 m0, s78
	s_addc_u32 vcc_hi, s55, 0
	global_load_lds_dwordx4 v[12:13], off
	v_lshl_add_u64 v[14:15], vcc, 0, v[166:167]
	s_mov_b32 m0, s79
	v_lshl_add_u64 v[16:17], s[74:75], 0, v[168:169]
	global_load_lds_dwordx4 v[14:15], off
	v_lshl_add_u64 v[14:15], vcc, 0, v[170:171]
	s_mov_b32 m0, s80
	s_nop 0
	global_load_lds_dwordx4 v[14:15], off
	v_lshl_add_u64 v[14:15], s[74:75], 0, v[164:165]
	s_mov_b32 m0, s53
	s_nop 0
	global_load_lds_dwordx4 v[14:15], off
	s_mov_b32 m0, s81
	s_nop 0
	global_load_lds_dwordx4 v[16:17], off
	s_waitcnt vmcnt(8)
	s_waitcnt lgkmcnt(0)
	s_barrier
	s_setprio 1
	s_waitcnt lgkmcnt(0)
	v_mfma_f32_16x16x128_f8f6f4 v[94:97], v[2:9], v[192:199], v[94:97]
	v_mfma_f32_16x16x128_f8f6f4 v[90:93], v[18:25], v[192:199], v[90:93]
	v_mfma_f32_16x16x128_f8f6f4 v[82:85], v[18:25], v[200:207], v[82:85]
	v_mfma_f32_16x16x128_f8f6f4 v[86:89], v[2:9], v[200:207], v[86:89]
	v_mfma_f32_16x16x128_f8f6f4 v[78:81], v[2:9], v[208:215], v[78:81]
	v_mfma_f32_16x16x128_f8f6f4 v[74:77], v[18:25], v[208:215], v[74:77]
	v_mfma_f32_16x16x128_f8f6f4 v[66:69], v[18:25], v[216:223], v[66:69]
	v_mfma_f32_16x16x128_f8f6f4 v[70:73], v[2:9], v[216:223], v[70:73]
	s_setprio 0
	s_setprio 1
	v_mfma_f32_16x16x128_f8f6f4 v[38:41], v[26:33], v[216:223], v[38:41]
	v_mfma_f32_16x16x128_f8f6f4 v[34:37], v[180:187], v[216:223], v[34:37]
	v_mfma_f32_16x16x128_f8f6f4 v[42:45], v[180:187], v[208:215], v[42:45]
	v_mfma_f32_16x16x128_f8f6f4 v[46:49], v[26:33], v[208:215], v[46:49]
	v_mfma_f32_16x16x128_f8f6f4 v[54:57], v[26:33], v[200:207], v[54:57]
	v_mfma_f32_16x16x128_f8f6f4 v[50:53], v[180:187], v[200:207], v[50:53]
	v_mfma_f32_16x16x128_f8f6f4 v[58:61], v[180:187], v[192:199], v[58:61]
	v_mfma_f32_16x16x128_f8f6f4 v[62:65], v[26:33], v[192:199], v[62:65]
	s_setprio 0
	s_barrier
	ds_read_b128 v[18:21], v190 offset:32768
	ds_read_b128 v[22:25], v190 offset:33792
	ds_read_b128 v[26:29], v190 offset:34816
	ds_read_b128 v[30:33], v190 offset:35840
	ds_read_b128 v[2:5], v190 offset:49152
	ds_read_b128 v[6:9], v190 offset:50176
	ds_read_b128 v[180:183], v190 offset:51200
	ds_read_b128 v[184:187], v190 offset:52224
	s_add_u32 s74, s74, 0x80000
	s_addc_u32 s75, s75, 0
	s_mov_b32 m0, s82
	v_lshl_add_u64 v[224:225], s[74:75], 0, v[164:165]
	ds_read_b128 v[192:195], v191 offset:32768
	ds_read_b128 v[196:199], v191 offset:33792
	ds_read_b128 v[200:203], v191 offset:34816
	ds_read_b128 v[204:207], v191 offset:35840
	ds_read_b128 v[208:211], v191 offset:36864
	ds_read_b128 v[212:215], v191 offset:37888
	ds_read_b128 v[216:219], v191 offset:38912
	ds_read_b128 v[220:223], v191 offset:39936
	global_load_lds_dwordx4 v[224:225], off
	v_lshl_add_u64 v[224:225], s[74:75], 0, v[168:169]
	s_mov_b32 m0, s83
	s_nop 0
	global_load_lds_dwordx4 v[224:225], off
	s_waitcnt vmcnt(8)
	s_waitcnt lgkmcnt(0)
	s_barrier
	s_setprio 1
	s_waitcnt lgkmcnt(0)
	v_mfma_f32_16x16x128_f8f6f4 v[158:161], v[18:25], v[192:199], v[158:161]
	v_mfma_f32_16x16x128_f8f6f4 v[154:157], v[26:33], v[192:199], v[154:157]
	v_mfma_f32_16x16x128_f8f6f4 v[146:149], v[26:33], v[200:207], v[146:149]
	v_mfma_f32_16x16x128_f8f6f4 v[150:153], v[18:25], v[200:207], v[150:153]
	v_mfma_f32_16x16x128_f8f6f4 v[142:145], v[18:25], v[208:215], v[142:145]
	v_mfma_f32_16x16x128_f8f6f4 v[138:141], v[26:33], v[208:215], v[138:141]
	v_mfma_f32_16x16x128_f8f6f4 v[130:133], v[26:33], v[216:223], v[130:133]
	v_mfma_f32_16x16x128_f8f6f4 v[134:137], v[18:25], v[216:223], v[134:137]
	s_setprio 0
	s_setprio 1
	v_mfma_f32_16x16x128_f8f6f4 v[102:105], v[2:9], v[216:223], v[102:105]
	v_mfma_f32_16x16x128_f8f6f4 v[98:101], v[180:187], v[216:223], v[98:101]
	v_mfma_f32_16x16x128_f8f6f4 v[106:109], v[180:187], v[208:215], v[106:109]
	v_mfma_f32_16x16x128_f8f6f4 v[110:113], v[2:9], v[208:215], v[110:113]
	v_mfma_f32_16x16x128_f8f6f4 v[118:121], v[2:9], v[200:207], v[118:121]
	v_mfma_f32_16x16x128_f8f6f4 v[114:117], v[180:187], v[200:207], v[114:117]
	v_mfma_f32_16x16x128_f8f6f4 v[122:125], v[180:187], v[192:199], v[122:125]
	v_mfma_f32_16x16x128_f8f6f4 v[126:129], v[2:9], v[192:199], v[126:129]
	s_setprio 0
	s_barrier
	s_mov_b32 m0, s86
	v_lshl_add_u64 v[10:11], v[10:11], 0, s[4:5]
	s_add_u32 s54, s54, 0x80080
	ds_read_b128 v[192:195], v191 offset:49152
	ds_read_b128 v[196:199], v191 offset:50176
	ds_read_b128 v[200:203], v191 offset:51200
	ds_read_b128 v[204:207], v191 offset:52224
	ds_read_b128 v[208:211], v191 offset:53248
	ds_read_b128 v[212:215], v191 offset:54272
	ds_read_b128 v[216:219], v191 offset:55296
	ds_read_b128 v[220:223], v191 offset:56320
	global_load_lds_dwordx4 v[10:11], off
	v_lshl_add_u64 v[10:11], v[12:13], 0, s[4:5]
	s_mov_b32 m0, s87
	s_addc_u32 s55, s55, 0
	global_load_lds_dwordx4 v[10:11], off
	v_lshl_add_u64 v[10:11], s[54:55], 0, v[166:167]
	s_mov_b32 m0, s90
	s_nop 0
	global_load_lds_dwordx4 v[10:11], off
	v_lshl_add_u64 v[10:11], s[54:55], 0, v[170:171]
	s_mov_b32 m0, s91
	s_nop 0
	global_load_lds_dwordx4 v[10:11], off
	v_lshl_add_u64 v[10:11], v[14:15], 0, s[4:5]
	s_mov_b32 m0, s88
	s_nop 0
	global_load_lds_dwordx4 v[10:11], off
	v_lshl_add_u64 v[10:11], v[16:17], 0, s[4:5]
	s_mov_b32 m0, s89
	s_nop 0
	global_load_lds_dwordx4 v[10:11], off
	s_waitcnt vmcnt(8)
	s_waitcnt lgkmcnt(0)
	s_barrier
	s_setprio 1
	s_waitcnt lgkmcnt(0)
	v_mfma_f32_16x16x128_f8f6f4 v[94:97], v[18:25], v[192:199], v[94:97]
	v_mfma_f32_16x16x128_f8f6f4 v[90:93], v[26:33], v[192:199], v[90:93]
	v_mfma_f32_16x16x128_f8f6f4 v[82:85], v[26:33], v[200:207], v[82:85]
	v_mfma_f32_16x16x128_f8f6f4 v[86:89], v[18:25], v[200:207], v[86:89]
	v_mfma_f32_16x16x128_f8f6f4 v[78:81], v[18:25], v[208:215], v[78:81]
	v_mfma_f32_16x16x128_f8f6f4 v[74:77], v[26:33], v[208:215], v[74:77]
	v_mfma_f32_16x16x128_f8f6f4 v[66:69], v[26:33], v[216:223], v[66:69]
	v_mfma_f32_16x16x128_f8f6f4 v[70:73], v[18:25], v[216:223], v[70:73]
	s_setprio 0
	s_setprio 1
	v_mfma_f32_16x16x128_f8f6f4 v[38:41], v[2:9], v[216:223], v[38:41]
	v_mfma_f32_16x16x128_f8f6f4 v[34:37], v[180:187], v[216:223], v[34:37]
	v_mfma_f32_16x16x128_f8f6f4 v[42:45], v[180:187], v[208:215], v[42:45]
	v_mfma_f32_16x16x128_f8f6f4 v[46:49], v[2:9], v[208:215], v[46:49]
	v_mfma_f32_16x16x128_f8f6f4 v[54:57], v[2:9], v[200:207], v[54:57]
	v_mfma_f32_16x16x128_f8f6f4 v[50:53], v[180:187], v[200:207], v[50:53]
	v_mfma_f32_16x16x128_f8f6f4 v[58:61], v[180:187], v[192:199], v[58:61]
	v_mfma_f32_16x16x128_f8f6f4 v[62:65], v[2:9], v[192:199], v[62:65]
	s_setprio 0
	s_barrier
	s_add_i32 s62, s62, 2
	s_add_u32 s72, s72, 0x100
	s_addc_u32 s73, s73, 0
	s_add_u32 s8, s8, 0x100
	s_addc_u32 s9, s9, 0
	s_cmp_gt_u32 s62, 29
	s_cbranch_scc0 .LBB0_198
	s_and_b64 vcc, exec, s[6:7]
	s_cbranch_vccz .LBB0_201
	s_barrier

.LBB0_282:
	ds_read_b128 v[2:5], v187
	ds_read_b128 v[6:9], v187 offset:1024
	ds_read_b128 v[174:177], v187 offset:2048
	ds_read_b128 v[178:181], v187 offset:3072
	ds_read_b128 v[190:193], v187 offset:16384
	ds_read_b128 v[194:197], v187 offset:17408
	ds_read_b128 v[198:201], v187 offset:18432
	ds_read_b128 v[202:205], v187 offset:19456
	s_add_u32 s49, s52, 0x100
	s_addc_u32 s71, s53, 0
	s_and_b64 s[62:63], s[54:55], exec
	s_cselect_b32 s73, s1, s71
	s_cselect_b32 s72, s0, s49
	s_add_u32 s49, s50, 0x100
	s_addc_u32 s62, s51, 0
	s_and_b64 s[54:55], s[54:55], exec
	s_cselect_b32 s55, s5, s62
	s_cselect_b32 s54, s4, s49
	s_add_u32 s62, s52, 0x158080
	s_addc_u32 s63, s53, 0
	s_add_i32 s49, s33, 0xc000
	v_lshl_add_u64 v[182:183], s[62:63], 0, v[154:155]
	s_mov_b32 m0, s49
	s_add_i32 s71, s33, 0xe000
	ds_read_b128 v[206:209], v188
	ds_read_b128 v[210:213], v188 offset:1024
	ds_read_b128 v[214:217], v188 offset:2048
	ds_read_b128 v[218:221], v188 offset:3072
	ds_read_b128 v[222:225], v188 offset:4096
	ds_read_b128 v[226:229], v188 offset:5120
	ds_read_b128 v[230:233], v188 offset:6144
	ds_read_b128 v[234:237], v188 offset:7168
	global_load_lds_dwordx4 v[182:183], off
	v_lshl_add_u64 v[182:183], s[62:63], 0, v[158:159]
	s_mov_b32 m0, s71
	s_nop 0
	global_load_lds_dwordx4 v[182:183], off
	s_waitcnt vmcnt(8)
	s_waitcnt lgkmcnt(0)
	s_barrier
	s_setprio 1
	s_waitcnt lgkmcnt(0)
	v_mfma_f32_16x16x128_f8f6f4 v[134:137], v[2:9], v[206:213], 0
	v_mfma_f32_16x16x128_f8f6f4 v[130:133], v[174:181], v[206:213], 0
	v_mfma_f32_16x16x128_f8f6f4 v[122:125], v[174:181], v[214:221], 0
	v_mfma_f32_16x16x128_f8f6f4 v[126:129], v[2:9], v[214:221], 0
	v_mfma_f32_16x16x128_f8f6f4 v[118:121], v[2:9], v[222:229], 0
	v_mfma_f32_16x16x128_f8f6f4 v[114:117], v[174:181], v[222:229], 0
	v_mfma_f32_16x16x128_f8f6f4 v[106:109], v[174:181], v[230:237], 0
	v_mfma_f32_16x16x128_f8f6f4 v[110:113], v[2:9], v[230:237], 0
	s_setprio 0
	s_setprio 1
	v_mfma_f32_16x16x128_f8f6f4 v[78:81], v[190:197], v[230:237], 0
	v_mfma_f32_16x16x128_f8f6f4 v[74:77], v[198:205], v[230:237], 0
	v_mfma_f32_16x16x128_f8f6f4 v[82:85], v[198:205], v[222:229], 0
	v_mfma_f32_16x16x128_f8f6f4 v[86:89], v[190:197], v[222:229], 0
	v_mfma_f32_16x16x128_f8f6f4 v[94:97], v[190:197], v[214:221], 0
	v_mfma_f32_16x16x128_f8f6f4 v[90:93], v[198:205], v[214:221], 0
	v_mfma_f32_16x16x128_f8f6f4 v[98:101], v[198:205], v[206:213], 0
	v_mfma_f32_16x16x128_f8f6f4 v[102:105], v[190:197], v[206:213], 0
	s_setprio 0
	s_barrier
	s_mov_b32 m0, s47
	v_lshl_add_u64 v[182:183], s[54:55], 0, v[156:157]
	s_add_u32 s62, s54, 0x158000
	ds_read_b128 v[206:209], v188 offset:16384
	ds_read_b128 v[210:213], v188 offset:17408
	ds_read_b128 v[214:217], v188 offset:18432
	ds_read_b128 v[218:221], v188 offset:19456
	ds_read_b128 v[222:225], v188 offset:20480
	ds_read_b128 v[226:229], v188 offset:21504
	ds_read_b128 v[230:233], v188 offset:22528
	ds_read_b128 v[234:237], v188 offset:23552
	global_load_lds_dwordx4 v[182:183], off
	v_lshl_add_u64 v[238:239], s[54:55], 0, v[160:161]
	s_mov_b32 m0, s68
	s_addc_u32 s63, s55, 0
	global_load_lds_dwordx4 v[238:239], off
	v_lshl_add_u64 v[242:243], s[62:63], 0, v[156:157]
	s_mov_b32 m0, s69
	v_lshl_add_u64 v[244:245], s[72:73], 0, v[158:159]
	global_load_lds_dwordx4 v[242:243], off
	v_lshl_add_u64 v[242:243], s[62:63], 0, v[160:161]
	s_mov_b32 m0, s74
	s_nop 0
	global_load_lds_dwordx4 v[242:243], off
	v_lshl_add_u64 v[242:243], s[72:73], 0, v[154:155]
	s_mov_b32 m0, s33
	s_nop 0
	global_load_lds_dwordx4 v[242:243], off
	s_mov_b32 m0, s75
	s_nop 0
	global_load_lds_dwordx4 v[244:245], off
	s_waitcnt vmcnt(8)
	s_waitcnt lgkmcnt(0)
	s_barrier
	s_setprio 1
	s_waitcnt lgkmcnt(0)
	v_mfma_f32_16x16x128_f8f6f4 v[70:73], v[2:9], v[206:213], 0
	v_mfma_f32_16x16x128_f8f6f4 v[66:69], v[174:181], v[206:213], 0
	v_mfma_f32_16x16x128_f8f6f4 v[58:61], v[174:181], v[214:221], 0
	v_mfma_f32_16x16x128_f8f6f4 v[62:65], v[2:9], v[214:221], 0
	v_mfma_f32_16x16x128_f8f6f4 v[54:57], v[2:9], v[222:229], 0
	v_mfma_f32_16x16x128_f8f6f4 v[50:53], v[174:181], v[222:229], 0
	v_mfma_f32_16x16x128_f8f6f4 v[42:45], v[174:181], v[230:237], 0
	v_mfma_f32_16x16x128_f8f6f4 v[46:49], v[2:9], v[230:237], 0
	s_setprio 0
	s_setprio 1
	v_mfma_f32_16x16x128_f8f6f4 v[14:17], v[190:197], v[230:237], 0
	v_mfma_f32_16x16x128_f8f6f4 v[10:13], v[198:205], v[230:237], 0
	v_mfma_f32_16x16x128_f8f6f4 v[18:21], v[198:205], v[222:229], 0
	v_mfma_f32_16x16x128_f8f6f4 v[22:25], v[190:197], v[222:229], 0
	v_mfma_f32_16x16x128_f8f6f4 v[30:33], v[190:197], v[214:221], 0
	v_mfma_f32_16x16x128_f8f6f4 v[26:29], v[198:205], v[214:221], 0
	v_mfma_f32_16x16x128_f8f6f4 v[34:37], v[198:205], v[206:213], 0
	v_mfma_f32_16x16x128_f8f6f4 v[38:41], v[190:197], v[206:213], 0
	s_setprio 0
	s_barrier
	ds_read_b128 v[2:5], v187 offset:32768
	ds_read_b128 v[6:9], v187 offset:33792
	ds_read_b128 v[174:177], v187 offset:34816
	ds_read_b128 v[178:181], v187 offset:35840
	ds_read_b128 v[190:193], v187 offset:49152
	ds_read_b128 v[194:197], v187 offset:50176
	ds_read_b128 v[198:201], v187 offset:51200
	ds_read_b128 v[202:205], v187 offset:52224
	s_add_u32 s62, s72, 0x158000
	s_addc_u32 s63, s73, 0
	s_mov_b32 m0, s76
	v_lshl_add_u64 v[246:247], s[62:63], 0, v[154:155]
	ds_read_b128 v[206:209], v188 offset:32768
	ds_read_b128 v[210:213], v188 offset:33792
	ds_read_b128 v[214:217], v188 offset:34816
	ds_read_b128 v[218:221], v188 offset:35840
	ds_read_b128 v[222:225], v188 offset:36864
	ds_read_b128 v[226:229], v188 offset:37888
	ds_read_b128 v[230:233], v188 offset:38912
	ds_read_b128 v[234:237], v188 offset:39936
	global_load_lds_dwordx4 v[246:247], off
	v_lshl_add_u64 v[246:247], s[62:63], 0, v[158:159]
	s_mov_b32 m0, s77
	s_nop 0
	global_load_lds_dwordx4 v[246:247], off
	s_waitcnt vmcnt(8)
	s_waitcnt lgkmcnt(0)
	s_barrier
	s_setprio 1
	s_waitcnt lgkmcnt(0)
	v_mfma_f32_16x16x128_f8f6f4 v[134:137], v[2:9], v[206:213], v[134:137]
	v_mfma_f32_16x16x128_f8f6f4 v[130:133], v[174:181], v[206:213], v[130:133]
	v_mfma_f32_16x16x128_f8f6f4 v[122:125], v[174:181], v[214:221], v[122:125]
	v_mfma_f32_16x16x128_f8f6f4 v[126:129], v[2:9], v[214:221], v[126:129]
	v_mfma_f32_16x16x128_f8f6f4 v[118:121], v[2:9], v[222:229], v[118:121]
	v_mfma_f32_16x16x128_f8f6f4 v[114:117], v[174:181], v[222:229], v[114:117]
	v_mfma_f32_16x16x128_f8f6f4 v[106:109], v[174:181], v[230:237], v[106:109]
	v_mfma_f32_16x16x128_f8f6f4 v[110:113], v[2:9], v[230:237], v[110:113]
	s_setprio 0
	s_setprio 1
	v_mfma_f32_16x16x128_f8f6f4 v[78:81], v[190:197], v[230:237], v[78:81]
	v_mfma_f32_16x16x128_f8f6f4 v[74:77], v[198:205], v[230:237], v[74:77]
	v_mfma_f32_16x16x128_f8f6f4 v[82:85], v[198:205], v[222:229], v[82:85]
	v_mfma_f32_16x16x128_f8f6f4 v[86:89], v[190:197], v[222:229], v[86:89]
	v_mfma_f32_16x16x128_f8f6f4 v[94:97], v[190:197], v[214:221], v[94:97]
	v_mfma_f32_16x16x128_f8f6f4 v[90:93], v[198:205], v[214:221], v[90:93]
	v_mfma_f32_16x16x128_f8f6f4 v[98:101], v[198:205], v[206:213], v[98:101]
	v_mfma_f32_16x16x128_f8f6f4 v[102:105], v[190:197], v[206:213], v[102:105]
	s_setprio 0
	s_barrier
	s_mov_b32 m0, s83
	v_lshl_add_u64 v[182:183], v[182:183], 0, s[26:27]
	s_add_u32 s54, s54, 0x158080
	ds_read_b128 v[206:209], v188 offset:49152
	ds_read_b128 v[210:213], v188 offset:50176
	ds_read_b128 v[214:217], v188 offset:51200
	ds_read_b128 v[218:221], v188 offset:52224
	ds_read_b128 v[222:225], v188 offset:53248
	ds_read_b128 v[226:229], v188 offset:54272
	ds_read_b128 v[230:233], v188 offset:55296
	ds_read_b128 v[234:237], v188 offset:56320
	global_load_lds_dwordx4 v[182:183], off
	v_lshl_add_u64 v[182:183], v[238:239], 0, s[26:27]
	s_mov_b32 m0, s84
	s_addc_u32 s55, s55, 0
	global_load_lds_dwordx4 v[182:183], off
	v_lshl_add_u64 v[182:183], s[54:55], 0, v[156:157]
	s_mov_b32 m0, s87
	s_nop 0
	global_load_lds_dwordx4 v[182:183], off
	v_lshl_add_u64 v[182:183], s[54:55], 0, v[160:161]
	s_mov_b32 m0, s88
	s_nop 0
	global_load_lds_dwordx4 v[182:183], off
	v_lshl_add_u64 v[182:183], v[242:243], 0, s[26:27]
	s_mov_b32 m0, s85
	s_nop 0
	global_load_lds_dwordx4 v[182:183], off
	v_lshl_add_u64 v[182:183], v[244:245], 0, s[26:27]
	s_mov_b32 m0, s86
	s_nop 0
	global_load_lds_dwordx4 v[182:183], off
	s_waitcnt vmcnt(8)
	s_waitcnt lgkmcnt(0)
	s_barrier
	s_setprio 1
	s_waitcnt lgkmcnt(0)
	v_mfma_f32_16x16x128_f8f6f4 v[70:73], v[2:9], v[206:213], v[70:73]
	v_mfma_f32_16x16x128_f8f6f4 v[66:69], v[174:181], v[206:213], v[66:69]
	v_mfma_f32_16x16x128_f8f6f4 v[58:61], v[174:181], v[214:221], v[58:61]
	v_mfma_f32_16x16x128_f8f6f4 v[62:65], v[2:9], v[214:221], v[62:65]
	v_mfma_f32_16x16x128_f8f6f4 v[54:57], v[2:9], v[222:229], v[54:57]
	v_mfma_f32_16x16x128_f8f6f4 v[50:53], v[174:181], v[222:229], v[50:53]
	v_mfma_f32_16x16x128_f8f6f4 v[42:45], v[174:181], v[230:237], v[42:45]
	v_mfma_f32_16x16x128_f8f6f4 v[46:49], v[2:9], v[230:237], v[46:49]
	s_setprio 0
	s_setprio 1
	v_mfma_f32_16x16x128_f8f6f4 v[14:17], v[190:197], v[230:237], v[14:17]
	v_mfma_f32_16x16x128_f8f6f4 v[10:13], v[198:205], v[230:237], v[10:13]
	v_mfma_f32_16x16x128_f8f6f4 v[18:21], v[198:205], v[222:229], v[18:21]
	v_mfma_f32_16x16x128_f8f6f4 v[22:25], v[190:197], v[222:229], v[22:25]
	v_mfma_f32_16x16x128_f8f6f4 v[30:33], v[190:197], v[214:221], v[30:33]
	v_mfma_f32_16x16x128_f8f6f4 v[26:29], v[198:205], v[214:221], v[26:29]
	v_mfma_f32_16x16x128_f8f6f4 v[34:37], v[198:205], v[206:213], v[34:37]
	v_mfma_f32_16x16x128_f8f6f4 v[38:41], v[190:197], v[206:213], v[38:41]
	s_setprio 0
	s_barrier
	s_cmp_lt_u32 s95, 3
	s_cbranch_scc1 .LBB0_287
	s_add_u32 s54, s79, s9
	s_addc_u32 s55, s80, s8
	s_add_u32 s52, s52, 0x158180
	s_addc_u32 s53, s53, 0
	s_add_u32 s8, s50, 0x200
	v_lshl_add_u64 v[174:175], v[172:173], 2, s[54:55]
	s_addc_u32 s9, s51, 0
	s_mov_b32 s72, 4
	s_cmp_eq_u32 s95, s72
	s_cselect_b64 s[50:51], -1, 0
	s_cmp_lg_u32 s95, s72
	s_cbranch_scc1 .LBB0_285

.LBB0_285:
	ds_read_b128 v[2:5], v187
	ds_read_b128 v[6:9], v187 offset:1024
	ds_read_b128 v[190:193], v187 offset:2048
	ds_read_b128 v[194:197], v187 offset:3072
	ds_read_b128 v[198:201], v187 offset:16384
	ds_read_b128 v[202:205], v187 offset:17408
	ds_read_b128 v[206:209], v187 offset:18432
	ds_read_b128 v[210:213], v187 offset:19456
	s_add_u32 s54, s52, 0xffea8080
	s_addc_u32 s55, s53, -1
	s_and_b64 s[50:51], s[50:51], exec
	s_cselect_b32 s50, s4, s8
	s_cselect_b32 s55, s1, s55
	s_cselect_b32 s54, s0, s54
	s_cselect_b32 s51, s5, s9
	s_mov_b32 m0, s49
	v_lshl_add_u64 v[238:239], s[52:53], 0, v[162:163]
	ds_read_b128 v[176:179], v188
	ds_read_b128 v[180:183], v188 offset:1024
	ds_read_b128 v[214:217], v188 offset:2048
	ds_read_b128 v[218:221], v188 offset:3072
	ds_read_b128 v[222:225], v188 offset:4096
	ds_read_b128 v[226:229], v188 offset:5120
	ds_read_b128 v[230:233], v188 offset:6144
	ds_read_b128 v[234:237], v188 offset:7168
	global_load_lds_dwordx4 v[238:239], off
	v_lshl_add_u64 v[238:239], s[52:53], 0, v[164:165]
	s_mov_b32 m0, s71
	s_nop 0
	global_load_lds_dwordx4 v[238:239], off
	s_waitcnt vmcnt(8)
	s_waitcnt lgkmcnt(0)
	s_barrier
	s_setprio 1
	s_waitcnt lgkmcnt(0)
	v_mfma_f32_16x16x128_f8f6f4 v[134:137], v[2:9], v[176:183], v[134:137]
	v_mfma_f32_16x16x128_f8f6f4 v[130:133], v[190:197], v[176:183], v[130:133]
	v_mfma_f32_16x16x128_f8f6f4 v[122:125], v[190:197], v[214:221], v[122:125]
	v_mfma_f32_16x16x128_f8f6f4 v[126:129], v[2:9], v[214:221], v[126:129]
	v_mfma_f32_16x16x128_f8f6f4 v[118:121], v[2:9], v[222:229], v[118:121]
	v_mfma_f32_16x16x128_f8f6f4 v[114:117], v[190:197], v[222:229], v[114:117]
	v_mfma_f32_16x16x128_f8f6f4 v[106:109], v[190:197], v[230:237], v[106:109]
	v_mfma_f32_16x16x128_f8f6f4 v[110:113], v[2:9], v[230:237], v[110:113]
	s_setprio 0
	s_setprio 1
	v_mfma_f32_16x16x128_f8f6f4 v[78:81], v[198:205], v[230:237], v[78:81]
	v_mfma_f32_16x16x128_f8f6f4 v[74:77], v[206:213], v[230:237], v[74:77]
	v_mfma_f32_16x16x128_f8f6f4 v[82:85], v[206:213], v[222:229], v[82:85]
	v_mfma_f32_16x16x128_f8f6f4 v[86:89], v[198:205], v[222:229], v[86:89]
	v_mfma_f32_16x16x128_f8f6f4 v[94:97], v[198:205], v[214:221], v[94:97]
	v_mfma_f32_16x16x128_f8f6f4 v[90:93], v[206:213], v[214:221], v[90:93]
	v_mfma_f32_16x16x128_f8f6f4 v[98:101], v[206:213], v[176:183], v[98:101]
	v_mfma_f32_16x16x128_f8f6f4 v[102:105], v[198:205], v[176:183], v[102:105]
	s_setprio 0
	s_barrier
	s_mov_b32 m0, s47
	v_lshl_add_u64 v[176:177], s[50:51], 0, v[156:157]
	s_add_u32 s62, s50, 0x158000
	ds_read_b128 v[214:217], v188 offset:16384
	ds_read_b128 v[218:221], v188 offset:17408
	ds_read_b128 v[222:225], v188 offset:18432
	ds_read_b128 v[226:229], v188 offset:19456
	ds_read_b128 v[230:233], v188 offset:20480
	ds_read_b128 v[234:237], v188 offset:21504
	ds_read_b128 v[242:245], v188 offset:22528
	ds_read_b128 v[246:249], v188 offset:23552
	global_load_lds_dwordx4 v[176:177], off
	v_lshl_add_u64 v[178:179], s[50:51], 0, v[160:161]
	s_mov_b32 m0, s68
	s_addc_u32 s63, s51, 0
	global_load_lds_dwordx4 v[178:179], off
	v_lshl_add_u64 v[180:181], s[62:63], 0, v[156:157]
	s_mov_b32 m0, s69
	v_lshl_add_u64 v[182:183], s[54:55], 0, v[158:159]
	global_load_lds_dwordx4 v[180:181], off
	v_lshl_add_u64 v[180:181], s[62:63], 0, v[160:161]
	s_mov_b32 m0, s74
	s_nop 0
	global_load_lds_dwordx4 v[180:181], off
	v_lshl_add_u64 v[180:181], s[54:55], 0, v[154:155]
	s_mov_b32 m0, s33
	s_nop 0
	global_load_lds_dwordx4 v[180:181], off
	s_mov_b32 m0, s75
	s_nop 0
	global_load_lds_dwordx4 v[182:183], off
	s_waitcnt vmcnt(8)
	s_waitcnt lgkmcnt(0)
	s_barrier
	s_setprio 1
	s_waitcnt lgkmcnt(0)
	v_mfma_f32_16x16x128_f8f6f4 v[70:73], v[2:9], v[214:221], v[70:73]
	v_mfma_f32_16x16x128_f8f6f4 v[66:69], v[190:197], v[214:221], v[66:69]
	v_mfma_f32_16x16x128_f8f6f4 v[58:61], v[190:197], v[222:229], v[58:61]
	v_mfma_f32_16x16x128_f8f6f4 v[62:65], v[2:9], v[222:229], v[62:65]
	v_mfma_f32_16x16x128_f8f6f4 v[54:57], v[2:9], v[230:237], v[54:57]
	v_mfma_f32_16x16x128_f8f6f4 v[50:53], v[190:197], v[230:237], v[50:53]
	v_mfma_f32_16x16x128_f8f6f4 v[42:45], v[190:197], v[242:249], v[42:45]
	v_mfma_f32_16x16x128_f8f6f4 v[46:49], v[2:9], v[242:249], v[46:49]
	s_setprio 0
	s_setprio 1
	v_mfma_f32_16x16x128_f8f6f4 v[14:17], v[198:205], v[242:249], v[14:17]
	v_mfma_f32_16x16x128_f8f6f4 v[10:13], v[206:213], v[242:249], v[10:13]
	v_mfma_f32_16x16x128_f8f6f4 v[18:21], v[206:213], v[230:237], v[18:21]
	v_mfma_f32_16x16x128_f8f6f4 v[22:25], v[198:205], v[230:237], v[22:25]
	v_mfma_f32_16x16x128_f8f6f4 v[30:33], v[198:205], v[222:229], v[30:33]
	v_mfma_f32_16x16x128_f8f6f4 v[26:29], v[206:213], v[222:229], v[26:29]
	v_mfma_f32_16x16x128_f8f6f4 v[34:37], v[206:213], v[214:221], v[34:37]
	v_mfma_f32_16x16x128_f8f6f4 v[38:41], v[198:205], v[214:221], v[38:41]
	s_setprio 0
	s_barrier
	ds_read_b128 v[190:193], v187 offset:32768
	ds_read_b128 v[194:197], v187 offset:33792
	ds_read_b128 v[198:201], v187 offset:34816
	ds_read_b128 v[202:205], v187 offset:35840
	ds_read_b128 v[2:5], v187 offset:49152
	ds_read_b128 v[6:9], v187 offset:50176
	ds_read_b128 v[206:209], v187 offset:51200
	ds_read_b128 v[210:213], v187 offset:52224
	s_add_u32 s54, s54, 0x158000
	s_addc_u32 s55, s55, 0
	s_mov_b32 m0, s76
	v_lshl_add_u64 v[238:239], s[54:55], 0, v[154:155]
	ds_read_b128 v[214:217], v188 offset:32768
	ds_read_b128 v[218:221], v188 offset:33792
	ds_read_b128 v[222:225], v188 offset:34816
	ds_read_b128 v[226:229], v188 offset:35840
	ds_read_b128 v[230:233], v188 offset:36864
	ds_read_b128 v[234:237], v188 offset:37888
	ds_read_b128 v[242:245], v188 offset:38912
	ds_read_b128 v[246:249], v188 offset:39936
	global_load_lds_dwordx4 v[238:239], off
	v_lshl_add_u64 v[238:239], s[54:55], 0, v[158:159]
	s_mov_b32 m0, s77
	s_nop 0
	global_load_lds_dwordx4 v[238:239], off
	s_waitcnt vmcnt(8)
	s_waitcnt lgkmcnt(0)
	s_barrier
	s_setprio 1
	s_waitcnt lgkmcnt(0)
	v_mfma_f32_16x16x128_f8f6f4 v[134:137], v[190:197], v[214:221], v[134:137]
	v_mfma_f32_16x16x128_f8f6f4 v[130:133], v[198:205], v[214:221], v[130:133]
	v_mfma_f32_16x16x128_f8f6f4 v[122:125], v[198:205], v[222:229], v[122:125]
	v_mfma_f32_16x16x128_f8f6f4 v[126:129], v[190:197], v[222:229], v[126:129]
	v_mfma_f32_16x16x128_f8f6f4 v[118:121], v[190:197], v[230:237], v[118:121]
	v_mfma_f32_16x16x128_f8f6f4 v[114:117], v[198:205], v[230:237], v[114:117]
	v_mfma_f32_16x16x128_f8f6f4 v[106:109], v[198:205], v[242:249], v[106:109]
	v_mfma_f32_16x16x128_f8f6f4 v[110:113], v[190:197], v[242:249], v[110:113]
	s_setprio 0
	s_setprio 1
	v_mfma_f32_16x16x128_f8f6f4 v[78:81], v[2:9], v[242:249], v[78:81]
	v_mfma_f32_16x16x128_f8f6f4 v[74:77], v[206:213], v[242:249], v[74:77]
	v_mfma_f32_16x16x128_f8f6f4 v[82:85], v[206:213], v[230:237], v[82:85]
	v_mfma_f32_16x16x128_f8f6f4 v[86:89], v[2:9], v[230:237], v[86:89]
	v_mfma_f32_16x16x128_f8f6f4 v[94:97], v[2:9], v[222:229], v[94:97]
	v_mfma_f32_16x16x128_f8f6f4 v[90:93], v[206:213], v[222:229], v[90:93]
	v_mfma_f32_16x16x128_f8f6f4 v[98:101], v[206:213], v[214:221], v[98:101]
	v_mfma_f32_16x16x128_f8f6f4 v[102:105], v[2:9], v[214:221], v[102:105]
	s_setprio 0
	s_barrier
	s_mov_b32 m0, s83
	v_lshl_add_u64 v[176:177], v[176:177], 0, s[26:27]
	s_add_u32 s50, s50, 0x158080
	ds_read_b128 v[214:217], v188 offset:49152
	ds_read_b128 v[218:221], v188 offset:50176
	ds_read_b128 v[222:225], v188 offset:51200
	ds_read_b128 v[226:229], v188 offset:52224
	ds_read_b128 v[230:233], v188 offset:53248
	ds_read_b128 v[234:237], v188 offset:54272
	ds_read_b128 v[242:245], v188 offset:55296
	ds_read_b128 v[246:249], v188 offset:56320
	global_load_lds_dwordx4 v[176:177], off
	v_lshl_add_u64 v[176:177], v[178:179], 0, s[26:27]
	s_mov_b32 m0, s84
	s_addc_u32 s51, s51, 0
	global_load_lds_dwordx4 v[176:177], off
	v_lshl_add_u64 v[176:177], s[50:51], 0, v[156:157]
	s_mov_b32 m0, s87
	s_nop 0
	global_load_lds_dwordx4 v[176:177], off
	v_lshl_add_u64 v[176:177], s[50:51], 0, v[160:161]
	s_mov_b32 m0, s88
	s_nop 0
	global_load_lds_dwordx4 v[176:177], off
	v_lshl_add_u64 v[176:177], v[180:181], 0, s[26:27]
	s_mov_b32 m0, s85
	s_nop 0
	global_load_lds_dwordx4 v[176:177], off
	v_lshl_add_u64 v[176:177], v[182:183], 0, s[26:27]
	s_mov_b32 m0, s86
	s_nop 0
	global_load_lds_dwordx4 v[176:177], off
	s_waitcnt vmcnt(8)
	s_waitcnt lgkmcnt(0)
	s_barrier
	s_setprio 1
	s_waitcnt lgkmcnt(0)
	v_mfma_f32_16x16x128_f8f6f4 v[70:73], v[190:197], v[214:221], v[70:73]
	v_mfma_f32_16x16x128_f8f6f4 v[66:69], v[198:205], v[214:221], v[66:69]
	v_mfma_f32_16x16x128_f8f6f4 v[58:61], v[198:205], v[222:229], v[58:61]
	v_mfma_f32_16x16x128_f8f6f4 v[62:65], v[190:197], v[222:229], v[62:65]
	v_mfma_f32_16x16x128_f8f6f4 v[54:57], v[190:197], v[230:237], v[54:57]
	v_mfma_f32_16x16x128_f8f6f4 v[50:53], v[198:205], v[230:237], v[50:53]
	v_mfma_f32_16x16x128_f8f6f4 v[42:45], v[198:205], v[242:249], v[42:45]
	v_mfma_f32_16x16x128_f8f6f4 v[46:49], v[190:197], v[242:249], v[46:49]
	s_setprio 0
	s_setprio 1
	v_mfma_f32_16x16x128_f8f6f4 v[14:17], v[2:9], v[242:249], v[14:17]
	v_mfma_f32_16x16x128_f8f6f4 v[10:13], v[206:213], v[242:249], v[10:13]
	v_mfma_f32_16x16x128_f8f6f4 v[18:21], v[206:213], v[230:237], v[18:21]
	v_mfma_f32_16x16x128_f8f6f4 v[22:25], v[2:9], v[230:237], v[22:25]
	v_mfma_f32_16x16x128_f8f6f4 v[30:33], v[2:9], v[222:229], v[30:33]
	v_mfma_f32_16x16x128_f8f6f4 v[26:29], v[206:213], v[222:229], v[26:29]
	v_mfma_f32_16x16x128_f8f6f4 v[34:37], v[206:213], v[214:221], v[34:37]
	v_mfma_f32_16x16x128_f8f6f4 v[38:41], v[2:9], v[214:221], v[38:41]
	s_setprio 0
	s_barrier
	s_add_i32 s50, s72, 2
	s_add_u32 s52, s52, 0x100
	s_addc_u32 s53, s53, 0
	s_add_u32 s8, s8, 0x100
	s_addc_u32 s9, s9, 0
	s_cmp_ge_i32 s72, s95
	s_cbranch_scc1 .LBB0_287
	s_mov_b32 s72, s50
	s_cmp_eq_u32 s95, s72
	s_cselect_b64 s[50:51], -1, 0
	s_cmp_lg_u32 s95, s72
	s_cbranch_scc0 .LBB0_284
	s_branch .LBB0_285

.LBB0_437:
	s_ashr_i32 s47, s46, 31
	ds_read_b128 v[18:21], v200
	ds_read_b128 v[22:25], v200 offset:1024
	ds_read_b128 v[26:29], v200 offset:2048
	ds_read_b128 v[30:33], v200 offset:3072
	ds_read_b128 v[2:5], v200 offset:16384
	ds_read_b128 v[6:9], v200 offset:17408
	ds_read_b128 v[10:13], v200 offset:18432
	ds_read_b128 v[14:17], v200 offset:19456
	s_lshl_b64 s[8:9], s[46:47], 20
	s_add_u32 s48, s12, s8
	s_addc_u32 s49, s13, s9
	s_and_b64 s[8:9], s[2:3], exec
	s_cselect_b32 s47, s49, s73
	s_cselect_b32 s71, s48, s72
	s_ashr_i32 s45, s44, 31
	s_lshl_b64 s[8:9], s[44:45], 20
	s_add_u32 s50, s39, s8
	s_addc_u32 s51, s76, s9
	s_and_b64 s[8:9], s[2:3], exec
	s_cselect_b32 s45, s51, s55
	s_cselect_b32 s94, s50, s54
	s_add_u32 s8, s72, 0x80080
	s_addc_u32 s9, s73, 0
	s_mov_b32 m0, s33
	v_lshl_add_u64 v[226:227], s[8:9], 0, v[162:163]
	ds_read_b128 v[180:183], v201
	ds_read_b128 v[184:187], v201 offset:1024
	ds_read_b128 v[202:205], v201 offset:2048
	ds_read_b128 v[206:209], v201 offset:3072
	ds_read_b128 v[210:213], v201 offset:4096
	ds_read_b128 v[214:217], v201 offset:5120
	ds_read_b128 v[218:221], v201 offset:6144
	ds_read_b128 v[222:225], v201 offset:7168
	global_load_lds_dwordx4 v[226:227], off
	v_lshl_add_u64 v[226:227], s[8:9], 0, v[166:167]
	s_mov_b32 m0, s93
	s_nop 0
	global_load_lds_dwordx4 v[226:227], off
	s_waitcnt vmcnt(8)
	s_waitcnt lgkmcnt(0)
	s_barrier
	s_setprio 1
	s_waitcnt lgkmcnt(0)
	v_mfma_f32_16x16x128_f8f6f4 v[158:161], v[18:25], v[180:187], 0
	v_mfma_f32_16x16x128_f8f6f4 v[154:157], v[26:33], v[180:187], 0
	v_mfma_f32_16x16x128_f8f6f4 v[146:149], v[26:33], v[202:209], 0
	v_mfma_f32_16x16x128_f8f6f4 v[150:153], v[18:25], v[202:209], 0
	v_mfma_f32_16x16x128_f8f6f4 v[142:145], v[18:25], v[210:217], 0
	v_mfma_f32_16x16x128_f8f6f4 v[138:141], v[26:33], v[210:217], 0
	v_mfma_f32_16x16x128_f8f6f4 v[130:133], v[26:33], v[218:225], 0
	v_mfma_f32_16x16x128_f8f6f4 v[134:137], v[18:25], v[218:225], 0
	s_setprio 0
	s_setprio 1
	v_mfma_f32_16x16x128_f8f6f4 v[102:105], v[2:9], v[218:225], 0
	v_mfma_f32_16x16x128_f8f6f4 v[98:101], v[10:17], v[218:225], 0
	v_mfma_f32_16x16x128_f8f6f4 v[106:109], v[10:17], v[210:217], 0
	v_mfma_f32_16x16x128_f8f6f4 v[110:113], v[2:9], v[210:217], 0
	v_mfma_f32_16x16x128_f8f6f4 v[118:121], v[2:9], v[202:209], 0
	v_mfma_f32_16x16x128_f8f6f4 v[114:117], v[10:17], v[202:209], 0
	v_mfma_f32_16x16x128_f8f6f4 v[122:125], v[10:17], v[180:187], 0
	v_mfma_f32_16x16x128_f8f6f4 v[126:129], v[2:9], v[180:187], 0
	s_setprio 0
	s_barrier
	v_lshl_add_u64 v[180:181], s[54:55], 0, v[164:165]
	s_mov_b32 m0, s78
	v_lshl_add_u64 v[182:183], v[180:181], 0, s[26:27]
	ds_read_b128 v[202:205], v201 offset:16384
	ds_read_b128 v[206:209], v201 offset:17408
	ds_read_b128 v[210:213], v201 offset:18432
	ds_read_b128 v[214:217], v201 offset:19456
	ds_read_b128 v[218:221], v201 offset:20480
	ds_read_b128 v[222:225], v201 offset:21504
	ds_read_b128 v[226:229], v201 offset:22528
	ds_read_b128 v[230:233], v201 offset:23552
	global_load_lds_dwordx4 v[182:183], off
	v_lshl_add_u64 v[182:183], s[54:55], 0, v[168:169]
	s_add_u32 s8, s54, 0x80100
	v_lshl_add_u64 v[184:185], v[182:183], 0, s[26:27]
	s_mov_b32 m0, s79
	s_addc_u32 s9, s55, 0
	global_load_lds_dwordx4 v[184:185], off
	v_lshl_add_u64 v[184:185], s[8:9], 0, v[164:165]
	s_mov_b32 m0, s80
	s_nop 0
	global_load_lds_dwordx4 v[184:185], off
	v_lshl_add_u64 v[184:185], s[8:9], 0, v[168:169]
	s_mov_b32 m0, s81
	s_nop 0
	global_load_lds_dwordx4 v[184:185], off
	v_lshl_add_u64 v[184:185], s[72:73], 0, v[162:163]
	v_lshl_add_u64 v[186:187], v[184:185], 0, s[26:27]
	s_mov_b32 m0, s53
	s_nop 0
	global_load_lds_dwordx4 v[186:187], off
	v_lshl_add_u64 v[186:187], s[72:73], 0, v[166:167]
	v_lshl_add_u64 v[234:235], v[186:187], 0, s[26:27]
	s_mov_b32 m0, s82
	s_nop 0
	global_load_lds_dwordx4 v[234:235], off
	s_waitcnt vmcnt(8)
	s_waitcnt lgkmcnt(0)
	s_barrier
	s_setprio 1
	s_waitcnt lgkmcnt(0)
	v_mfma_f32_16x16x128_f8f6f4 v[94:97], v[18:25], v[202:209], 0
	v_mfma_f32_16x16x128_f8f6f4 v[90:93], v[26:33], v[202:209], 0
	v_mfma_f32_16x16x128_f8f6f4 v[82:85], v[26:33], v[210:217], 0
	v_mfma_f32_16x16x128_f8f6f4 v[86:89], v[18:25], v[210:217], 0
	v_mfma_f32_16x16x128_f8f6f4 v[78:81], v[18:25], v[218:225], 0
	v_mfma_f32_16x16x128_f8f6f4 v[74:77], v[26:33], v[218:225], 0
	v_mfma_f32_16x16x128_f8f6f4 v[66:69], v[26:33], v[226:233], 0
	v_mfma_f32_16x16x128_f8f6f4 v[70:73], v[18:25], v[226:233], 0
	s_setprio 0
	s_setprio 1
	v_mfma_f32_16x16x128_f8f6f4 v[38:41], v[2:9], v[226:233], 0
	v_mfma_f32_16x16x128_f8f6f4 v[34:37], v[10:17], v[226:233], 0
	v_mfma_f32_16x16x128_f8f6f4 v[42:45], v[10:17], v[218:225], 0
	v_mfma_f32_16x16x128_f8f6f4 v[46:49], v[2:9], v[218:225], 0
	v_mfma_f32_16x16x128_f8f6f4 v[54:57], v[2:9], v[210:217], 0
	v_mfma_f32_16x16x128_f8f6f4 v[50:53], v[10:17], v[210:217], 0
	v_mfma_f32_16x16x128_f8f6f4 v[58:61], v[10:17], v[202:209], 0
	v_mfma_f32_16x16x128_f8f6f4 v[62:65], v[2:9], v[202:209], 0
	s_setprio 0
	s_barrier
	ds_read_b128 v[18:21], v200 offset:32768
	ds_read_b128 v[22:25], v200 offset:33792
	ds_read_b128 v[26:29], v200 offset:34816
	ds_read_b128 v[30:33], v200 offset:35840
	ds_read_b128 v[2:5], v200 offset:49152
	ds_read_b128 v[6:9], v200 offset:50176
	ds_read_b128 v[10:13], v200 offset:51200
	ds_read_b128 v[14:17], v200 offset:52224
	s_add_u32 s8, s72, 0x80100
	s_addc_u32 s9, s73, 0
	s_mov_b32 m0, s83
	v_lshl_add_u64 v[234:235], s[8:9], 0, v[162:163]
	ds_read_b128 v[202:205], v201 offset:32768
	ds_read_b128 v[206:209], v201 offset:33792
	ds_read_b128 v[210:213], v201 offset:34816
	ds_read_b128 v[214:217], v201 offset:35840
	ds_read_b128 v[218:221], v201 offset:36864
	ds_read_b128 v[222:225], v201 offset:37888
	ds_read_b128 v[226:229], v201 offset:38912
	ds_read_b128 v[230:233], v201 offset:39936
	global_load_lds_dwordx4 v[234:235], off
	v_lshl_add_u64 v[234:235], s[8:9], 0, v[166:167]
	s_mov_b32 m0, s84
	s_nop 0
	global_load_lds_dwordx4 v[234:235], off
	s_waitcnt vmcnt(8)
	s_waitcnt lgkmcnt(0)
	s_barrier
	s_setprio 1
	s_waitcnt lgkmcnt(0)
	v_mfma_f32_16x16x128_f8f6f4 v[158:161], v[18:25], v[202:209], v[158:161]
	v_mfma_f32_16x16x128_f8f6f4 v[154:157], v[26:33], v[202:209], v[154:157]
	v_mfma_f32_16x16x128_f8f6f4 v[146:149], v[26:33], v[210:217], v[146:149]
	v_mfma_f32_16x16x128_f8f6f4 v[150:153], v[18:25], v[210:217], v[150:153]
	v_mfma_f32_16x16x128_f8f6f4 v[142:145], v[18:25], v[218:225], v[142:145]
	v_mfma_f32_16x16x128_f8f6f4 v[138:141], v[26:33], v[218:225], v[138:141]
	v_mfma_f32_16x16x128_f8f6f4 v[130:133], v[26:33], v[226:233], v[130:133]
	v_mfma_f32_16x16x128_f8f6f4 v[134:137], v[18:25], v[226:233], v[134:137]
	s_setprio 0
	s_setprio 1
	v_mfma_f32_16x16x128_f8f6f4 v[102:105], v[2:9], v[226:233], v[102:105]
	v_mfma_f32_16x16x128_f8f6f4 v[98:101], v[10:17], v[226:233], v[98:101]
	v_mfma_f32_16x16x128_f8f6f4 v[106:109], v[10:17], v[218:225], v[106:109]
	v_mfma_f32_16x16x128_f8f6f4 v[110:113], v[2:9], v[218:225], v[110:113]
	v_mfma_f32_16x16x128_f8f6f4 v[118:121], v[2:9], v[210:217], v[118:121]
	v_mfma_f32_16x16x128_f8f6f4 v[114:117], v[10:17], v[210:217], v[114:117]
	v_mfma_f32_16x16x128_f8f6f4 v[122:125], v[10:17], v[202:209], v[122:125]
	v_mfma_f32_16x16x128_f8f6f4 v[126:129], v[2:9], v[202:209], v[126:129]
	s_setprio 0
	s_barrier
	s_mov_b32 m0, s87
	v_lshl_add_u64 v[180:181], v[180:181], 0, s[36:37]
	s_add_u32 s8, s54, 0x80180
	ds_read_b128 v[202:205], v201 offset:49152
	ds_read_b128 v[206:209], v201 offset:50176
	ds_read_b128 v[210:213], v201 offset:51200
	ds_read_b128 v[214:217], v201 offset:52224
	ds_read_b128 v[218:221], v201 offset:53248
	ds_read_b128 v[222:225], v201 offset:54272
	ds_read_b128 v[226:229], v201 offset:55296
	ds_read_b128 v[230:233], v201 offset:56320
	global_load_lds_dwordx4 v[180:181], off
	v_lshl_add_u64 v[180:181], v[182:183], 0, s[36:37]
	s_mov_b32 m0, s88
	s_addc_u32 s9, s55, 0
	global_load_lds_dwordx4 v[180:181], off
	v_lshl_add_u64 v[180:181], s[8:9], 0, v[164:165]
	s_mov_b32 m0, s91
	s_nop 0
	global_load_lds_dwordx4 v[180:181], off
	v_lshl_add_u64 v[180:181], s[8:9], 0, v[168:169]
	s_mov_b32 m0, s92
	s_nop 0
	global_load_lds_dwordx4 v[180:181], off
	v_lshl_add_u64 v[180:181], v[184:185], 0, s[36:37]
	s_mov_b32 m0, s89
	s_nop 0
	global_load_lds_dwordx4 v[180:181], off
	v_lshl_add_u64 v[180:181], v[186:187], 0, s[36:37]
	s_mov_b32 m0, s90
	s_nop 0
	global_load_lds_dwordx4 v[180:181], off
	s_waitcnt vmcnt(8)
	s_waitcnt lgkmcnt(0)
	s_barrier
	s_setprio 1
	s_waitcnt lgkmcnt(0)
	v_mfma_f32_16x16x128_f8f6f4 v[94:97], v[18:25], v[202:209], v[94:97]
	v_mfma_f32_16x16x128_f8f6f4 v[90:93], v[26:33], v[202:209], v[90:93]
	v_mfma_f32_16x16x128_f8f6f4 v[82:85], v[26:33], v[210:217], v[82:85]
	v_mfma_f32_16x16x128_f8f6f4 v[86:89], v[18:25], v[210:217], v[86:89]
	v_mfma_f32_16x16x128_f8f6f4 v[78:81], v[18:25], v[218:225], v[78:81]
	v_mfma_f32_16x16x128_f8f6f4 v[74:77], v[26:33], v[218:225], v[74:77]
	v_mfma_f32_16x16x128_f8f6f4 v[66:69], v[26:33], v[226:233], v[66:69]
	v_mfma_f32_16x16x128_f8f6f4 v[70:73], v[18:25], v[226:233], v[70:73]
	s_setprio 0
	s_setprio 1
	v_mfma_f32_16x16x128_f8f6f4 v[38:41], v[2:9], v[226:233], v[38:41]
	v_mfma_f32_16x16x128_f8f6f4 v[34:37], v[10:17], v[226:233], v[34:37]
	v_mfma_f32_16x16x128_f8f6f4 v[42:45], v[10:17], v[218:225], v[42:45]
	v_mfma_f32_16x16x128_f8f6f4 v[46:49], v[2:9], v[218:225], v[46:49]
	v_mfma_f32_16x16x128_f8f6f4 v[54:57], v[2:9], v[210:217], v[54:57]
	v_mfma_f32_16x16x128_f8f6f4 v[50:53], v[10:17], v[210:217], v[50:53]
	v_mfma_f32_16x16x128_f8f6f4 v[58:61], v[10:17], v[202:209], v[58:61]
	v_mfma_f32_16x16x128_f8f6f4 v[62:65], v[2:9], v[202:209], v[62:65]
	s_setprio 0
	s_barrier
	s_add_u32 s72, s72, 0x80180
	s_addc_u32 s73, s73, 0
	s_add_u32 s8, s54, 0x200
	s_addc_u32 s9, s55, 0
	s_mov_b32 s62, 0
.LBB0_438:
	ds_read_b128 v[2:5], v200
	ds_read_b128 v[6:9], v200 offset:1024
	ds_read_b128 v[18:21], v200 offset:2048
	ds_read_b128 v[22:25], v200 offset:3072
	ds_read_b128 v[26:29], v200 offset:16384
	ds_read_b128 v[30:33], v200 offset:17408
	ds_read_b128 v[180:183], v200 offset:18432
	ds_read_b128 v[184:187], v200 offset:19456
	s_add_u32 s54, s72, 0xfff80080
	s_addc_u32 s55, s73, -1
	s_cmp_eq_u32 s62, 28
	s_cselect_b32 s75, s47, s55
	s_cselect_b32 s74, s71, s54
	s_cselect_b32 s55, s45, s9
	s_cselect_b32 s54, s94, s8
	s_mov_b32 m0, s33
	v_lshl_add_u64 v[226:227], s[72:73], 0, v[170:171]
	ds_read_b128 v[10:13], v201
	ds_read_b128 v[14:17], v201 offset:1024
	ds_read_b128 v[202:205], v201 offset:2048
	ds_read_b128 v[206:209], v201 offset:3072
	ds_read_b128 v[210:213], v201 offset:4096
	ds_read_b128 v[214:217], v201 offset:5120
	ds_read_b128 v[218:221], v201 offset:6144
	ds_read_b128 v[222:225], v201 offset:7168
	global_load_lds_dwordx4 v[226:227], off
	v_lshl_add_u64 v[226:227], s[72:73], 0, v[172:173]
	s_mov_b32 m0, s93
	s_nop 0
	global_load_lds_dwordx4 v[226:227], off
	s_waitcnt vmcnt(8)
	s_waitcnt lgkmcnt(0)
	s_barrier
	s_setprio 1
	s_waitcnt lgkmcnt(0)
	v_mfma_f32_16x16x128_f8f6f4 v[158:161], v[2:9], v[10:17], v[158:161]
	v_mfma_f32_16x16x128_f8f6f4 v[154:157], v[18:25], v[10:17], v[154:157]
	v_mfma_f32_16x16x128_f8f6f4 v[146:149], v[18:25], v[202:209], v[146:149]
	v_mfma_f32_16x16x128_f8f6f4 v[150:153], v[2:9], v[202:209], v[150:153]
	v_mfma_f32_16x16x128_f8f6f4 v[142:145], v[2:9], v[210:217], v[142:145]
	v_mfma_f32_16x16x128_f8f6f4 v[138:141], v[18:25], v[210:217], v[138:141]
	v_mfma_f32_16x16x128_f8f6f4 v[130:133], v[18:25], v[218:225], v[130:133]
	v_mfma_f32_16x16x128_f8f6f4 v[134:137], v[2:9], v[218:225], v[134:137]
	s_setprio 0
	s_setprio 1
	v_mfma_f32_16x16x128_f8f6f4 v[102:105], v[26:33], v[218:225], v[102:105]
	v_mfma_f32_16x16x128_f8f6f4 v[98:101], v[180:187], v[218:225], v[98:101]
	v_mfma_f32_16x16x128_f8f6f4 v[106:109], v[180:187], v[210:217], v[106:109]
	v_mfma_f32_16x16x128_f8f6f4 v[110:113], v[26:33], v[210:217], v[110:113]
	v_mfma_f32_16x16x128_f8f6f4 v[118:121], v[26:33], v[202:209], v[118:121]
	v_mfma_f32_16x16x128_f8f6f4 v[114:117], v[180:187], v[202:209], v[114:117]
	v_mfma_f32_16x16x128_f8f6f4 v[122:125], v[180:187], v[10:17], v[122:125]
	v_mfma_f32_16x16x128_f8f6f4 v[126:129], v[26:33], v[10:17], v[126:129]
	s_setprio 0
	s_barrier
	s_mov_b32 m0, s78
	v_lshl_add_u64 v[10:11], s[54:55], 0, v[164:165]
	s_add_u32 s96, s54, 0x80000
	ds_read_b128 v[202:205], v201 offset:16384
	ds_read_b128 v[206:209], v201 offset:17408
	ds_read_b128 v[210:213], v201 offset:18432
	ds_read_b128 v[214:217], v201 offset:19456
	ds_read_b128 v[218:221], v201 offset:20480
	ds_read_b128 v[222:225], v201 offset:21504
	ds_read_b128 v[226:229], v201 offset:22528
	ds_read_b128 v[230:233], v201 offset:23552
	global_load_lds_dwordx4 v[10:11], off
	v_lshl_add_u64 v[12:13], s[54:55], 0, v[168:169]
	s_mov_b32 m0, s79
	s_addc_u32 s97, s55, 0
	global_load_lds_dwordx4 v[12:13], off
	v_lshl_add_u64 v[14:15], s[96:97], 0, v[164:165]
	s_mov_b32 m0, s80
	v_lshl_add_u64 v[16:17], s[74:75], 0, v[166:167]
	global_load_lds_dwordx4 v[14:15], off
	v_lshl_add_u64 v[14:15], s[96:97], 0, v[168:169]
	s_mov_b32 m0, s81
	s_nop 0
	global_load_lds_dwordx4 v[14:15], off
	v_lshl_add_u64 v[14:15], s[74:75], 0, v[162:163]
	s_mov_b32 m0, s53
	s_nop 0
	global_load_lds_dwordx4 v[14:15], off
	s_mov_b32 m0, s82
	s_nop 0
	global_load_lds_dwordx4 v[16:17], off
	s_waitcnt vmcnt(8)
	s_waitcnt lgkmcnt(0)
	s_barrier
	s_setprio 1
	s_waitcnt lgkmcnt(0)
	v_mfma_f32_16x16x128_f8f6f4 v[94:97], v[2:9], v[202:209], v[94:97]
	v_mfma_f32_16x16x128_f8f6f4 v[90:93], v[18:25], v[202:209], v[90:93]
	v_mfma_f32_16x16x128_f8f6f4 v[82:85], v[18:25], v[210:217], v[82:85]
	v_mfma_f32_16x16x128_f8f6f4 v[86:89], v[2:9], v[210:217], v[86:89]
	v_mfma_f32_16x16x128_f8f6f4 v[78:81], v[2:9], v[218:225], v[78:81]
	v_mfma_f32_16x16x128_f8f6f4 v[74:77], v[18:25], v[218:225], v[74:77]
	v_mfma_f32_16x16x128_f8f6f4 v[66:69], v[18:25], v[226:233], v[66:69]
	v_mfma_f32_16x16x128_f8f6f4 v[70:73], v[2:9], v[226:233], v[70:73]
	s_setprio 0
	s_setprio 1
	v_mfma_f32_16x16x128_f8f6f4 v[38:41], v[26:33], v[226:233], v[38:41]
	v_mfma_f32_16x16x128_f8f6f4 v[34:37], v[180:187], v[226:233], v[34:37]
	v_mfma_f32_16x16x128_f8f6f4 v[42:45], v[180:187], v[218:225], v[42:45]
	v_mfma_f32_16x16x128_f8f6f4 v[46:49], v[26:33], v[218:225], v[46:49]
	v_mfma_f32_16x16x128_f8f6f4 v[54:57], v[26:33], v[210:217], v[54:57]
	v_mfma_f32_16x16x128_f8f6f4 v[50:53], v[180:187], v[210:217], v[50:53]
	v_mfma_f32_16x16x128_f8f6f4 v[58:61], v[180:187], v[202:209], v[58:61]
	v_mfma_f32_16x16x128_f8f6f4 v[62:65], v[26:33], v[202:209], v[62:65]
	s_setprio 0
	s_barrier
	ds_read_b128 v[18:21], v200 offset:32768
	ds_read_b128 v[22:25], v200 offset:33792
	ds_read_b128 v[26:29], v200 offset:34816
	ds_read_b128 v[30:33], v200 offset:35840
	ds_read_b128 v[2:5], v200 offset:49152
	ds_read_b128 v[6:9], v200 offset:50176
	ds_read_b128 v[180:183], v200 offset:51200
	ds_read_b128 v[184:187], v200 offset:52224
	s_add_u32 s74, s74, 0x80000
	s_addc_u32 s75, s75, 0
	s_mov_b32 m0, s83
	v_lshl_add_u64 v[234:235], s[74:75], 0, v[162:163]
	ds_read_b128 v[202:205], v201 offset:32768
	ds_read_b128 v[206:209], v201 offset:33792
	ds_read_b128 v[210:213], v201 offset:34816
	ds_read_b128 v[214:217], v201 offset:35840
	ds_read_b128 v[218:221], v201 offset:36864
	ds_read_b128 v[222:225], v201 offset:37888
	ds_read_b128 v[226:229], v201 offset:38912
	ds_read_b128 v[230:233], v201 offset:39936
	global_load_lds_dwordx4 v[234:235], off
	v_lshl_add_u64 v[234:235], s[74:75], 0, v[166:167]
	s_mov_b32 m0, s84
	s_nop 0
	global_load_lds_dwordx4 v[234:235], off
	s_waitcnt vmcnt(8)
	s_waitcnt lgkmcnt(0)
	s_barrier
	s_setprio 1
	s_waitcnt lgkmcnt(0)
	v_mfma_f32_16x16x128_f8f6f4 v[158:161], v[18:25], v[202:209], v[158:161]
	v_mfma_f32_16x16x128_f8f6f4 v[154:157], v[26:33], v[202:209], v[154:157]
	v_mfma_f32_16x16x128_f8f6f4 v[146:149], v[26:33], v[210:217], v[146:149]
	v_mfma_f32_16x16x128_f8f6f4 v[150:153], v[18:25], v[210:217], v[150:153]
	v_mfma_f32_16x16x128_f8f6f4 v[142:145], v[18:25], v[218:225], v[142:145]
	v_mfma_f32_16x16x128_f8f6f4 v[138:141], v[26:33], v[218:225], v[138:141]
	v_mfma_f32_16x16x128_f8f6f4 v[130:133], v[26:33], v[226:233], v[130:133]
	v_mfma_f32_16x16x128_f8f6f4 v[134:137], v[18:25], v[226:233], v[134:137]
	s_setprio 0
	s_setprio 1
	v_mfma_f32_16x16x128_f8f6f4 v[102:105], v[2:9], v[226:233], v[102:105]
	v_mfma_f32_16x16x128_f8f6f4 v[98:101], v[180:187], v[226:233], v[98:101]
	v_mfma_f32_16x16x128_f8f6f4 v[106:109], v[180:187], v[218:225], v[106:109]
	v_mfma_f32_16x16x128_f8f6f4 v[110:113], v[2:9], v[218:225], v[110:113]
	v_mfma_f32_16x16x128_f8f6f4 v[118:121], v[2:9], v[210:217], v[118:121]
	v_mfma_f32_16x16x128_f8f6f4 v[114:117], v[180:187], v[210:217], v[114:117]
	v_mfma_f32_16x16x128_f8f6f4 v[122:125], v[180:187], v[202:209], v[122:125]
	v_mfma_f32_16x16x128_f8f6f4 v[126:129], v[2:9], v[202:209], v[126:129]
	s_setprio 0
	s_barrier
	s_mov_b32 m0, s87
	v_lshl_add_u64 v[10:11], v[10:11], 0, s[4:5]
	s_add_u32 s54, s54, 0x80080
	ds_read_b128 v[202:205], v201 offset:49152
	ds_read_b128 v[206:209], v201 offset:50176
	ds_read_b128 v[210:213], v201 offset:51200
	ds_read_b128 v[214:217], v201 offset:52224
	ds_read_b128 v[218:221], v201 offset:53248
	ds_read_b128 v[222:225], v201 offset:54272
	ds_read_b128 v[226:229], v201 offset:55296
	ds_read_b128 v[230:233], v201 offset:56320
	global_load_lds_dwordx4 v[10:11], off
	v_lshl_add_u64 v[10:11], v[12:13], 0, s[4:5]
	s_mov_b32 m0, s88
	s_addc_u32 s55, s55, 0
	global_load_lds_dwordx4 v[10:11], off
	v_lshl_add_u64 v[10:11], s[54:55], 0, v[164:165]
	s_mov_b32 m0, s91
	s_nop 0
	global_load_lds_dwordx4 v[10:11], off
	v_lshl_add_u64 v[10:11], s[54:55], 0, v[168:169]
	s_mov_b32 m0, s92
	s_nop 0
	global_load_lds_dwordx4 v[10:11], off
	v_lshl_add_u64 v[10:11], v[14:15], 0, s[4:5]
	s_mov_b32 m0, s89
	s_nop 0
	global_load_lds_dwordx4 v[10:11], off
	v_lshl_add_u64 v[10:11], v[16:17], 0, s[4:5]
	s_mov_b32 m0, s90
	s_nop 0
	global_load_lds_dwordx4 v[10:11], off
	s_waitcnt vmcnt(8)
	s_waitcnt lgkmcnt(0)
	s_barrier
	s_setprio 1
	s_waitcnt lgkmcnt(0)
	v_mfma_f32_16x16x128_f8f6f4 v[94:97], v[18:25], v[202:209], v[94:97]
	v_mfma_f32_16x16x128_f8f6f4 v[90:93], v[26:33], v[202:209], v[90:93]
	v_mfma_f32_16x16x128_f8f6f4 v[82:85], v[26:33], v[210:217], v[82:85]
	v_mfma_f32_16x16x128_f8f6f4 v[86:89], v[18:25], v[210:217], v[86:89]
	v_mfma_f32_16x16x128_f8f6f4 v[78:81], v[18:25], v[218:225], v[78:81]
	v_mfma_f32_16x16x128_f8f6f4 v[74:77], v[26:33], v[218:225], v[74:77]
	v_mfma_f32_16x16x128_f8f6f4 v[66:69], v[26:33], v[226:233], v[66:69]
	v_mfma_f32_16x16x128_f8f6f4 v[70:73], v[18:25], v[226:233], v[70:73]
	s_setprio 0
	s_setprio 1
	v_mfma_f32_16x16x128_f8f6f4 v[38:41], v[2:9], v[226:233], v[38:41]
	v_mfma_f32_16x16x128_f8f6f4 v[34:37], v[180:187], v[226:233], v[34:37]
	v_mfma_f32_16x16x128_f8f6f4 v[42:45], v[180:187], v[218:225], v[42:45]
	v_mfma_f32_16x16x128_f8f6f4 v[46:49], v[2:9], v[218:225], v[46:49]
	v_mfma_f32_16x16x128_f8f6f4 v[54:57], v[2:9], v[210:217], v[54:57]
	v_mfma_f32_16x16x128_f8f6f4 v[50:53], v[180:187], v[210:217], v[50:53]
	v_mfma_f32_16x16x128_f8f6f4 v[58:61], v[180:187], v[202:209], v[58:61]
	v_mfma_f32_16x16x128_f8f6f4 v[62:65], v[2:9], v[202:209], v[62:65]
	s_setprio 0
	s_barrier
	s_add_i32 s62, s62, 2
	s_add_u32 s72, s72, 0x100
	s_addc_u32 s73, s73, 0
	s_add_u32 s8, s8, 0x100
	s_addc_u32 s9, s9, 0
	s_cmp_gt_u32 s62, 29
	s_cbranch_scc0 .LBB0_438
	s_and_b64 vcc, exec, s[6:7]
	s_cbranch_vccz .LBB0_441
	s_barrier

.LBB0_600:
	s_ashr_i32 s55, s54, 31
	ds_read_b128 v[18:21], v200
	ds_read_b128 v[22:25], v200 offset:1024
	ds_read_b128 v[26:29], v200 offset:2048
	ds_read_b128 v[30:33], v200 offset:3072
	ds_read_b128 v[2:5], v200 offset:16384
	ds_read_b128 v[6:9], v200 offset:17408
	ds_read_b128 v[10:13], v200 offset:18432
	ds_read_b128 v[14:17], v200 offset:19456
	s_lshl_b64 s[4:5], s[54:55], 18
	s_add_u32 s72, s38, s4
	s_addc_u32 s73, s39, s5
	s_and_b64 s[4:5], s[2:3], exec
	s_cselect_b32 s4, s73, s81
	s_cselect_b32 s5, s72, s80
	s_ashr_i32 s53, s52, 31
	s_lshl_b64 s[8:9], s[52:53], 18
	s_add_u32 s74, s94, s8
	v_readlane_b32 s8, v254, 6
	s_addc_u32 s75, s8, s9
	s_and_b64 s[8:9], s[2:3], exec
	s_cselect_b32 s53, s75, s79
	s_cselect_b32 s55, s74, s78
	s_add_u32 s8, s80, 0x20080
	s_addc_u32 s9, s81, 0
	s_mov_b32 m0, s96
	v_lshl_add_u64 v[226:227], s[8:9], 0, v[162:163]
	ds_read_b128 v[182:185], v201
	ds_read_b128 v[186:189], v201 offset:1024
	ds_read_b128 v[202:205], v201 offset:2048
	ds_read_b128 v[206:209], v201 offset:3072
	ds_read_b128 v[210:213], v201 offset:4096
	ds_read_b128 v[214:217], v201 offset:5120
	ds_read_b128 v[218:221], v201 offset:6144
	ds_read_b128 v[222:225], v201 offset:7168
	global_load_lds_dwordx4 v[226:227], off
	v_lshl_add_u64 v[226:227], s[8:9], 0, v[166:167]
	s_mov_b32 m0, s61
	s_nop 0
	global_load_lds_dwordx4 v[226:227], off
	s_waitcnt vmcnt(8)
	s_waitcnt lgkmcnt(0)
	s_barrier
	s_setprio 1
	s_waitcnt lgkmcnt(0)
	v_mfma_f32_16x16x128_f8f6f4 v[158:161], v[18:25], v[182:189], 0
	v_mfma_f32_16x16x128_f8f6f4 v[154:157], v[26:33], v[182:189], 0
	v_mfma_f32_16x16x128_f8f6f4 v[146:149], v[26:33], v[202:209], 0
	v_mfma_f32_16x16x128_f8f6f4 v[150:153], v[18:25], v[202:209], 0
	v_mfma_f32_16x16x128_f8f6f4 v[142:145], v[18:25], v[210:217], 0
	v_mfma_f32_16x16x128_f8f6f4 v[138:141], v[26:33], v[210:217], 0
	v_mfma_f32_16x16x128_f8f6f4 v[130:133], v[26:33], v[218:225], 0
	v_mfma_f32_16x16x128_f8f6f4 v[134:137], v[18:25], v[218:225], 0
	s_setprio 0
	s_setprio 1
	v_mfma_f32_16x16x128_f8f6f4 v[102:105], v[2:9], v[218:225], 0
	v_mfma_f32_16x16x128_f8f6f4 v[98:101], v[10:17], v[218:225], 0
	v_mfma_f32_16x16x128_f8f6f4 v[106:109], v[10:17], v[210:217], 0
	v_mfma_f32_16x16x128_f8f6f4 v[110:113], v[2:9], v[210:217], 0
	v_mfma_f32_16x16x128_f8f6f4 v[118:121], v[2:9], v[202:209], 0
	v_mfma_f32_16x16x128_f8f6f4 v[114:117], v[10:17], v[202:209], 0
	v_mfma_f32_16x16x128_f8f6f4 v[122:125], v[10:17], v[182:189], 0
	v_mfma_f32_16x16x128_f8f6f4 v[126:129], v[2:9], v[182:189], 0
	s_setprio 0
	s_barrier
	v_lshl_add_u64 v[182:183], s[78:79], 0, v[164:165]
	s_mov_b32 m0, s68
	v_lshl_add_u64 v[184:185], v[182:183], 0, s[46:47]
	ds_read_b128 v[202:205], v201 offset:16384
	ds_read_b128 v[206:209], v201 offset:17408
	ds_read_b128 v[210:213], v201 offset:18432
	ds_read_b128 v[214:217], v201 offset:19456
	ds_read_b128 v[218:221], v201 offset:20480
	ds_read_b128 v[222:225], v201 offset:21504
	ds_read_b128 v[226:229], v201 offset:22528
	ds_read_b128 v[230:233], v201 offset:23552
	global_load_lds_dwordx4 v[184:185], off
	v_lshl_add_u64 v[184:185], s[78:79], 0, v[168:169]
	s_add_u32 s8, s78, 0x20100
	v_lshl_add_u64 v[186:187], v[184:185], 0, s[46:47]
	s_mov_b32 m0, s69
	s_addc_u32 s9, s79, 0
	global_load_lds_dwordx4 v[186:187], off
	v_lshl_add_u64 v[186:187], s[8:9], 0, v[164:165]
	s_mov_b32 m0, s77
	s_nop 0
	global_load_lds_dwordx4 v[186:187], off
	v_lshl_add_u64 v[186:187], s[8:9], 0, v[168:169]
	s_mov_b32 m0, s84
	s_nop 0
	global_load_lds_dwordx4 v[186:187], off
	v_lshl_add_u64 v[186:187], s[80:81], 0, v[162:163]
	v_lshl_add_u64 v[188:189], v[186:187], 0, s[46:47]
	s_mov_b32 m0, s33
	s_nop 0
	global_load_lds_dwordx4 v[188:189], off
	v_lshl_add_u64 v[188:189], s[80:81], 0, v[166:167]
	v_lshl_add_u64 v[234:235], v[188:189], 0, s[46:47]
	s_mov_b32 m0, s85
	s_nop 0
	global_load_lds_dwordx4 v[234:235], off
	s_waitcnt vmcnt(8)
	s_waitcnt lgkmcnt(0)
	s_barrier
	s_setprio 1
	s_waitcnt lgkmcnt(0)
	v_mfma_f32_16x16x128_f8f6f4 v[94:97], v[18:25], v[202:209], 0
	v_mfma_f32_16x16x128_f8f6f4 v[90:93], v[26:33], v[202:209], 0
	v_mfma_f32_16x16x128_f8f6f4 v[82:85], v[26:33], v[210:217], 0
	v_mfma_f32_16x16x128_f8f6f4 v[86:89], v[18:25], v[210:217], 0
	v_mfma_f32_16x16x128_f8f6f4 v[78:81], v[18:25], v[218:225], 0
	v_mfma_f32_16x16x128_f8f6f4 v[74:77], v[26:33], v[218:225], 0
	v_mfma_f32_16x16x128_f8f6f4 v[66:69], v[26:33], v[226:233], 0
	v_mfma_f32_16x16x128_f8f6f4 v[70:73], v[18:25], v[226:233], 0
	s_setprio 0
	s_setprio 1
	v_mfma_f32_16x16x128_f8f6f4 v[38:41], v[2:9], v[226:233], 0
	v_mfma_f32_16x16x128_f8f6f4 v[34:37], v[10:17], v[226:233], 0
	v_mfma_f32_16x16x128_f8f6f4 v[42:45], v[10:17], v[218:225], 0
	v_mfma_f32_16x16x128_f8f6f4 v[46:49], v[2:9], v[218:225], 0
	v_mfma_f32_16x16x128_f8f6f4 v[54:57], v[2:9], v[210:217], 0
	v_mfma_f32_16x16x128_f8f6f4 v[50:53], v[10:17], v[210:217], 0
	v_mfma_f32_16x16x128_f8f6f4 v[58:61], v[10:17], v[202:209], 0
	v_mfma_f32_16x16x128_f8f6f4 v[62:65], v[2:9], v[202:209], 0
	s_setprio 0
	s_barrier
	ds_read_b128 v[18:21], v200 offset:32768
	ds_read_b128 v[22:25], v200 offset:33792
	ds_read_b128 v[26:29], v200 offset:34816
	ds_read_b128 v[30:33], v200 offset:35840
	ds_read_b128 v[2:5], v200 offset:49152
	ds_read_b128 v[6:9], v200 offset:50176
	ds_read_b128 v[10:13], v200 offset:51200
	ds_read_b128 v[14:17], v200 offset:52224
	s_add_u32 s8, s80, 0x20100
	s_addc_u32 s9, s81, 0
	s_mov_b32 m0, s86
	v_lshl_add_u64 v[234:235], s[8:9], 0, v[162:163]
	ds_read_b128 v[202:205], v201 offset:32768
	ds_read_b128 v[206:209], v201 offset:33792
	ds_read_b128 v[210:213], v201 offset:34816
	ds_read_b128 v[214:217], v201 offset:35840
	ds_read_b128 v[218:221], v201 offset:36864
	ds_read_b128 v[222:225], v201 offset:37888
	ds_read_b128 v[226:229], v201 offset:38912
	ds_read_b128 v[230:233], v201 offset:39936
	global_load_lds_dwordx4 v[234:235], off
	v_lshl_add_u64 v[234:235], s[8:9], 0, v[166:167]
	s_mov_b32 m0, s87
	s_nop 0
	global_load_lds_dwordx4 v[234:235], off
	s_waitcnt vmcnt(8)
	s_waitcnt lgkmcnt(0)
	s_barrier
	s_setprio 1
	s_waitcnt lgkmcnt(0)
	v_mfma_f32_16x16x128_f8f6f4 v[158:161], v[18:25], v[202:209], v[158:161]
	v_mfma_f32_16x16x128_f8f6f4 v[154:157], v[26:33], v[202:209], v[154:157]
	v_mfma_f32_16x16x128_f8f6f4 v[146:149], v[26:33], v[210:217], v[146:149]
	v_mfma_f32_16x16x128_f8f6f4 v[150:153], v[18:25], v[210:217], v[150:153]
	v_mfma_f32_16x16x128_f8f6f4 v[142:145], v[18:25], v[218:225], v[142:145]
	v_mfma_f32_16x16x128_f8f6f4 v[138:141], v[26:33], v[218:225], v[138:141]
	v_mfma_f32_16x16x128_f8f6f4 v[130:133], v[26:33], v[226:233], v[130:133]
	v_mfma_f32_16x16x128_f8f6f4 v[134:137], v[18:25], v[226:233], v[134:137]
	s_setprio 0
	s_setprio 1
	v_mfma_f32_16x16x128_f8f6f4 v[102:105], v[2:9], v[226:233], v[102:105]
	v_mfma_f32_16x16x128_f8f6f4 v[98:101], v[10:17], v[226:233], v[98:101]
	v_mfma_f32_16x16x128_f8f6f4 v[106:109], v[10:17], v[218:225], v[106:109]
	v_mfma_f32_16x16x128_f8f6f4 v[110:113], v[2:9], v[218:225], v[110:113]
	v_mfma_f32_16x16x128_f8f6f4 v[118:121], v[2:9], v[210:217], v[118:121]
	v_mfma_f32_16x16x128_f8f6f4 v[114:117], v[10:17], v[210:217], v[114:117]
	v_mfma_f32_16x16x128_f8f6f4 v[122:125], v[10:17], v[202:209], v[122:125]
	v_mfma_f32_16x16x128_f8f6f4 v[126:129], v[2:9], v[202:209], v[126:129]
	s_setprio 0
	s_barrier
	s_mov_b32 m0, s89
	v_lshl_add_u64 v[182:183], v[182:183], 0, s[48:49]
	s_add_u32 s8, s78, 0x20180
	ds_read_b128 v[202:205], v201 offset:49152
	ds_read_b128 v[206:209], v201 offset:50176
	ds_read_b128 v[210:213], v201 offset:51200
	ds_read_b128 v[214:217], v201 offset:52224
	ds_read_b128 v[218:221], v201 offset:53248
	ds_read_b128 v[222:225], v201 offset:54272
	ds_read_b128 v[226:229], v201 offset:55296
	ds_read_b128 v[230:233], v201 offset:56320
	global_load_lds_dwordx4 v[182:183], off
	v_lshl_add_u64 v[182:183], v[184:185], 0, s[48:49]
	s_mov_b32 m0, s90
	s_addc_u32 s9, s79, 0
	global_load_lds_dwordx4 v[182:183], off
	v_lshl_add_u64 v[182:183], s[8:9], 0, v[164:165]
	s_mov_b32 m0, s93
	s_nop 0
	global_load_lds_dwordx4 v[182:183], off
	v_lshl_add_u64 v[182:183], s[8:9], 0, v[168:169]
	s_mov_b32 m0, s95
	s_nop 0
	global_load_lds_dwordx4 v[182:183], off
	v_lshl_add_u64 v[182:183], v[186:187], 0, s[48:49]
	s_mov_b32 m0, s91
	s_nop 0
	global_load_lds_dwordx4 v[182:183], off
	v_lshl_add_u64 v[182:183], v[188:189], 0, s[48:49]
	s_mov_b32 m0, s92
	s_nop 0
	global_load_lds_dwordx4 v[182:183], off
	s_waitcnt vmcnt(8)
	s_waitcnt lgkmcnt(0)
	s_barrier
	s_setprio 1
	s_waitcnt lgkmcnt(0)
	v_mfma_f32_16x16x128_f8f6f4 v[94:97], v[18:25], v[202:209], v[94:97]
	v_mfma_f32_16x16x128_f8f6f4 v[90:93], v[26:33], v[202:209], v[90:93]
	v_mfma_f32_16x16x128_f8f6f4 v[82:85], v[26:33], v[210:217], v[82:85]
	v_mfma_f32_16x16x128_f8f6f4 v[86:89], v[18:25], v[210:217], v[86:89]
	v_mfma_f32_16x16x128_f8f6f4 v[78:81], v[18:25], v[218:225], v[78:81]
	v_mfma_f32_16x16x128_f8f6f4 v[74:77], v[26:33], v[218:225], v[74:77]
	v_mfma_f32_16x16x128_f8f6f4 v[66:69], v[26:33], v[226:233], v[66:69]
	v_mfma_f32_16x16x128_f8f6f4 v[70:73], v[18:25], v[226:233], v[70:73]
	s_setprio 0
	s_setprio 1
	v_mfma_f32_16x16x128_f8f6f4 v[38:41], v[2:9], v[226:233], v[38:41]
	v_mfma_f32_16x16x128_f8f6f4 v[34:37], v[10:17], v[226:233], v[34:37]
	v_mfma_f32_16x16x128_f8f6f4 v[42:45], v[10:17], v[218:225], v[42:45]
	v_mfma_f32_16x16x128_f8f6f4 v[46:49], v[2:9], v[218:225], v[46:49]
	v_mfma_f32_16x16x128_f8f6f4 v[54:57], v[2:9], v[210:217], v[54:57]
	v_mfma_f32_16x16x128_f8f6f4 v[50:53], v[10:17], v[210:217], v[50:53]
	v_mfma_f32_16x16x128_f8f6f4 v[58:61], v[10:17], v[202:209], v[58:61]
	v_mfma_f32_16x16x128_f8f6f4 v[62:65], v[2:9], v[202:209], v[62:65]
	s_setprio 0
	s_barrier
	s_add_u32 s80, s80, 0x20180
	s_addc_u32 s81, s81, 0
	s_add_u32 s8, s78, 0x200
	s_addc_u32 s9, s79, 0
	s_mov_b32 s62, 0
.LBB0_601:
	ds_read_b128 v[2:5], v200
	ds_read_b128 v[6:9], v200 offset:1024
	ds_read_b128 v[18:21], v200 offset:2048
	ds_read_b128 v[22:25], v200 offset:3072
	ds_read_b128 v[26:29], v200 offset:16384
	ds_read_b128 v[30:33], v200 offset:17408
	ds_read_b128 v[182:185], v200 offset:18432
	ds_read_b128 v[186:189], v200 offset:19456
	s_add_u32 s63, s80, 0xfffe0080
	s_addc_u32 s71, s81, -1
	s_cmp_eq_u32 s62, 4
	s_cselect_b32 s83, s4, s71
	s_cselect_b32 s82, s5, s63
	s_cselect_b32 s79, s53, s9
	s_cselect_b32 s78, s55, s8
	s_mov_b32 m0, s96
	v_lshl_add_u64 v[226:227], s[80:81], 0, v[170:171]
	ds_read_b128 v[10:13], v201
	ds_read_b128 v[14:17], v201 offset:1024
	ds_read_b128 v[202:205], v201 offset:2048
	ds_read_b128 v[206:209], v201 offset:3072
	ds_read_b128 v[210:213], v201 offset:4096
	ds_read_b128 v[214:217], v201 offset:5120
	ds_read_b128 v[218:221], v201 offset:6144
	ds_read_b128 v[222:225], v201 offset:7168
	global_load_lds_dwordx4 v[226:227], off
	v_lshl_add_u64 v[226:227], s[80:81], 0, v[172:173]
	s_mov_b32 m0, s61
	s_nop 0
	global_load_lds_dwordx4 v[226:227], off
	s_waitcnt vmcnt(8)
	s_waitcnt lgkmcnt(0)
	s_barrier
	s_setprio 1
	s_waitcnt lgkmcnt(0)
	v_mfma_f32_16x16x128_f8f6f4 v[158:161], v[2:9], v[10:17], v[158:161]
	v_mfma_f32_16x16x128_f8f6f4 v[154:157], v[18:25], v[10:17], v[154:157]
	v_mfma_f32_16x16x128_f8f6f4 v[146:149], v[18:25], v[202:209], v[146:149]
	v_mfma_f32_16x16x128_f8f6f4 v[150:153], v[2:9], v[202:209], v[150:153]
	v_mfma_f32_16x16x128_f8f6f4 v[142:145], v[2:9], v[210:217], v[142:145]
	v_mfma_f32_16x16x128_f8f6f4 v[138:141], v[18:25], v[210:217], v[138:141]
	v_mfma_f32_16x16x128_f8f6f4 v[130:133], v[18:25], v[218:225], v[130:133]
	v_mfma_f32_16x16x128_f8f6f4 v[134:137], v[2:9], v[218:225], v[134:137]
	s_setprio 0
	s_setprio 1
	v_mfma_f32_16x16x128_f8f6f4 v[102:105], v[26:33], v[218:225], v[102:105]
	v_mfma_f32_16x16x128_f8f6f4 v[98:101], v[182:189], v[218:225], v[98:101]
	v_mfma_f32_16x16x128_f8f6f4 v[106:109], v[182:189], v[210:217], v[106:109]
	v_mfma_f32_16x16x128_f8f6f4 v[110:113], v[26:33], v[210:217], v[110:113]
	v_mfma_f32_16x16x128_f8f6f4 v[118:121], v[26:33], v[202:209], v[118:121]
	v_mfma_f32_16x16x128_f8f6f4 v[114:117], v[182:189], v[202:209], v[114:117]
	v_mfma_f32_16x16x128_f8f6f4 v[122:125], v[182:189], v[10:17], v[122:125]
	v_mfma_f32_16x16x128_f8f6f4 v[126:129], v[26:33], v[10:17], v[126:129]
	s_setprio 0
	s_barrier
	s_mov_b32 m0, s68
	v_lshl_add_u64 v[10:11], s[78:79], 0, v[164:165]
	s_add_u32 vcc_lo, s78, 0x20000
	ds_read_b128 v[202:205], v201 offset:16384
	ds_read_b128 v[206:209], v201 offset:17408
	ds_read_b128 v[210:213], v201 offset:18432
	ds_read_b128 v[214:217], v201 offset:19456
	ds_read_b128 v[218:221], v201 offset:20480
	ds_read_b128 v[222:225], v201 offset:21504
	ds_read_b128 v[226:229], v201 offset:22528
	ds_read_b128 v[230:233], v201 offset:23552
	global_load_lds_dwordx4 v[10:11], off
	v_lshl_add_u64 v[12:13], s[78:79], 0, v[168:169]
	s_mov_b32 m0, s69
	s_addc_u32 vcc_hi, s79, 0
	global_load_lds_dwordx4 v[12:13], off
	v_lshl_add_u64 v[14:15], vcc, 0, v[164:165]
	s_mov_b32 m0, s77
	v_lshl_add_u64 v[16:17], s[82:83], 0, v[166:167]
	global_load_lds_dwordx4 v[14:15], off
	v_lshl_add_u64 v[14:15], vcc, 0, v[168:169]
	s_mov_b32 m0, s84
	s_nop 0
	global_load_lds_dwordx4 v[14:15], off
	v_lshl_add_u64 v[14:15], s[82:83], 0, v[162:163]
	s_mov_b32 m0, s33
	s_nop 0
	global_load_lds_dwordx4 v[14:15], off
	s_mov_b32 m0, s85
	s_nop 0
	global_load_lds_dwordx4 v[16:17], off
	s_waitcnt vmcnt(8)
	s_waitcnt lgkmcnt(0)
	s_barrier
	s_setprio 1
	s_waitcnt lgkmcnt(0)
	v_mfma_f32_16x16x128_f8f6f4 v[94:97], v[2:9], v[202:209], v[94:97]
	v_mfma_f32_16x16x128_f8f6f4 v[90:93], v[18:25], v[202:209], v[90:93]
	v_mfma_f32_16x16x128_f8f6f4 v[82:85], v[18:25], v[210:217], v[82:85]
	v_mfma_f32_16x16x128_f8f6f4 v[86:89], v[2:9], v[210:217], v[86:89]
	v_mfma_f32_16x16x128_f8f6f4 v[78:81], v[2:9], v[218:225], v[78:81]
	v_mfma_f32_16x16x128_f8f6f4 v[74:77], v[18:25], v[218:225], v[74:77]
	v_mfma_f32_16x16x128_f8f6f4 v[66:69], v[18:25], v[226:233], v[66:69]
	v_mfma_f32_16x16x128_f8f6f4 v[70:73], v[2:9], v[226:233], v[70:73]
	s_setprio 0
	s_setprio 1
	v_mfma_f32_16x16x128_f8f6f4 v[38:41], v[26:33], v[226:233], v[38:41]
	v_mfma_f32_16x16x128_f8f6f4 v[34:37], v[182:189], v[226:233], v[34:37]
	v_mfma_f32_16x16x128_f8f6f4 v[42:45], v[182:189], v[218:225], v[42:45]
	v_mfma_f32_16x16x128_f8f6f4 v[46:49], v[26:33], v[218:225], v[46:49]
	v_mfma_f32_16x16x128_f8f6f4 v[54:57], v[26:33], v[210:217], v[54:57]
	v_mfma_f32_16x16x128_f8f6f4 v[50:53], v[182:189], v[210:217], v[50:53]
	v_mfma_f32_16x16x128_f8f6f4 v[58:61], v[182:189], v[202:209], v[58:61]
	v_mfma_f32_16x16x128_f8f6f4 v[62:65], v[26:33], v[202:209], v[62:65]
	s_setprio 0
	s_barrier
	ds_read_b128 v[18:21], v200 offset:32768
	ds_read_b128 v[22:25], v200 offset:33792
	ds_read_b128 v[26:29], v200 offset:34816
	ds_read_b128 v[30:33], v200 offset:35840
	ds_read_b128 v[2:5], v200 offset:49152
	ds_read_b128 v[6:9], v200 offset:50176
	ds_read_b128 v[182:185], v200 offset:51200
	ds_read_b128 v[186:189], v200 offset:52224
	s_add_u32 s82, s82, 0x20000
	s_addc_u32 s83, s83, 0
	s_mov_b32 m0, s86
	v_lshl_add_u64 v[234:235], s[82:83], 0, v[162:163]
	ds_read_b128 v[202:205], v201 offset:32768
	ds_read_b128 v[206:209], v201 offset:33792
	ds_read_b128 v[210:213], v201 offset:34816
	ds_read_b128 v[214:217], v201 offset:35840
	ds_read_b128 v[218:221], v201 offset:36864
	ds_read_b128 v[222:225], v201 offset:37888
	ds_read_b128 v[226:229], v201 offset:38912
	ds_read_b128 v[230:233], v201 offset:39936
	global_load_lds_dwordx4 v[234:235], off
	v_lshl_add_u64 v[234:235], s[82:83], 0, v[166:167]
	s_mov_b32 m0, s87
	s_nop 0
	global_load_lds_dwordx4 v[234:235], off
	s_waitcnt vmcnt(8)
	s_waitcnt lgkmcnt(0)
	s_barrier
	s_setprio 1
	s_waitcnt lgkmcnt(0)
	v_mfma_f32_16x16x128_f8f6f4 v[158:161], v[18:25], v[202:209], v[158:161]
	v_mfma_f32_16x16x128_f8f6f4 v[154:157], v[26:33], v[202:209], v[154:157]
	v_mfma_f32_16x16x128_f8f6f4 v[146:149], v[26:33], v[210:217], v[146:149]
	v_mfma_f32_16x16x128_f8f6f4 v[150:153], v[18:25], v[210:217], v[150:153]
	v_mfma_f32_16x16x128_f8f6f4 v[142:145], v[18:25], v[218:225], v[142:145]
	v_mfma_f32_16x16x128_f8f6f4 v[138:141], v[26:33], v[218:225], v[138:141]
	v_mfma_f32_16x16x128_f8f6f4 v[130:133], v[26:33], v[226:233], v[130:133]
	v_mfma_f32_16x16x128_f8f6f4 v[134:137], v[18:25], v[226:233], v[134:137]
	s_setprio 0
	s_setprio 1
	v_mfma_f32_16x16x128_f8f6f4 v[102:105], v[2:9], v[226:233], v[102:105]
	v_mfma_f32_16x16x128_f8f6f4 v[98:101], v[182:189], v[226:233], v[98:101]
	v_mfma_f32_16x16x128_f8f6f4 v[106:109], v[182:189], v[218:225], v[106:109]
	v_mfma_f32_16x16x128_f8f6f4 v[110:113], v[2:9], v[218:225], v[110:113]
	v_mfma_f32_16x16x128_f8f6f4 v[118:121], v[2:9], v[210:217], v[118:121]
	v_mfma_f32_16x16x128_f8f6f4 v[114:117], v[182:189], v[210:217], v[114:117]
	v_mfma_f32_16x16x128_f8f6f4 v[122:125], v[182:189], v[202:209], v[122:125]
	v_mfma_f32_16x16x128_f8f6f4 v[126:129], v[2:9], v[202:209], v[126:129]
	s_setprio 0
	s_barrier
	s_mov_b32 m0, s89
	v_lshl_add_u64 v[10:11], v[10:11], 0, s[42:43]
	s_add_u32 s78, s78, 0x20080
	ds_read_b128 v[202:205], v201 offset:49152
	ds_read_b128 v[206:209], v201 offset:50176
	ds_read_b128 v[210:213], v201 offset:51200
	ds_read_b128 v[214:217], v201 offset:52224
	ds_read_b128 v[218:221], v201 offset:53248
	ds_read_b128 v[222:225], v201 offset:54272
	ds_read_b128 v[226:229], v201 offset:55296
	ds_read_b128 v[230:233], v201 offset:56320
	global_load_lds_dwordx4 v[10:11], off
	v_lshl_add_u64 v[10:11], v[12:13], 0, s[42:43]
	s_mov_b32 m0, s90
	s_addc_u32 s79, s79, 0
	global_load_lds_dwordx4 v[10:11], off
	v_lshl_add_u64 v[10:11], s[78:79], 0, v[164:165]
	s_mov_b32 m0, s93
	s_nop 0
	global_load_lds_dwordx4 v[10:11], off
	v_lshl_add_u64 v[10:11], s[78:79], 0, v[168:169]
	s_mov_b32 m0, s95
	s_nop 0
	global_load_lds_dwordx4 v[10:11], off
	v_lshl_add_u64 v[10:11], v[14:15], 0, s[42:43]
	s_mov_b32 m0, s91
	s_nop 0
	global_load_lds_dwordx4 v[10:11], off
	v_lshl_add_u64 v[10:11], v[16:17], 0, s[42:43]
	s_mov_b32 m0, s92
	s_nop 0
	global_load_lds_dwordx4 v[10:11], off
	s_waitcnt vmcnt(8)
	s_waitcnt lgkmcnt(0)
	s_barrier
	s_setprio 1
	s_waitcnt lgkmcnt(0)
	v_mfma_f32_16x16x128_f8f6f4 v[94:97], v[18:25], v[202:209], v[94:97]
	v_mfma_f32_16x16x128_f8f6f4 v[90:93], v[26:33], v[202:209], v[90:93]
	v_mfma_f32_16x16x128_f8f6f4 v[82:85], v[26:33], v[210:217], v[82:85]
	v_mfma_f32_16x16x128_f8f6f4 v[86:89], v[18:25], v[210:217], v[86:89]
	v_mfma_f32_16x16x128_f8f6f4 v[78:81], v[18:25], v[218:225], v[78:81]
	v_mfma_f32_16x16x128_f8f6f4 v[74:77], v[26:33], v[218:225], v[74:77]
	v_mfma_f32_16x16x128_f8f6f4 v[66:69], v[26:33], v[226:233], v[66:69]
	v_mfma_f32_16x16x128_f8f6f4 v[70:73], v[18:25], v[226:233], v[70:73]
	s_setprio 0
	s_setprio 1
	v_mfma_f32_16x16x128_f8f6f4 v[38:41], v[2:9], v[226:233], v[38:41]
	v_mfma_f32_16x16x128_f8f6f4 v[34:37], v[182:189], v[226:233], v[34:37]
	v_mfma_f32_16x16x128_f8f6f4 v[42:45], v[182:189], v[218:225], v[42:45]
	v_mfma_f32_16x16x128_f8f6f4 v[46:49], v[2:9], v[218:225], v[46:49]
	v_mfma_f32_16x16x128_f8f6f4 v[54:57], v[2:9], v[210:217], v[54:57]
	v_mfma_f32_16x16x128_f8f6f4 v[50:53], v[182:189], v[210:217], v[50:53]
	v_mfma_f32_16x16x128_f8f6f4 v[58:61], v[182:189], v[202:209], v[58:61]
	v_mfma_f32_16x16x128_f8f6f4 v[62:65], v[2:9], v[202:209], v[62:65]
	s_setprio 0
	s_barrier
	s_add_i32 s62, s62, 2
	s_add_u32 s80, s80, 0x100
	s_addc_u32 s81, s81, 0
	s_add_u32 s8, s8, 0x100
	s_addc_u32 s9, s9, 0
	s_cmp_gt_u32 s62, 5
	s_cbranch_scc0 .LBB0_601
	s_and_b64 vcc, exec, s[44:45]
	s_cbranch_vccz .LBB0_604
	s_barrier

.LBB0_616:
	ds_read_b128 v[18:21], v188
	ds_read_b128 v[22:25], v188 offset:1024
	ds_read_b128 v[26:29], v188 offset:2048
	ds_read_b128 v[30:33], v188 offset:3072
	ds_read_b128 v[2:5], v188 offset:16384
	ds_read_b128 v[6:9], v188 offset:17408
	ds_read_b128 v[10:13], v188 offset:18432
	ds_read_b128 v[14:17], v188 offset:19456
	s_ashr_i32 s55, s54, 31
	s_lshl_b64 s[62:63], s[54:55], 17
	s_add_u32 s72, s36, s62
	s_addc_u32 s73, s37, s63
	s_and_b64 s[62:63], s[2:3], exec
	s_cselect_b32 s85, s73, s79
	s_cselect_b32 s84, s72, s78
	s_ashr_i32 s53, s52, 31
	s_lshl_b64 s[62:63], s[52:53], 17
	s_add_u32 s74, s94, s62
	v_readlane_b32 s5, v254, 8
	s_addc_u32 s75, s5, s63
	s_and_b64 s[62:63], s[2:3], exec
	s_cselect_b32 s83, s75, s81
	s_cselect_b32 s82, s74, s80
	s_add_u32 s62, s78, 0x10080
	s_addc_u32 s63, s79, 0
	s_mov_b32 m0, s96
	v_lshl_add_u64 v[174:175], s[62:63], 0, v[166:167]
	ds_read_b128 v[196:199], v189
	ds_read_b128 v[200:203], v189 offset:1024
	ds_read_b128 v[204:207], v189 offset:2048
	ds_read_b128 v[208:211], v189 offset:3072
	ds_read_b128 v[212:215], v189 offset:4096
	ds_read_b128 v[216:219], v189 offset:5120
	ds_read_b128 v[220:223], v189 offset:6144
	ds_read_b128 v[224:227], v189 offset:7168
	global_load_lds_dwordx4 v[174:175], off
	v_lshl_add_u64 v[174:175], s[62:63], 0, v[168:169]
	s_mov_b32 m0, s97
	s_nop 0
	global_load_lds_dwordx4 v[174:175], off
	s_waitcnt vmcnt(8)
	s_waitcnt lgkmcnt(0)
	s_barrier
	s_setprio 1
	s_waitcnt lgkmcnt(0)
	v_mfma_f32_16x16x128_f8f6f4 v[158:161], v[18:25], v[196:203], 0
	v_mfma_f32_16x16x128_f8f6f4 v[154:157], v[26:33], v[196:203], 0
	v_mfma_f32_16x16x128_f8f6f4 v[146:149], v[26:33], v[204:211], 0
	v_mfma_f32_16x16x128_f8f6f4 v[150:153], v[18:25], v[204:211], 0
	v_mfma_f32_16x16x128_f8f6f4 v[142:145], v[18:25], v[212:219], 0
	v_mfma_f32_16x16x128_f8f6f4 v[138:141], v[26:33], v[212:219], 0
	v_mfma_f32_16x16x128_f8f6f4 v[130:133], v[26:33], v[220:227], 0
	v_mfma_f32_16x16x128_f8f6f4 v[134:137], v[18:25], v[220:227], 0
	s_setprio 0
	s_setprio 1
	v_mfma_f32_16x16x128_f8f6f4 v[102:105], v[2:9], v[220:227], 0
	v_mfma_f32_16x16x128_f8f6f4 v[98:101], v[10:17], v[220:227], 0
	v_mfma_f32_16x16x128_f8f6f4 v[106:109], v[10:17], v[212:219], 0
	v_mfma_f32_16x16x128_f8f6f4 v[110:113], v[2:9], v[212:219], 0
	v_mfma_f32_16x16x128_f8f6f4 v[118:121], v[2:9], v[204:211], 0
	v_mfma_f32_16x16x128_f8f6f4 v[114:117], v[10:17], v[204:211], 0
	v_mfma_f32_16x16x128_f8f6f4 v[122:125], v[10:17], v[196:203], 0
	v_mfma_f32_16x16x128_f8f6f4 v[126:129], v[2:9], v[196:203], 0
	s_setprio 0
	s_barrier
	v_lshl_add_u64 v[174:175], s[80:81], 0, v[162:163]
	s_mov_b32 m0, s61
	v_lshl_add_u64 v[176:177], v[174:175], 0, s[46:47]
	ds_read_b128 v[196:199], v189 offset:16384
	ds_read_b128 v[200:203], v189 offset:17408
	ds_read_b128 v[204:207], v189 offset:18432
	ds_read_b128 v[208:211], v189 offset:19456
	ds_read_b128 v[212:215], v189 offset:20480
	ds_read_b128 v[216:219], v189 offset:21504
	ds_read_b128 v[220:223], v189 offset:22528
	ds_read_b128 v[224:227], v189 offset:23552
	global_load_lds_dwordx4 v[176:177], off
	v_lshl_add_u64 v[176:177], s[80:81], 0, v[164:165]
	s_add_u32 s62, s80, 0x10100
	v_lshl_add_u64 v[182:183], v[176:177], 0, s[46:47]
	s_mov_b32 m0, s68
	s_addc_u32 s63, s81, 0
	global_load_lds_dwordx4 v[182:183], off
	v_lshl_add_u64 v[182:183], s[62:63], 0, v[162:163]
	s_mov_b32 m0, s69
	s_nop 0
	global_load_lds_dwordx4 v[182:183], off
	v_lshl_add_u64 v[182:183], s[62:63], 0, v[164:165]
	s_mov_b32 m0, s77
	s_nop 0
	global_load_lds_dwordx4 v[182:183], off
	v_lshl_add_u64 v[182:183], s[78:79], 0, v[166:167]
	v_lshl_add_u64 v[184:185], v[182:183], 0, s[46:47]
	s_mov_b32 m0, s51
	s_nop 0
	global_load_lds_dwordx4 v[184:185], off
	v_lshl_add_u64 v[184:185], s[78:79], 0, v[168:169]
	v_lshl_add_u64 v[228:229], v[184:185], 0, s[46:47]
	s_mov_b32 m0, s86
	s_nop 0
	global_load_lds_dwordx4 v[228:229], off
	s_waitcnt vmcnt(8)
	s_waitcnt lgkmcnt(0)
	s_barrier
	s_setprio 1
	s_waitcnt lgkmcnt(0)
	v_mfma_f32_16x16x128_f8f6f4 v[94:97], v[18:25], v[196:203], 0
	v_mfma_f32_16x16x128_f8f6f4 v[90:93], v[26:33], v[196:203], 0
	v_mfma_f32_16x16x128_f8f6f4 v[82:85], v[26:33], v[204:211], 0
	v_mfma_f32_16x16x128_f8f6f4 v[86:89], v[18:25], v[204:211], 0
	v_mfma_f32_16x16x128_f8f6f4 v[78:81], v[18:25], v[212:219], 0
	v_mfma_f32_16x16x128_f8f6f4 v[74:77], v[26:33], v[212:219], 0
	v_mfma_f32_16x16x128_f8f6f4 v[66:69], v[26:33], v[220:227], 0
	v_mfma_f32_16x16x128_f8f6f4 v[70:73], v[18:25], v[220:227], 0
	s_setprio 0
	s_setprio 1
	v_mfma_f32_16x16x128_f8f6f4 v[38:41], v[2:9], v[220:227], 0
	v_mfma_f32_16x16x128_f8f6f4 v[34:37], v[10:17], v[220:227], 0
	v_mfma_f32_16x16x128_f8f6f4 v[42:45], v[10:17], v[212:219], 0
	v_mfma_f32_16x16x128_f8f6f4 v[46:49], v[2:9], v[212:219], 0
	v_mfma_f32_16x16x128_f8f6f4 v[54:57], v[2:9], v[204:211], 0
	v_mfma_f32_16x16x128_f8f6f4 v[50:53], v[10:17], v[204:211], 0
	v_mfma_f32_16x16x128_f8f6f4 v[58:61], v[10:17], v[196:203], 0
	v_mfma_f32_16x16x128_f8f6f4 v[62:65], v[2:9], v[196:203], 0
	s_setprio 0
	s_barrier
	ds_read_b128 v[2:5], v188 offset:32768
	ds_read_b128 v[6:9], v188 offset:33792
	ds_read_b128 v[10:13], v188 offset:34816
	ds_read_b128 v[14:17], v188 offset:35840
	ds_read_b128 v[18:21], v188 offset:49152
	ds_read_b128 v[22:25], v188 offset:50176
	ds_read_b128 v[26:29], v188 offset:51200
	ds_read_b128 v[30:33], v188 offset:52224
	s_add_u32 s62, s78, 0x10100
	s_addc_u32 s63, s79, 0
	s_mov_b32 m0, s87
	v_lshl_add_u64 v[228:229], s[62:63], 0, v[166:167]
	ds_read_b128 v[196:199], v189 offset:32768
	ds_read_b128 v[200:203], v189 offset:33792
	ds_read_b128 v[204:207], v189 offset:34816
	ds_read_b128 v[208:211], v189 offset:35840
	ds_read_b128 v[212:215], v189 offset:36864
	ds_read_b128 v[216:219], v189 offset:37888
	ds_read_b128 v[220:223], v189 offset:38912
	ds_read_b128 v[224:227], v189 offset:39936
	global_load_lds_dwordx4 v[228:229], off
	v_lshl_add_u64 v[228:229], s[62:63], 0, v[168:169]
	s_mov_b32 m0, s88
	s_nop 0
	global_load_lds_dwordx4 v[228:229], off
	s_waitcnt vmcnt(8)
	s_waitcnt lgkmcnt(0)
	s_barrier
	s_setprio 1
	s_waitcnt lgkmcnt(0)
	v_mfma_f32_16x16x128_f8f6f4 v[158:161], v[2:9], v[196:203], v[158:161]
	v_mfma_f32_16x16x128_f8f6f4 v[154:157], v[10:17], v[196:203], v[154:157]
	v_mfma_f32_16x16x128_f8f6f4 v[146:149], v[10:17], v[204:211], v[146:149]
	v_mfma_f32_16x16x128_f8f6f4 v[150:153], v[2:9], v[204:211], v[150:153]
	v_mfma_f32_16x16x128_f8f6f4 v[142:145], v[2:9], v[212:219], v[142:145]
	v_mfma_f32_16x16x128_f8f6f4 v[138:141], v[10:17], v[212:219], v[138:141]
	v_mfma_f32_16x16x128_f8f6f4 v[130:133], v[10:17], v[220:227], v[130:133]
	v_mfma_f32_16x16x128_f8f6f4 v[134:137], v[2:9], v[220:227], v[134:137]
	s_setprio 0
	s_setprio 1
	v_mfma_f32_16x16x128_f8f6f4 v[102:105], v[18:25], v[220:227], v[102:105]
	v_mfma_f32_16x16x128_f8f6f4 v[98:101], v[26:33], v[220:227], v[98:101]
	v_mfma_f32_16x16x128_f8f6f4 v[106:109], v[26:33], v[212:219], v[106:109]
	v_mfma_f32_16x16x128_f8f6f4 v[110:113], v[18:25], v[212:219], v[110:113]
	v_mfma_f32_16x16x128_f8f6f4 v[118:121], v[18:25], v[204:211], v[118:121]
	v_mfma_f32_16x16x128_f8f6f4 v[114:117], v[26:33], v[204:211], v[114:117]
	v_mfma_f32_16x16x128_f8f6f4 v[122:125], v[26:33], v[196:203], v[122:125]
	v_mfma_f32_16x16x128_f8f6f4 v[126:129], v[18:25], v[196:203], v[126:129]
	s_setprio 0
	s_barrier
	s_mov_b32 m0, s89
	v_lshl_add_u64 v[174:175], v[174:175], 0, s[48:49]
	s_add_u32 s62, s80, 0x10180
	ds_read_b128 v[196:199], v189 offset:49152
	ds_read_b128 v[200:203], v189 offset:50176
	ds_read_b128 v[204:207], v189 offset:51200
	ds_read_b128 v[208:211], v189 offset:52224
	ds_read_b128 v[212:215], v189 offset:53248
	ds_read_b128 v[216:219], v189 offset:54272
	ds_read_b128 v[220:223], v189 offset:55296
	ds_read_b128 v[224:227], v189 offset:56320
	global_load_lds_dwordx4 v[174:175], off
	v_lshl_add_u64 v[174:175], v[176:177], 0, s[48:49]
	s_mov_b32 m0, s90
	s_addc_u32 s63, s81, 0
	global_load_lds_dwordx4 v[174:175], off
	v_lshl_add_u64 v[174:175], s[62:63], 0, v[162:163]
	s_mov_b32 m0, s93
	s_nop 0
	global_load_lds_dwordx4 v[174:175], off
	v_lshl_add_u64 v[174:175], s[62:63], 0, v[164:165]
	s_mov_b32 m0, s95
	s_nop 0
	global_load_lds_dwordx4 v[174:175], off
	v_lshl_add_u64 v[174:175], v[182:183], 0, s[48:49]
	s_mov_b32 m0, s91
	s_nop 0
	global_load_lds_dwordx4 v[174:175], off
	v_lshl_add_u64 v[174:175], v[184:185], 0, s[48:49]
	s_mov_b32 m0, s92
	s_nop 0
	global_load_lds_dwordx4 v[174:175], off
	s_waitcnt vmcnt(8)
	s_waitcnt lgkmcnt(0)
	s_barrier
	s_setprio 1
	s_waitcnt lgkmcnt(0)
	v_mfma_f32_16x16x128_f8f6f4 v[94:97], v[2:9], v[196:203], v[94:97]
	v_mfma_f32_16x16x128_f8f6f4 v[90:93], v[10:17], v[196:203], v[90:93]
	v_mfma_f32_16x16x128_f8f6f4 v[82:85], v[10:17], v[204:211], v[82:85]
	v_mfma_f32_16x16x128_f8f6f4 v[86:89], v[2:9], v[204:211], v[86:89]
	v_mfma_f32_16x16x128_f8f6f4 v[78:81], v[2:9], v[212:219], v[78:81]
	v_mfma_f32_16x16x128_f8f6f4 v[74:77], v[10:17], v[212:219], v[74:77]
	v_mfma_f32_16x16x128_f8f6f4 v[66:69], v[10:17], v[220:227], v[66:69]
	v_mfma_f32_16x16x128_f8f6f4 v[70:73], v[2:9], v[220:227], v[70:73]
	s_setprio 0
	s_setprio 1
	v_mfma_f32_16x16x128_f8f6f4 v[38:41], v[18:25], v[220:227], v[38:41]
	v_mfma_f32_16x16x128_f8f6f4 v[34:37], v[26:33], v[220:227], v[34:37]
	v_mfma_f32_16x16x128_f8f6f4 v[42:45], v[26:33], v[212:219], v[42:45]
	v_mfma_f32_16x16x128_f8f6f4 v[46:49], v[18:25], v[212:219], v[46:49]
	v_mfma_f32_16x16x128_f8f6f4 v[54:57], v[18:25], v[204:211], v[54:57]
	v_mfma_f32_16x16x128_f8f6f4 v[50:53], v[26:33], v[204:211], v[50:53]
	v_mfma_f32_16x16x128_f8f6f4 v[58:61], v[26:33], v[196:203], v[58:61]
	v_mfma_f32_16x16x128_f8f6f4 v[62:65], v[18:25], v[196:203], v[62:65]
	s_setprio 0
	s_barrier
	ds_read_b128 v[2:5], v188
	ds_read_b128 v[6:9], v188 offset:1024
	ds_read_b128 v[10:13], v188 offset:2048
	ds_read_b128 v[14:17], v188 offset:3072
	ds_read_b128 v[18:21], v188 offset:16384
	ds_read_b128 v[22:25], v188 offset:17408
	ds_read_b128 v[26:29], v188 offset:18432
	ds_read_b128 v[30:33], v188 offset:19456
	s_add_u32 s62, s78, 0x10180
	s_addc_u32 s63, s79, 0
	s_mov_b32 m0, s96
	v_lshl_add_u64 v[174:175], s[62:63], 0, v[166:167]
	ds_read_b128 v[196:199], v189
	ds_read_b128 v[200:203], v189 offset:1024
	ds_read_b128 v[204:207], v189 offset:2048
	ds_read_b128 v[208:211], v189 offset:3072
	ds_read_b128 v[212:215], v189 offset:4096
	ds_read_b128 v[216:219], v189 offset:5120
	ds_read_b128 v[220:223], v189 offset:6144
	ds_read_b128 v[224:227], v189 offset:7168
	global_load_lds_dwordx4 v[174:175], off
	v_lshl_add_u64 v[174:175], s[62:63], 0, v[168:169]
	s_mov_b32 m0, s97
	s_nop 0
	global_load_lds_dwordx4 v[174:175], off
	s_waitcnt vmcnt(8)
	s_waitcnt lgkmcnt(0)
	s_barrier
	s_setprio 1
	s_waitcnt lgkmcnt(0)
	v_mfma_f32_16x16x128_f8f6f4 v[158:161], v[2:9], v[196:203], v[158:161]
	v_mfma_f32_16x16x128_f8f6f4 v[154:157], v[10:17], v[196:203], v[154:157]
	v_mfma_f32_16x16x128_f8f6f4 v[146:149], v[10:17], v[204:211], v[146:149]
	v_mfma_f32_16x16x128_f8f6f4 v[150:153], v[2:9], v[204:211], v[150:153]
	v_mfma_f32_16x16x128_f8f6f4 v[142:145], v[2:9], v[212:219], v[142:145]
	v_mfma_f32_16x16x128_f8f6f4 v[138:141], v[10:17], v[212:219], v[138:141]
	v_mfma_f32_16x16x128_f8f6f4 v[130:133], v[10:17], v[220:227], v[130:133]
	v_mfma_f32_16x16x128_f8f6f4 v[134:137], v[2:9], v[220:227], v[134:137]
	s_setprio 0
	s_setprio 1
	v_mfma_f32_16x16x128_f8f6f4 v[102:105], v[18:25], v[220:227], v[102:105]
	v_mfma_f32_16x16x128_f8f6f4 v[98:101], v[26:33], v[220:227], v[98:101]
	v_mfma_f32_16x16x128_f8f6f4 v[106:109], v[26:33], v[212:219], v[106:109]
	v_mfma_f32_16x16x128_f8f6f4 v[110:113], v[18:25], v[212:219], v[110:113]
	v_mfma_f32_16x16x128_f8f6f4 v[118:121], v[18:25], v[204:211], v[118:121]
	v_mfma_f32_16x16x128_f8f6f4 v[114:117], v[26:33], v[204:211], v[114:117]
	v_mfma_f32_16x16x128_f8f6f4 v[122:125], v[26:33], v[196:203], v[122:125]
	v_mfma_f32_16x16x128_f8f6f4 v[126:129], v[18:25], v[196:203], v[126:129]
	s_setprio 0
	s_barrier
	s_mov_b32 m0, s61
	v_lshl_add_u64 v[174:175], s[82:83], 0, v[162:163]
	s_add_u32 s62, s82, 0x10000
	ds_read_b128 v[196:199], v189 offset:16384
	ds_read_b128 v[200:203], v189 offset:17408
	ds_read_b128 v[204:207], v189 offset:18432
	ds_read_b128 v[208:211], v189 offset:19456
	ds_read_b128 v[212:215], v189 offset:20480
	ds_read_b128 v[216:219], v189 offset:21504
	ds_read_b128 v[220:223], v189 offset:22528
	ds_read_b128 v[224:227], v189 offset:23552
	global_load_lds_dwordx4 v[174:175], off
	v_lshl_add_u64 v[176:177], s[82:83], 0, v[164:165]
	s_mov_b32 m0, s68
	s_addc_u32 s63, s83, 0
	global_load_lds_dwordx4 v[176:177], off
	v_lshl_add_u64 v[182:183], s[62:63], 0, v[162:163]
	s_mov_b32 m0, s69
	v_lshl_add_u64 v[184:185], s[84:85], 0, v[168:169]
	global_load_lds_dwordx4 v[182:183], off
	v_lshl_add_u64 v[182:183], s[62:63], 0, v[164:165]
	s_mov_b32 m0, s77
	s_nop 0
	global_load_lds_dwordx4 v[182:183], off
	v_lshl_add_u64 v[182:183], s[84:85], 0, v[166:167]
	s_mov_b32 m0, s51
	s_nop 0
	global_load_lds_dwordx4 v[182:183], off
	s_mov_b32 m0, s86
	s_nop 0
	global_load_lds_dwordx4 v[184:185], off
	s_waitcnt vmcnt(8)
	s_waitcnt lgkmcnt(0)
	s_barrier
	s_setprio 1
	s_waitcnt lgkmcnt(0)
	v_mfma_f32_16x16x128_f8f6f4 v[94:97], v[2:9], v[196:203], v[94:97]
	v_mfma_f32_16x16x128_f8f6f4 v[90:93], v[10:17], v[196:203], v[90:93]
	v_mfma_f32_16x16x128_f8f6f4 v[82:85], v[10:17], v[204:211], v[82:85]
	v_mfma_f32_16x16x128_f8f6f4 v[86:89], v[2:9], v[204:211], v[86:89]
	v_mfma_f32_16x16x128_f8f6f4 v[78:81], v[2:9], v[212:219], v[78:81]
	v_mfma_f32_16x16x128_f8f6f4 v[74:77], v[10:17], v[212:219], v[74:77]
	v_mfma_f32_16x16x128_f8f6f4 v[66:69], v[10:17], v[220:227], v[66:69]
	v_mfma_f32_16x16x128_f8f6f4 v[70:73], v[2:9], v[220:227], v[70:73]
	s_setprio 0
	s_setprio 1
	v_mfma_f32_16x16x128_f8f6f4 v[38:41], v[18:25], v[220:227], v[38:41]
	v_mfma_f32_16x16x128_f8f6f4 v[34:37], v[26:33], v[220:227], v[34:37]
	v_mfma_f32_16x16x128_f8f6f4 v[42:45], v[26:33], v[212:219], v[42:45]
	v_mfma_f32_16x16x128_f8f6f4 v[46:49], v[18:25], v[212:219], v[46:49]
	v_mfma_f32_16x16x128_f8f6f4 v[54:57], v[18:25], v[204:211], v[54:57]
	v_mfma_f32_16x16x128_f8f6f4 v[50:53], v[26:33], v[204:211], v[50:53]
	v_mfma_f32_16x16x128_f8f6f4 v[58:61], v[26:33], v[196:203], v[58:61]
	v_mfma_f32_16x16x128_f8f6f4 v[62:65], v[18:25], v[196:203], v[62:65]
	s_setprio 0
	s_barrier
	ds_read_b128 v[2:5], v188 offset:32768
	ds_read_b128 v[6:9], v188 offset:33792
	ds_read_b128 v[10:13], v188 offset:34816
	ds_read_b128 v[14:17], v188 offset:35840
	ds_read_b128 v[18:21], v188 offset:49152
	ds_read_b128 v[22:25], v188 offset:50176
	ds_read_b128 v[26:29], v188 offset:51200
	ds_read_b128 v[30:33], v188 offset:52224
	s_add_u32 s62, s84, 0x10000
	s_addc_u32 s63, s85, 0
	s_mov_b32 m0, s87
	v_lshl_add_u64 v[228:229], s[62:63], 0, v[166:167]
	ds_read_b128 v[196:199], v189 offset:32768
	ds_read_b128 v[200:203], v189 offset:33792
	ds_read_b128 v[204:207], v189 offset:34816
	ds_read_b128 v[208:211], v189 offset:35840
	ds_read_b128 v[212:215], v189 offset:36864
	ds_read_b128 v[216:219], v189 offset:37888
	ds_read_b128 v[220:223], v189 offset:38912
	ds_read_b128 v[224:227], v189 offset:39936
	global_load_lds_dwordx4 v[228:229], off
	v_lshl_add_u64 v[228:229], s[62:63], 0, v[168:169]
	s_mov_b32 m0, s88
	s_nop 0
	global_load_lds_dwordx4 v[228:229], off
	s_waitcnt vmcnt(8)
	s_waitcnt lgkmcnt(0)
	s_barrier
	s_setprio 1
	s_waitcnt lgkmcnt(0)
	v_mfma_f32_16x16x128_f8f6f4 v[158:161], v[2:9], v[196:203], v[158:161]
	v_mfma_f32_16x16x128_f8f6f4 v[154:157], v[10:17], v[196:203], v[154:157]
	v_mfma_f32_16x16x128_f8f6f4 v[146:149], v[10:17], v[204:211], v[146:149]
	v_mfma_f32_16x16x128_f8f6f4 v[150:153], v[2:9], v[204:211], v[150:153]
	v_mfma_f32_16x16x128_f8f6f4 v[142:145], v[2:9], v[212:219], v[142:145]
	v_mfma_f32_16x16x128_f8f6f4 v[138:141], v[10:17], v[212:219], v[138:141]
	v_mfma_f32_16x16x128_f8f6f4 v[130:133], v[10:17], v[220:227], v[130:133]
	v_mfma_f32_16x16x128_f8f6f4 v[134:137], v[2:9], v[220:227], v[134:137]
	s_setprio 0
	s_setprio 1
	v_mfma_f32_16x16x128_f8f6f4 v[102:105], v[18:25], v[220:227], v[102:105]
	v_mfma_f32_16x16x128_f8f6f4 v[98:101], v[26:33], v[220:227], v[98:101]
	v_mfma_f32_16x16x128_f8f6f4 v[106:109], v[26:33], v[212:219], v[106:109]
	v_mfma_f32_16x16x128_f8f6f4 v[110:113], v[18:25], v[212:219], v[110:113]
	v_mfma_f32_16x16x128_f8f6f4 v[118:121], v[18:25], v[204:211], v[118:121]
	v_mfma_f32_16x16x128_f8f6f4 v[114:117], v[26:33], v[204:211], v[114:117]
	v_mfma_f32_16x16x128_f8f6f4 v[122:125], v[26:33], v[196:203], v[122:125]
	v_mfma_f32_16x16x128_f8f6f4 v[126:129], v[18:25], v[196:203], v[126:129]
	s_setprio 0
	s_barrier
	s_mov_b32 m0, s89
	v_lshl_add_u64 v[174:175], v[174:175], 0, s[40:41]
	s_add_u32 s62, s82, 0x10080
	ds_read_b128 v[196:199], v189 offset:49152
	ds_read_b128 v[200:203], v189 offset:50176
	ds_read_b128 v[204:207], v189 offset:51200
	ds_read_b128 v[208:211], v189 offset:52224
	ds_read_b128 v[212:215], v189 offset:53248
	ds_read_b128 v[216:219], v189 offset:54272
	ds_read_b128 v[220:223], v189 offset:55296
	ds_read_b128 v[224:227], v189 offset:56320
	global_load_lds_dwordx4 v[174:175], off
	v_lshl_add_u64 v[174:175], v[176:177], 0, s[40:41]
	s_mov_b32 m0, s90
	s_addc_u32 s63, s83, 0
	global_load_lds_dwordx4 v[174:175], off
	v_lshl_add_u64 v[174:175], s[62:63], 0, v[162:163]
	s_mov_b32 m0, s93
	s_nop 0
	global_load_lds_dwordx4 v[174:175], off
	v_lshl_add_u64 v[174:175], s[62:63], 0, v[164:165]
	s_mov_b32 m0, s95
	s_nop 0
	global_load_lds_dwordx4 v[174:175], off
	v_lshl_add_u64 v[174:175], v[182:183], 0, s[40:41]
	s_mov_b32 m0, s91
	s_nop 0
	global_load_lds_dwordx4 v[174:175], off
	v_lshl_add_u64 v[174:175], v[184:185], 0, s[40:41]
	s_mov_b32 m0, s92
	s_nop 0
	global_load_lds_dwordx4 v[174:175], off
	s_waitcnt vmcnt(8)
	s_waitcnt lgkmcnt(0)
	s_barrier
	s_setprio 1
	s_waitcnt lgkmcnt(0)
	v_mfma_f32_16x16x128_f8f6f4 v[94:97], v[2:9], v[196:203], v[94:97]
	v_mfma_f32_16x16x128_f8f6f4 v[90:93], v[10:17], v[196:203], v[90:93]
	v_mfma_f32_16x16x128_f8f6f4 v[82:85], v[10:17], v[204:211], v[82:85]
	v_mfma_f32_16x16x128_f8f6f4 v[86:89], v[2:9], v[204:211], v[86:89]
	v_mfma_f32_16x16x128_f8f6f4 v[78:81], v[2:9], v[212:219], v[78:81]
	v_mfma_f32_16x16x128_f8f6f4 v[74:77], v[10:17], v[212:219], v[74:77]
	v_mfma_f32_16x16x128_f8f6f4 v[66:69], v[10:17], v[220:227], v[66:69]
	v_mfma_f32_16x16x128_f8f6f4 v[70:73], v[2:9], v[220:227], v[70:73]
	s_setprio 0
	s_setprio 1
	v_mfma_f32_16x16x128_f8f6f4 v[38:41], v[18:25], v[220:227], v[38:41]
	v_mfma_f32_16x16x128_f8f6f4 v[34:37], v[26:33], v[220:227], v[34:37]
	v_mfma_f32_16x16x128_f8f6f4 v[42:45], v[26:33], v[212:219], v[42:45]
	v_mfma_f32_16x16x128_f8f6f4 v[46:49], v[18:25], v[212:219], v[46:49]
	v_mfma_f32_16x16x128_f8f6f4 v[54:57], v[18:25], v[204:211], v[54:57]
	v_mfma_f32_16x16x128_f8f6f4 v[50:53], v[26:33], v[204:211], v[50:53]
	v_mfma_f32_16x16x128_f8f6f4 v[58:61], v[26:33], v[196:203], v[58:61]
	v_mfma_f32_16x16x128_f8f6f4 v[62:65], v[18:25], v[196:203], v[62:65]
	s_setprio 0
	s_barrier
	s_andn2_b64 vcc, exec, s[42:43]
	s_cbranch_vccnz .LBB0_618
	s_barrier

.LBB0_630:
	s_ashr_i32 s54, s48, 1
	s_ashr_i32 s51, s50, 31
	s_ashr_i32 s55, s54, 31
	s_lshl_b64 s[52:53], s[50:51], 19
	s_lshl_b64 s[54:55], s[54:55], 9
	s_waitcnt vmcnt(0)
	ds_read_b128 v[18:21], v181
	ds_read_b128 v[22:25], v181 offset:1024
	ds_read_b128 v[26:29], v181 offset:2048
	ds_read_b128 v[30:33], v181 offset:3072
	ds_read_b128 v[2:5], v181 offset:16384
	ds_read_b128 v[6:9], v181 offset:17408
	ds_read_b128 v[10:13], v181 offset:18432
	ds_read_b128 v[14:17], v181 offset:19456
	s_add_u32 s5, s26, s52
	s_addc_u32 s33, s27, s53
	s_add_u32 s52, s5, s54
	s_addc_u32 s53, s33, s55
	s_and_b64 s[54:55], s[2:3], exec
	s_cselect_b32 s81, s53, s75
	s_cselect_b32 s80, s52, s74
	s_ashr_i32 s49, s48, 31
	s_lshl_b64 s[54:55], s[48:49], 17
	v_readlane_b32 s5, v254, 9
	s_add_u32 s54, s5, s54
	v_readlane_b32 s5, v254, 10
	s_addc_u32 s55, s5, s55
	s_and_b64 s[62:63], s[2:3], exec
	s_cselect_b32 s79, s55, s77
	s_cselect_b32 s78, s54, s76
	s_add_u32 s62, s74, 0x40080
	s_addc_u32 s63, s75, 0
	s_add_i32 s33, s8, 0xc000
	v_lshl_add_u64 v[174:175], s[62:63], 0, v[166:167]
	s_mov_b32 m0, s33
	s_add_i32 s5, s8, 0xe000
	ds_read_b128 v[190:193], v187
	ds_read_b128 v[194:197], v187 offset:1024
	ds_read_b128 v[198:201], v187 offset:2048
	ds_read_b128 v[202:205], v187 offset:3072
	ds_read_b128 v[206:209], v187 offset:4096
	ds_read_b128 v[210:213], v187 offset:5120
	ds_read_b128 v[214:217], v187 offset:6144
	ds_read_b128 v[218:221], v187 offset:7168
	global_load_lds_dwordx4 v[174:175], off
	v_lshl_add_u64 v[174:175], s[62:63], 0, v[168:169]
	s_mov_b32 m0, s5
	s_nop 0
	global_load_lds_dwordx4 v[174:175], off
	s_waitcnt vmcnt(8)
	s_waitcnt lgkmcnt(0)
	s_barrier
	s_setprio 1
	s_waitcnt lgkmcnt(0)
	v_mfma_f32_16x16x128_f8f6f4 v[158:161], v[18:25], v[190:197], 0
	v_mfma_f32_16x16x128_f8f6f4 v[154:157], v[26:33], v[190:197], 0
	v_mfma_f32_16x16x128_f8f6f4 v[146:149], v[26:33], v[198:205], 0
	v_mfma_f32_16x16x128_f8f6f4 v[150:153], v[18:25], v[198:205], 0
	v_mfma_f32_16x16x128_f8f6f4 v[142:145], v[18:25], v[206:213], 0
	v_mfma_f32_16x16x128_f8f6f4 v[138:141], v[26:33], v[206:213], 0
	v_mfma_f32_16x16x128_f8f6f4 v[130:133], v[26:33], v[214:221], 0
	v_mfma_f32_16x16x128_f8f6f4 v[134:137], v[18:25], v[214:221], 0
	s_setprio 0
	s_setprio 1
	v_mfma_f32_16x16x128_f8f6f4 v[102:105], v[2:9], v[214:221], 0
	v_mfma_f32_16x16x128_f8f6f4 v[98:101], v[10:17], v[214:221], 0
	v_mfma_f32_16x16x128_f8f6f4 v[106:109], v[10:17], v[206:213], 0
	v_mfma_f32_16x16x128_f8f6f4 v[110:113], v[2:9], v[206:213], 0
	v_mfma_f32_16x16x128_f8f6f4 v[118:121], v[2:9], v[198:205], 0
	v_mfma_f32_16x16x128_f8f6f4 v[114:117], v[10:17], v[198:205], 0
	v_mfma_f32_16x16x128_f8f6f4 v[122:125], v[10:17], v[190:197], 0
	v_mfma_f32_16x16x128_f8f6f4 v[126:129], v[2:9], v[190:197], 0
	s_setprio 0
	s_barrier
	v_lshl_add_u64 v[174:175], s[76:77], 0, v[162:163]
	s_mov_b32 m0, s9
	v_lshl_add_u64 v[176:177], v[174:175], 0, s[44:45]
	ds_read_b128 v[190:193], v187 offset:16384
	ds_read_b128 v[194:197], v187 offset:17408
	ds_read_b128 v[198:201], v187 offset:18432
	ds_read_b128 v[202:205], v187 offset:19456
	ds_read_b128 v[206:209], v187 offset:20480
	ds_read_b128 v[210:213], v187 offset:21504
	ds_read_b128 v[214:217], v187 offset:22528
	ds_read_b128 v[218:221], v187 offset:23552
	global_load_lds_dwordx4 v[176:177], off
	v_lshl_add_u64 v[176:177], s[76:77], 0, v[164:165]
	s_add_u32 s62, s76, 0x10100
	v_lshl_add_u64 v[182:183], v[176:177], 0, s[44:45]
	s_mov_b32 m0, s61
	s_addc_u32 s63, s77, 0
	global_load_lds_dwordx4 v[182:183], off
	v_lshl_add_u64 v[182:183], s[62:63], 0, v[162:163]
	s_mov_b32 m0, s68
	s_nop 0
	global_load_lds_dwordx4 v[182:183], off
	v_lshl_add_u64 v[182:183], s[62:63], 0, v[164:165]
	s_mov_b32 m0, s69
	s_nop 0
	global_load_lds_dwordx4 v[182:183], off
	v_lshl_add_u64 v[182:183], s[74:75], 0, v[166:167]
	v_lshl_add_u64 v[184:185], v[182:183], 0, s[44:45]
	s_mov_b32 m0, s8
	s_nop 0
	global_load_lds_dwordx4 v[184:185], off
	v_lshl_add_u64 v[184:185], s[74:75], 0, v[168:169]
	v_lshl_add_u64 v[222:223], v[184:185], 0, s[44:45]
	s_mov_b32 m0, s71
	s_nop 0
	global_load_lds_dwordx4 v[222:223], off
	s_waitcnt vmcnt(8)
	s_waitcnt lgkmcnt(0)
	s_barrier
	s_setprio 1
	s_waitcnt lgkmcnt(0)
	v_mfma_f32_16x16x128_f8f6f4 v[94:97], v[18:25], v[190:197], 0
	v_mfma_f32_16x16x128_f8f6f4 v[90:93], v[26:33], v[190:197], 0
	v_mfma_f32_16x16x128_f8f6f4 v[82:85], v[26:33], v[198:205], 0
	v_mfma_f32_16x16x128_f8f6f4 v[86:89], v[18:25], v[198:205], 0
	v_mfma_f32_16x16x128_f8f6f4 v[78:81], v[18:25], v[206:213], 0
	v_mfma_f32_16x16x128_f8f6f4 v[74:77], v[26:33], v[206:213], 0
	v_mfma_f32_16x16x128_f8f6f4 v[66:69], v[26:33], v[214:221], 0
	v_mfma_f32_16x16x128_f8f6f4 v[70:73], v[18:25], v[214:221], 0
	s_setprio 0
	s_setprio 1
	v_mfma_f32_16x16x128_f8f6f4 v[38:41], v[2:9], v[214:221], 0
	v_mfma_f32_16x16x128_f8f6f4 v[34:37], v[10:17], v[214:221], 0
	v_mfma_f32_16x16x128_f8f6f4 v[42:45], v[10:17], v[206:213], 0
	v_mfma_f32_16x16x128_f8f6f4 v[46:49], v[2:9], v[206:213], 0
	v_mfma_f32_16x16x128_f8f6f4 v[54:57], v[2:9], v[198:205], 0
	v_mfma_f32_16x16x128_f8f6f4 v[50:53], v[10:17], v[198:205], 0
	v_mfma_f32_16x16x128_f8f6f4 v[58:61], v[10:17], v[190:197], 0
	v_mfma_f32_16x16x128_f8f6f4 v[62:65], v[2:9], v[190:197], 0
	s_setprio 0
	s_barrier
	ds_read_b128 v[2:5], v181 offset:32768
	ds_read_b128 v[6:9], v181 offset:33792
	ds_read_b128 v[10:13], v181 offset:34816
	ds_read_b128 v[14:17], v181 offset:35840
	ds_read_b128 v[18:21], v181 offset:49152
	ds_read_b128 v[22:25], v181 offset:50176
	ds_read_b128 v[26:29], v181 offset:51200
	ds_read_b128 v[30:33], v181 offset:52224
	s_add_u32 s62, s74, 0x40100
	s_addc_u32 s63, s75, 0
	s_mov_b32 m0, s73
	v_lshl_add_u64 v[222:223], s[62:63], 0, v[166:167]
	ds_read_b128 v[190:193], v187 offset:32768
	ds_read_b128 v[194:197], v187 offset:33792
	ds_read_b128 v[198:201], v187 offset:34816
	ds_read_b128 v[202:205], v187 offset:35840
	ds_read_b128 v[206:209], v187 offset:36864
	ds_read_b128 v[210:213], v187 offset:37888
	ds_read_b128 v[214:217], v187 offset:38912
	ds_read_b128 v[218:221], v187 offset:39936
	global_load_lds_dwordx4 v[222:223], off
	v_lshl_add_u64 v[222:223], s[62:63], 0, v[168:169]
	s_mov_b32 m0, s82
	s_nop 0
	global_load_lds_dwordx4 v[222:223], off
	s_waitcnt vmcnt(8)
	s_waitcnt lgkmcnt(0)
	s_barrier
	s_setprio 1
	s_waitcnt lgkmcnt(0)
	v_mfma_f32_16x16x128_f8f6f4 v[158:161], v[2:9], v[190:197], v[158:161]
	v_mfma_f32_16x16x128_f8f6f4 v[154:157], v[10:17], v[190:197], v[154:157]
	v_mfma_f32_16x16x128_f8f6f4 v[146:149], v[10:17], v[198:205], v[146:149]
	v_mfma_f32_16x16x128_f8f6f4 v[150:153], v[2:9], v[198:205], v[150:153]
	v_mfma_f32_16x16x128_f8f6f4 v[142:145], v[2:9], v[206:213], v[142:145]
	v_mfma_f32_16x16x128_f8f6f4 v[138:141], v[10:17], v[206:213], v[138:141]
	v_mfma_f32_16x16x128_f8f6f4 v[130:133], v[10:17], v[214:221], v[130:133]
	v_mfma_f32_16x16x128_f8f6f4 v[134:137], v[2:9], v[214:221], v[134:137]
	s_setprio 0
	s_setprio 1
	v_mfma_f32_16x16x128_f8f6f4 v[102:105], v[18:25], v[214:221], v[102:105]
	v_mfma_f32_16x16x128_f8f6f4 v[98:101], v[26:33], v[214:221], v[98:101]
	v_mfma_f32_16x16x128_f8f6f4 v[106:109], v[26:33], v[206:213], v[106:109]
	v_mfma_f32_16x16x128_f8f6f4 v[110:113], v[18:25], v[206:213], v[110:113]
	v_mfma_f32_16x16x128_f8f6f4 v[118:121], v[18:25], v[198:205], v[118:121]
	v_mfma_f32_16x16x128_f8f6f4 v[114:117], v[26:33], v[198:205], v[114:117]
	v_mfma_f32_16x16x128_f8f6f4 v[122:125], v[26:33], v[190:197], v[122:125]
	v_mfma_f32_16x16x128_f8f6f4 v[126:129], v[18:25], v[190:197], v[126:129]
	s_setprio 0
	s_barrier
	s_mov_b32 m0, s83
	v_lshl_add_u64 v[174:175], v[174:175], 0, s[46:47]
	s_add_u32 s62, s76, 0x10180
	ds_read_b128 v[190:193], v187 offset:49152
	ds_read_b128 v[194:197], v187 offset:50176
	ds_read_b128 v[198:201], v187 offset:51200
	ds_read_b128 v[202:205], v187 offset:52224
	ds_read_b128 v[206:209], v187 offset:53248
	ds_read_b128 v[210:213], v187 offset:54272
	ds_read_b128 v[214:217], v187 offset:55296
	ds_read_b128 v[218:221], v187 offset:56320
	global_load_lds_dwordx4 v[174:175], off
	v_lshl_add_u64 v[174:175], v[176:177], 0, s[46:47]
	s_mov_b32 m0, s84
	s_addc_u32 s63, s77, 0
	global_load_lds_dwordx4 v[174:175], off
	v_lshl_add_u64 v[174:175], s[62:63], 0, v[162:163]
	s_mov_b32 m0, s87
	s_nop 0
	global_load_lds_dwordx4 v[174:175], off
	v_lshl_add_u64 v[174:175], s[62:63], 0, v[164:165]
	s_mov_b32 m0, s88
	s_nop 0
	global_load_lds_dwordx4 v[174:175], off
	v_lshl_add_u64 v[174:175], v[182:183], 0, s[46:47]
	s_mov_b32 m0, s85
	s_nop 0
	global_load_lds_dwordx4 v[174:175], off
	v_lshl_add_u64 v[174:175], v[184:185], 0, s[46:47]
	s_mov_b32 m0, s86
	s_nop 0
	global_load_lds_dwordx4 v[174:175], off
	s_waitcnt vmcnt(8)
	s_waitcnt lgkmcnt(0)
	s_barrier
	s_setprio 1
	s_waitcnt lgkmcnt(0)
	v_mfma_f32_16x16x128_f8f6f4 v[94:97], v[2:9], v[190:197], v[94:97]
	v_mfma_f32_16x16x128_f8f6f4 v[90:93], v[10:17], v[190:197], v[90:93]
	v_mfma_f32_16x16x128_f8f6f4 v[82:85], v[10:17], v[198:205], v[82:85]
	v_mfma_f32_16x16x128_f8f6f4 v[86:89], v[2:9], v[198:205], v[86:89]
	v_mfma_f32_16x16x128_f8f6f4 v[78:81], v[2:9], v[206:213], v[78:81]
	v_mfma_f32_16x16x128_f8f6f4 v[74:77], v[10:17], v[206:213], v[74:77]
	v_mfma_f32_16x16x128_f8f6f4 v[66:69], v[10:17], v[214:221], v[66:69]
	v_mfma_f32_16x16x128_f8f6f4 v[70:73], v[2:9], v[214:221], v[70:73]
	s_setprio 0
	s_setprio 1
	v_mfma_f32_16x16x128_f8f6f4 v[38:41], v[18:25], v[214:221], v[38:41]
	v_mfma_f32_16x16x128_f8f6f4 v[34:37], v[26:33], v[214:221], v[34:37]
	v_mfma_f32_16x16x128_f8f6f4 v[42:45], v[26:33], v[206:213], v[42:45]
	v_mfma_f32_16x16x128_f8f6f4 v[46:49], v[18:25], v[206:213], v[46:49]
	v_mfma_f32_16x16x128_f8f6f4 v[54:57], v[18:25], v[198:205], v[54:57]
	v_mfma_f32_16x16x128_f8f6f4 v[50:53], v[26:33], v[198:205], v[50:53]
	v_mfma_f32_16x16x128_f8f6f4 v[58:61], v[26:33], v[190:197], v[58:61]
	v_mfma_f32_16x16x128_f8f6f4 v[62:65], v[18:25], v[190:197], v[62:65]
	s_setprio 0
	s_barrier
	ds_read_b128 v[2:5], v181
	ds_read_b128 v[6:9], v181 offset:1024
	ds_read_b128 v[10:13], v181 offset:2048
	ds_read_b128 v[14:17], v181 offset:3072
	ds_read_b128 v[18:21], v181 offset:16384
	ds_read_b128 v[22:25], v181 offset:17408
	ds_read_b128 v[26:29], v181 offset:18432
	ds_read_b128 v[30:33], v181 offset:19456
	s_add_u32 s62, s74, 0x40180
	s_addc_u32 s63, s75, 0
	s_mov_b32 m0, s33
	v_lshl_add_u64 v[174:175], s[62:63], 0, v[166:167]
	ds_read_b128 v[190:193], v187
	ds_read_b128 v[194:197], v187 offset:1024
	ds_read_b128 v[198:201], v187 offset:2048
	ds_read_b128 v[202:205], v187 offset:3072
	ds_read_b128 v[206:209], v187 offset:4096
	ds_read_b128 v[210:213], v187 offset:5120
	ds_read_b128 v[214:217], v187 offset:6144
	ds_read_b128 v[218:221], v187 offset:7168
	global_load_lds_dwordx4 v[174:175], off
	v_lshl_add_u64 v[174:175], s[62:63], 0, v[168:169]
	s_mov_b32 m0, s5
	s_nop 0
	global_load_lds_dwordx4 v[174:175], off
	s_waitcnt vmcnt(8)
	s_waitcnt lgkmcnt(0)
	s_barrier
	s_setprio 1
	s_waitcnt lgkmcnt(0)
	v_mfma_f32_16x16x128_f8f6f4 v[158:161], v[2:9], v[190:197], v[158:161]
	v_mfma_f32_16x16x128_f8f6f4 v[154:157], v[10:17], v[190:197], v[154:157]
	v_mfma_f32_16x16x128_f8f6f4 v[146:149], v[10:17], v[198:205], v[146:149]
	v_mfma_f32_16x16x128_f8f6f4 v[150:153], v[2:9], v[198:205], v[150:153]
	v_mfma_f32_16x16x128_f8f6f4 v[142:145], v[2:9], v[206:213], v[142:145]
	v_mfma_f32_16x16x128_f8f6f4 v[138:141], v[10:17], v[206:213], v[138:141]
	v_mfma_f32_16x16x128_f8f6f4 v[130:133], v[10:17], v[214:221], v[130:133]
	v_mfma_f32_16x16x128_f8f6f4 v[134:137], v[2:9], v[214:221], v[134:137]
	s_setprio 0
	s_setprio 1
	v_mfma_f32_16x16x128_f8f6f4 v[102:105], v[18:25], v[214:221], v[102:105]
	v_mfma_f32_16x16x128_f8f6f4 v[98:101], v[26:33], v[214:221], v[98:101]
	v_mfma_f32_16x16x128_f8f6f4 v[106:109], v[26:33], v[206:213], v[106:109]
	v_mfma_f32_16x16x128_f8f6f4 v[110:113], v[18:25], v[206:213], v[110:113]
	v_mfma_f32_16x16x128_f8f6f4 v[118:121], v[18:25], v[198:205], v[118:121]
	v_mfma_f32_16x16x128_f8f6f4 v[114:117], v[26:33], v[198:205], v[114:117]
	v_mfma_f32_16x16x128_f8f6f4 v[122:125], v[26:33], v[190:197], v[122:125]
	v_mfma_f32_16x16x128_f8f6f4 v[126:129], v[18:25], v[190:197], v[126:129]
	s_setprio 0
	s_barrier
	s_mov_b32 m0, s9
	v_lshl_add_u64 v[174:175], s[78:79], 0, v[162:163]
	s_add_u32 s62, s78, 0x10000
	ds_read_b128 v[190:193], v187 offset:16384
	ds_read_b128 v[194:197], v187 offset:17408
	ds_read_b128 v[198:201], v187 offset:18432
	ds_read_b128 v[202:205], v187 offset:19456
	ds_read_b128 v[206:209], v187 offset:20480
	ds_read_b128 v[210:213], v187 offset:21504
	ds_read_b128 v[214:217], v187 offset:22528
	ds_read_b128 v[218:221], v187 offset:23552
	global_load_lds_dwordx4 v[174:175], off
	v_lshl_add_u64 v[176:177], s[78:79], 0, v[164:165]
	s_mov_b32 m0, s61
	s_addc_u32 s63, s79, 0
	global_load_lds_dwordx4 v[176:177], off
	v_lshl_add_u64 v[182:183], s[62:63], 0, v[162:163]
	s_mov_b32 m0, s68
	v_lshl_add_u64 v[184:185], s[80:81], 0, v[168:169]
	global_load_lds_dwordx4 v[182:183], off
	v_lshl_add_u64 v[182:183], s[62:63], 0, v[164:165]
	s_mov_b32 m0, s69
	s_nop 0
	global_load_lds_dwordx4 v[182:183], off
	v_lshl_add_u64 v[182:183], s[80:81], 0, v[166:167]
	s_mov_b32 m0, s8
	s_nop 0
	global_load_lds_dwordx4 v[182:183], off
	s_mov_b32 m0, s71
	s_nop 0
	global_load_lds_dwordx4 v[184:185], off
	s_waitcnt vmcnt(8)
	s_waitcnt lgkmcnt(0)
	s_barrier
	s_setprio 1
	s_waitcnt lgkmcnt(0)
	v_mfma_f32_16x16x128_f8f6f4 v[94:97], v[2:9], v[190:197], v[94:97]
	v_mfma_f32_16x16x128_f8f6f4 v[90:93], v[10:17], v[190:197], v[90:93]
	v_mfma_f32_16x16x128_f8f6f4 v[82:85], v[10:17], v[198:205], v[82:85]
	v_mfma_f32_16x16x128_f8f6f4 v[86:89], v[2:9], v[198:205], v[86:89]
	v_mfma_f32_16x16x128_f8f6f4 v[78:81], v[2:9], v[206:213], v[78:81]
	v_mfma_f32_16x16x128_f8f6f4 v[74:77], v[10:17], v[206:213], v[74:77]
	v_mfma_f32_16x16x128_f8f6f4 v[66:69], v[10:17], v[214:221], v[66:69]
	v_mfma_f32_16x16x128_f8f6f4 v[70:73], v[2:9], v[214:221], v[70:73]
	s_setprio 0
	s_setprio 1
	v_mfma_f32_16x16x128_f8f6f4 v[38:41], v[18:25], v[214:221], v[38:41]
	v_mfma_f32_16x16x128_f8f6f4 v[34:37], v[26:33], v[214:221], v[34:37]
	v_mfma_f32_16x16x128_f8f6f4 v[42:45], v[26:33], v[206:213], v[42:45]
	v_mfma_f32_16x16x128_f8f6f4 v[46:49], v[18:25], v[206:213], v[46:49]
	v_mfma_f32_16x16x128_f8f6f4 v[54:57], v[18:25], v[198:205], v[54:57]
	v_mfma_f32_16x16x128_f8f6f4 v[50:53], v[26:33], v[198:205], v[50:53]
	v_mfma_f32_16x16x128_f8f6f4 v[58:61], v[26:33], v[190:197], v[58:61]
	v_mfma_f32_16x16x128_f8f6f4 v[62:65], v[18:25], v[190:197], v[62:65]
	s_setprio 0
	s_barrier
	ds_read_b128 v[2:5], v181 offset:32768
	ds_read_b128 v[6:9], v181 offset:33792
	ds_read_b128 v[10:13], v181 offset:34816
	ds_read_b128 v[14:17], v181 offset:35840
	ds_read_b128 v[18:21], v181 offset:49152
	ds_read_b128 v[22:25], v181 offset:50176
	ds_read_b128 v[26:29], v181 offset:51200
	ds_read_b128 v[30:33], v181 offset:52224
	s_add_u32 s62, s80, 0x40000
	s_addc_u32 s63, s81, 0
	s_mov_b32 m0, s73
	v_lshl_add_u64 v[222:223], s[62:63], 0, v[166:167]
	ds_read_b128 v[190:193], v187 offset:32768
	ds_read_b128 v[194:197], v187 offset:33792
	ds_read_b128 v[198:201], v187 offset:34816
	ds_read_b128 v[202:205], v187 offset:35840
	ds_read_b128 v[206:209], v187 offset:36864
	ds_read_b128 v[210:213], v187 offset:37888
	ds_read_b128 v[214:217], v187 offset:38912
	ds_read_b128 v[218:221], v187 offset:39936
	global_load_lds_dwordx4 v[222:223], off
	v_lshl_add_u64 v[222:223], s[62:63], 0, v[168:169]
	s_mov_b32 m0, s82
	s_nop 0
	global_load_lds_dwordx4 v[222:223], off
	s_waitcnt vmcnt(8)
	s_waitcnt lgkmcnt(0)
	s_barrier
	s_setprio 1
	s_waitcnt lgkmcnt(0)
	v_mfma_f32_16x16x128_f8f6f4 v[158:161], v[2:9], v[190:197], v[158:161]
	v_mfma_f32_16x16x128_f8f6f4 v[154:157], v[10:17], v[190:197], v[154:157]
	v_mfma_f32_16x16x128_f8f6f4 v[146:149], v[10:17], v[198:205], v[146:149]
	v_mfma_f32_16x16x128_f8f6f4 v[150:153], v[2:9], v[198:205], v[150:153]
	v_mfma_f32_16x16x128_f8f6f4 v[142:145], v[2:9], v[206:213], v[142:145]
	v_mfma_f32_16x16x128_f8f6f4 v[138:141], v[10:17], v[206:213], v[138:141]
	v_mfma_f32_16x16x128_f8f6f4 v[130:133], v[10:17], v[214:221], v[130:133]
	v_mfma_f32_16x16x128_f8f6f4 v[134:137], v[2:9], v[214:221], v[134:137]
	s_setprio 0
	s_setprio 1
	v_mfma_f32_16x16x128_f8f6f4 v[102:105], v[18:25], v[214:221], v[102:105]
	v_mfma_f32_16x16x128_f8f6f4 v[98:101], v[26:33], v[214:221], v[98:101]
	v_mfma_f32_16x16x128_f8f6f4 v[106:109], v[26:33], v[206:213], v[106:109]
	v_mfma_f32_16x16x128_f8f6f4 v[110:113], v[18:25], v[206:213], v[110:113]
	v_mfma_f32_16x16x128_f8f6f4 v[118:121], v[18:25], v[198:205], v[118:121]
	v_mfma_f32_16x16x128_f8f6f4 v[114:117], v[26:33], v[198:205], v[114:117]
	v_mfma_f32_16x16x128_f8f6f4 v[122:125], v[26:33], v[190:197], v[122:125]
	v_mfma_f32_16x16x128_f8f6f4 v[126:129], v[18:25], v[190:197], v[126:129]
	s_setprio 0
	s_barrier
	s_mov_b32 m0, s83
	v_lshl_add_u64 v[174:175], v[174:175], 0, s[38:39]
	s_add_u32 s62, s78, 0x10080
	ds_read_b128 v[190:193], v187 offset:49152
	ds_read_b128 v[194:197], v187 offset:50176
	ds_read_b128 v[198:201], v187 offset:51200
	ds_read_b128 v[202:205], v187 offset:52224
	ds_read_b128 v[206:209], v187 offset:53248
	ds_read_b128 v[210:213], v187 offset:54272
	ds_read_b128 v[214:217], v187 offset:55296
	ds_read_b128 v[218:221], v187 offset:56320
	global_load_lds_dwordx4 v[174:175], off
	v_lshl_add_u64 v[174:175], v[176:177], 0, s[38:39]
	s_mov_b32 m0, s84
	s_addc_u32 s63, s79, 0
	global_load_lds_dwordx4 v[174:175], off
	v_lshl_add_u64 v[174:175], s[62:63], 0, v[162:163]
	s_mov_b32 m0, s87
	s_nop 0
	global_load_lds_dwordx4 v[174:175], off
	v_lshl_add_u64 v[174:175], s[62:63], 0, v[164:165]
	s_mov_b32 m0, s88
	s_nop 0
	global_load_lds_dwordx4 v[174:175], off
	v_lshl_add_u64 v[174:175], v[182:183], 0, s[38:39]
	s_mov_b32 m0, s85
	s_nop 0
	global_load_lds_dwordx4 v[174:175], off
	v_lshl_add_u64 v[174:175], v[184:185], 0, s[38:39]
	s_mov_b32 m0, s86
	s_nop 0
	global_load_lds_dwordx4 v[174:175], off
	s_waitcnt vmcnt(8)
	s_waitcnt lgkmcnt(0)
	s_barrier
	s_setprio 1
	s_waitcnt lgkmcnt(0)
	v_mfma_f32_16x16x128_f8f6f4 v[94:97], v[2:9], v[190:197], v[94:97]
	v_mfma_f32_16x16x128_f8f6f4 v[90:93], v[10:17], v[190:197], v[90:93]
	v_mfma_f32_16x16x128_f8f6f4 v[82:85], v[10:17], v[198:205], v[82:85]
	v_mfma_f32_16x16x128_f8f6f4 v[86:89], v[2:9], v[198:205], v[86:89]
	v_mfma_f32_16x16x128_f8f6f4 v[78:81], v[2:9], v[206:213], v[78:81]
	v_mfma_f32_16x16x128_f8f6f4 v[74:77], v[10:17], v[206:213], v[74:77]
	v_mfma_f32_16x16x128_f8f6f4 v[66:69], v[10:17], v[214:221], v[66:69]
	v_mfma_f32_16x16x128_f8f6f4 v[70:73], v[2:9], v[214:221], v[70:73]
	s_setprio 0
	s_setprio 1
	v_mfma_f32_16x16x128_f8f6f4 v[38:41], v[18:25], v[214:221], v[38:41]
	v_mfma_f32_16x16x128_f8f6f4 v[34:37], v[26:33], v[214:221], v[34:37]
	v_mfma_f32_16x16x128_f8f6f4 v[42:45], v[26:33], v[206:213], v[42:45]
	v_mfma_f32_16x16x128_f8f6f4 v[46:49], v[18:25], v[206:213], v[46:49]
	v_mfma_f32_16x16x128_f8f6f4 v[54:57], v[18:25], v[198:205], v[54:57]
	v_mfma_f32_16x16x128_f8f6f4 v[50:53], v[26:33], v[198:205], v[50:53]
	v_mfma_f32_16x16x128_f8f6f4 v[58:61], v[26:33], v[190:197], v[58:61]
	v_mfma_f32_16x16x128_f8f6f4 v[62:65], v[18:25], v[190:197], v[62:65]
	s_setprio 0
	s_barrier
	s_andn2_b64 vcc, exec, s[40:41]
	s_cbranch_vccnz .LBB0_632
	s_barrier

.LBB0_791:
	ds_read_b128 v[2:5], v189
	ds_read_b128 v[6:9], v189 offset:1024
	ds_read_b128 v[192:195], v189 offset:2048
	ds_read_b128 v[196:199], v189 offset:3072
	ds_read_b128 v[200:203], v189 offset:16384
	ds_read_b128 v[204:207], v189 offset:17408
	ds_read_b128 v[208:211], v189 offset:18432
	ds_read_b128 v[212:215], v189 offset:19456
	s_add_u32 s37, s46, 0x100
	s_addc_u32 s39, s47, 0
	s_and_b64 s[50:51], s[48:49], exec
	s_cselect_b32 s51, s1, s39
	s_cselect_b32 s50, s0, s37
	s_add_u32 s37, s44, 0x100
	s_addc_u32 s39, s45, 0
	s_and_b64 s[48:49], s[48:49], exec
	s_cselect_b32 s49, s5, s39
	s_cselect_b32 s48, s4, s37
	s_add_u32 s88, s46, 0x80080
	s_addc_u32 s89, s47, 0
	s_add_i32 s37, s8, 0xc000
	v_lshl_add_u64 v[174:175], s[88:89], 0, v[154:155]
	s_mov_b32 m0, s37
	s_add_i32 s39, s8, 0xe000
	ds_read_b128 v[216:219], v190
	ds_read_b128 v[220:223], v190 offset:1024
	ds_read_b128 v[224:227], v190 offset:2048
	ds_read_b128 v[228:231], v190 offset:3072
	ds_read_b128 v[242:245], v190 offset:4096
	ds_read_b128 v[246:249], v190 offset:5120
	ds_read_b128 v[232:235], v190 offset:6144
	ds_read_b128 v[236:239], v190 offset:7168
	global_load_lds_dwordx4 v[174:175], off
	v_lshl_add_u64 v[174:175], s[88:89], 0, v[158:159]
	s_mov_b32 m0, s39
	s_nop 0
	global_load_lds_dwordx4 v[174:175], off
	s_waitcnt vmcnt(8)
	s_waitcnt lgkmcnt(0)
	s_barrier
	s_setprio 1
	s_waitcnt lgkmcnt(0)
	v_mfma_f32_16x16x128_f8f6f4 v[134:137], v[2:9], v[216:223], 0
	v_mfma_f32_16x16x128_f8f6f4 v[130:133], v[192:199], v[216:223], 0
	v_mfma_f32_16x16x128_f8f6f4 v[122:125], v[192:199], v[224:231], 0
	v_mfma_f32_16x16x128_f8f6f4 v[126:129], v[2:9], v[224:231], 0
	v_mfma_f32_16x16x128_f8f6f4 v[118:121], v[2:9], v[242:249], 0
	v_mfma_f32_16x16x128_f8f6f4 v[114:117], v[192:199], v[242:249], 0
	v_mfma_f32_16x16x128_f8f6f4 v[106:109], v[192:199], v[232:239], 0
	v_mfma_f32_16x16x128_f8f6f4 v[110:113], v[2:9], v[232:239], 0
	s_setprio 0
	s_setprio 1
	v_mfma_f32_16x16x128_f8f6f4 v[78:81], v[200:207], v[232:239], 0
	v_mfma_f32_16x16x128_f8f6f4 v[74:77], v[208:215], v[232:239], 0
	v_mfma_f32_16x16x128_f8f6f4 v[82:85], v[208:215], v[242:249], 0
	v_mfma_f32_16x16x128_f8f6f4 v[86:89], v[200:207], v[242:249], 0
	v_mfma_f32_16x16x128_f8f6f4 v[94:97], v[200:207], v[224:231], 0
	v_mfma_f32_16x16x128_f8f6f4 v[90:93], v[208:215], v[224:231], 0
	v_mfma_f32_16x16x128_f8f6f4 v[98:101], v[208:215], v[216:223], 0
	v_mfma_f32_16x16x128_f8f6f4 v[102:105], v[200:207], v[216:223], 0
	s_setprio 0
	s_barrier
	s_mov_b32 m0, s9
	v_lshl_add_u64 v[174:175], s[48:49], 0, v[156:157]
	s_add_u32 s88, s48, 0x80000
	ds_read_b128 v[216:219], v190 offset:16384
	ds_read_b128 v[220:223], v190 offset:17408
	ds_read_b128 v[224:227], v190 offset:18432
	ds_read_b128 v[228:231], v190 offset:19456
	ds_read_b128 v[232:235], v190 offset:20480
	ds_read_b128 v[236:239], v190 offset:21504
	ds_read_b128 v[242:245], v190 offset:22528
	ds_read_b128 v[246:249], v190 offset:23552
	global_load_lds_dwordx4 v[174:175], off
	v_lshl_add_u64 v[176:177], s[48:49], 0, v[160:161]
	s_mov_b32 m0, s27
	s_addc_u32 s89, s49, 0
	global_load_lds_dwordx4 v[176:177], off
	v_lshl_add_u64 v[182:183], s[88:89], 0, v[156:157]
	s_mov_b32 m0, s33
	v_lshl_add_u64 v[184:185], s[50:51], 0, v[158:159]
	global_load_lds_dwordx4 v[182:183], off
	v_lshl_add_u64 v[182:183], s[88:89], 0, v[160:161]
	s_mov_b32 m0, s35
	s_nop 0
	global_load_lds_dwordx4 v[182:183], off
	v_lshl_add_u64 v[182:183], s[50:51], 0, v[154:155]
	s_mov_b32 m0, s8
	s_nop 0
	global_load_lds_dwordx4 v[182:183], off
	s_mov_b32 m0, s43
	s_nop 0
	global_load_lds_dwordx4 v[184:185], off
	s_waitcnt vmcnt(8)
	s_waitcnt lgkmcnt(0)
	s_barrier
	s_setprio 1
	s_waitcnt lgkmcnt(0)
	v_mfma_f32_16x16x128_f8f6f4 v[70:73], v[2:9], v[216:223], 0
	v_mfma_f32_16x16x128_f8f6f4 v[66:69], v[192:199], v[216:223], 0
	v_mfma_f32_16x16x128_f8f6f4 v[58:61], v[192:199], v[224:231], 0
	v_mfma_f32_16x16x128_f8f6f4 v[62:65], v[2:9], v[224:231], 0
	v_mfma_f32_16x16x128_f8f6f4 v[54:57], v[2:9], v[232:239], 0
	v_mfma_f32_16x16x128_f8f6f4 v[50:53], v[192:199], v[232:239], 0
	v_mfma_f32_16x16x128_f8f6f4 v[42:45], v[192:199], v[242:249], 0
	v_mfma_f32_16x16x128_f8f6f4 v[46:49], v[2:9], v[242:249], 0
	s_setprio 0
	s_setprio 1
	v_mfma_f32_16x16x128_f8f6f4 v[14:17], v[200:207], v[242:249], 0
	v_mfma_f32_16x16x128_f8f6f4 v[10:13], v[208:215], v[242:249], 0
	v_mfma_f32_16x16x128_f8f6f4 v[18:21], v[208:215], v[232:239], 0
	v_mfma_f32_16x16x128_f8f6f4 v[22:25], v[200:207], v[232:239], 0
	v_mfma_f32_16x16x128_f8f6f4 v[30:33], v[200:207], v[224:231], 0
	v_mfma_f32_16x16x128_f8f6f4 v[26:29], v[208:215], v[224:231], 0
	v_mfma_f32_16x16x128_f8f6f4 v[34:37], v[208:215], v[216:223], 0
	v_mfma_f32_16x16x128_f8f6f4 v[38:41], v[200:207], v[216:223], 0
	s_setprio 0
	s_barrier
	ds_read_b128 v[2:5], v189 offset:32768
	ds_read_b128 v[6:9], v189 offset:33792
	ds_read_b128 v[192:195], v189 offset:34816
	ds_read_b128 v[196:199], v189 offset:35840
	ds_read_b128 v[200:203], v189 offset:49152
	ds_read_b128 v[204:207], v189 offset:50176
	ds_read_b128 v[208:211], v189 offset:51200
	ds_read_b128 v[212:215], v189 offset:52224
	s_add_u32 s50, s50, 0x80000
	s_addc_u32 s51, s51, 0
	s_mov_b32 m0, s52
	v_lshl_add_u64 v[186:187], s[50:51], 0, v[154:155]
	ds_read_b128 v[216:219], v190 offset:32768
	ds_read_b128 v[220:223], v190 offset:33792
	ds_read_b128 v[224:227], v190 offset:34816
	ds_read_b128 v[228:231], v190 offset:35840
	ds_read_b128 v[232:235], v190 offset:36864
	ds_read_b128 v[236:239], v190 offset:37888
	ds_read_b128 v[242:245], v190 offset:38912
	ds_read_b128 v[246:249], v190 offset:39936
	global_load_lds_dwordx4 v[186:187], off
	v_lshl_add_u64 v[186:187], s[50:51], 0, v[158:159]
	s_mov_b32 m0, s53
	s_nop 0
	global_load_lds_dwordx4 v[186:187], off
	s_waitcnt vmcnt(8)
	s_waitcnt lgkmcnt(0)
	s_barrier
	s_setprio 1
	s_waitcnt lgkmcnt(0)
	v_mfma_f32_16x16x128_f8f6f4 v[134:137], v[2:9], v[216:223], v[134:137]
	v_mfma_f32_16x16x128_f8f6f4 v[130:133], v[192:199], v[216:223], v[130:133]
	v_mfma_f32_16x16x128_f8f6f4 v[122:125], v[192:199], v[224:231], v[122:125]
	v_mfma_f32_16x16x128_f8f6f4 v[126:129], v[2:9], v[224:231], v[126:129]
	v_mfma_f32_16x16x128_f8f6f4 v[118:121], v[2:9], v[232:239], v[118:121]
	v_mfma_f32_16x16x128_f8f6f4 v[114:117], v[192:199], v[232:239], v[114:117]
	v_mfma_f32_16x16x128_f8f6f4 v[106:109], v[192:199], v[242:249], v[106:109]
	v_mfma_f32_16x16x128_f8f6f4 v[110:113], v[2:9], v[242:249], v[110:113]
	s_setprio 0
	s_setprio 1
	v_mfma_f32_16x16x128_f8f6f4 v[78:81], v[200:207], v[242:249], v[78:81]
	v_mfma_f32_16x16x128_f8f6f4 v[74:77], v[208:215], v[242:249], v[74:77]
	v_mfma_f32_16x16x128_f8f6f4 v[82:85], v[208:215], v[232:239], v[82:85]
	v_mfma_f32_16x16x128_f8f6f4 v[86:89], v[200:207], v[232:239], v[86:89]
	v_mfma_f32_16x16x128_f8f6f4 v[94:97], v[200:207], v[224:231], v[94:97]
	v_mfma_f32_16x16x128_f8f6f4 v[90:93], v[208:215], v[224:231], v[90:93]
	v_mfma_f32_16x16x128_f8f6f4 v[98:101], v[208:215], v[216:223], v[98:101]
	v_mfma_f32_16x16x128_f8f6f4 v[102:105], v[200:207], v[216:223], v[102:105]
	s_setprio 0
	s_barrier
	s_mov_b32 m0, s70
	v_lshl_add_u64 v[174:175], v[174:175], 0, s[18:19]
	s_add_u32 s48, s48, 0x80080
	ds_read_b128 v[216:219], v190 offset:49152
	ds_read_b128 v[220:223], v190 offset:50176
	ds_read_b128 v[224:227], v190 offset:51200
	ds_read_b128 v[228:231], v190 offset:52224
	ds_read_b128 v[232:235], v190 offset:53248
	ds_read_b128 v[236:239], v190 offset:54272
	ds_read_b128 v[242:245], v190 offset:55296
	ds_read_b128 v[246:249], v190 offset:56320
	global_load_lds_dwordx4 v[174:175], off
	v_lshl_add_u64 v[174:175], v[176:177], 0, s[18:19]
	s_mov_b32 m0, s71
	s_addc_u32 s49, s49, 0
	global_load_lds_dwordx4 v[174:175], off
	v_lshl_add_u64 v[174:175], s[48:49], 0, v[156:157]
	s_mov_b32 m0, s74
	s_nop 0
	global_load_lds_dwordx4 v[174:175], off
	v_lshl_add_u64 v[174:175], s[48:49], 0, v[160:161]
	s_mov_b32 m0, s75
	s_nop 0
	global_load_lds_dwordx4 v[174:175], off
	v_lshl_add_u64 v[174:175], v[182:183], 0, s[18:19]
	s_mov_b32 m0, s72
	s_nop 0
	global_load_lds_dwordx4 v[174:175], off
	v_lshl_add_u64 v[174:175], v[184:185], 0, s[18:19]
	s_mov_b32 m0, s73
	s_nop 0
	global_load_lds_dwordx4 v[174:175], off
	s_waitcnt vmcnt(8)
	s_waitcnt lgkmcnt(0)
	s_barrier
	s_setprio 1
	s_waitcnt lgkmcnt(0)
	v_mfma_f32_16x16x128_f8f6f4 v[70:73], v[2:9], v[216:223], v[70:73]
	v_mfma_f32_16x16x128_f8f6f4 v[66:69], v[192:199], v[216:223], v[66:69]
	v_mfma_f32_16x16x128_f8f6f4 v[58:61], v[192:199], v[224:231], v[58:61]
	v_mfma_f32_16x16x128_f8f6f4 v[62:65], v[2:9], v[224:231], v[62:65]
	v_mfma_f32_16x16x128_f8f6f4 v[54:57], v[2:9], v[232:239], v[54:57]
	v_mfma_f32_16x16x128_f8f6f4 v[50:53], v[192:199], v[232:239], v[50:53]
	v_mfma_f32_16x16x128_f8f6f4 v[42:45], v[192:199], v[242:249], v[42:45]
	v_mfma_f32_16x16x128_f8f6f4 v[46:49], v[2:9], v[242:249], v[46:49]
	s_setprio 0
	s_setprio 1
	v_mfma_f32_16x16x128_f8f6f4 v[14:17], v[200:207], v[242:249], v[14:17]
	v_mfma_f32_16x16x128_f8f6f4 v[10:13], v[208:215], v[242:249], v[10:13]
	v_mfma_f32_16x16x128_f8f6f4 v[18:21], v[208:215], v[232:239], v[18:21]
	v_mfma_f32_16x16x128_f8f6f4 v[22:25], v[200:207], v[232:239], v[22:25]
	v_mfma_f32_16x16x128_f8f6f4 v[30:33], v[200:207], v[224:231], v[30:33]
	v_mfma_f32_16x16x128_f8f6f4 v[26:29], v[208:215], v[224:231], v[26:29]
	v_mfma_f32_16x16x128_f8f6f4 v[34:37], v[208:215], v[216:223], v[34:37]
	v_mfma_f32_16x16x128_f8f6f4 v[38:41], v[200:207], v[216:223], v[38:41]
	s_setprio 0
	s_barrier
	s_cmp_lt_u32 s86, 3
	s_cbranch_scc1 .LBB0_796
	s_add_u32 s48, s55, s62
	s_addc_u32 s49, s61, s41
	s_add_u32 s46, s46, 0x80180
	s_addc_u32 s47, s47, 0
	s_add_u32 s41, s44, 0x200
	v_lshl_add_u64 v[174:175], v[172:173], 2, s[48:49]
	s_addc_u32 s50, s45, 0
	s_mov_b32 s51, 4
	s_cmp_eq_u32 s86, s51
	s_cselect_b64 s[44:45], -1, 0
	s_cmp_lg_u32 s86, s51
	s_cbranch_scc1 .LBB0_794

.LBB0_794:
	ds_read_b128 v[2:5], v189
	ds_read_b128 v[6:9], v189 offset:1024
	ds_read_b128 v[192:195], v189 offset:2048
	ds_read_b128 v[196:199], v189 offset:3072
	ds_read_b128 v[200:203], v189 offset:16384
	ds_read_b128 v[204:207], v189 offset:17408
	ds_read_b128 v[208:211], v189 offset:18432
	ds_read_b128 v[212:215], v189 offset:19456
	s_add_u32 s48, s46, 0xfff80080
	s_addc_u32 s49, s47, -1
	s_and_b64 s[44:45], s[44:45], exec
	s_cselect_b32 s44, s4, s41
	s_cselect_b32 s49, s1, s49
	s_cselect_b32 s48, s0, s48
	s_cselect_b32 s45, s5, s50
	s_mov_b32 m0, s37
	v_lshl_add_u64 v[176:177], s[46:47], 0, v[162:163]
	ds_read_b128 v[216:219], v190
	ds_read_b128 v[220:223], v190 offset:1024
	ds_read_b128 v[224:227], v190 offset:2048
	ds_read_b128 v[228:231], v190 offset:3072
	ds_read_b128 v[232:235], v190 offset:4096
	ds_read_b128 v[236:239], v190 offset:5120
	ds_read_b128 v[242:245], v190 offset:6144
	ds_read_b128 v[246:249], v190 offset:7168
	global_load_lds_dwordx4 v[176:177], off
	v_lshl_add_u64 v[176:177], s[46:47], 0, v[164:165]
	s_mov_b32 m0, s39
	s_nop 0
	global_load_lds_dwordx4 v[176:177], off
	s_waitcnt vmcnt(8)
	s_waitcnt lgkmcnt(0)
	s_barrier
	s_setprio 1
	s_waitcnt lgkmcnt(0)
	v_mfma_f32_16x16x128_f8f6f4 v[134:137], v[2:9], v[216:223], v[134:137]
	v_mfma_f32_16x16x128_f8f6f4 v[130:133], v[192:199], v[216:223], v[130:133]
	v_mfma_f32_16x16x128_f8f6f4 v[122:125], v[192:199], v[224:231], v[122:125]
	v_mfma_f32_16x16x128_f8f6f4 v[126:129], v[2:9], v[224:231], v[126:129]
	v_mfma_f32_16x16x128_f8f6f4 v[118:121], v[2:9], v[232:239], v[118:121]
	v_mfma_f32_16x16x128_f8f6f4 v[114:117], v[192:199], v[232:239], v[114:117]
	v_mfma_f32_16x16x128_f8f6f4 v[106:109], v[192:199], v[242:249], v[106:109]
	v_mfma_f32_16x16x128_f8f6f4 v[110:113], v[2:9], v[242:249], v[110:113]
	s_setprio 0
	s_setprio 1
	v_mfma_f32_16x16x128_f8f6f4 v[78:81], v[200:207], v[242:249], v[78:81]
	v_mfma_f32_16x16x128_f8f6f4 v[74:77], v[208:215], v[242:249], v[74:77]
	v_mfma_f32_16x16x128_f8f6f4 v[82:85], v[208:215], v[232:239], v[82:85]
	v_mfma_f32_16x16x128_f8f6f4 v[86:89], v[200:207], v[232:239], v[86:89]
	v_mfma_f32_16x16x128_f8f6f4 v[94:97], v[200:207], v[224:231], v[94:97]
	v_mfma_f32_16x16x128_f8f6f4 v[90:93], v[208:215], v[224:231], v[90:93]
	v_mfma_f32_16x16x128_f8f6f4 v[98:101], v[208:215], v[216:223], v[98:101]
	v_mfma_f32_16x16x128_f8f6f4 v[102:105], v[200:207], v[216:223], v[102:105]
	s_setprio 0
	s_barrier
	s_mov_b32 m0, s9
	v_lshl_add_u64 v[176:177], s[44:45], 0, v[156:157]
	s_add_u32 s62, s44, 0x80000
	ds_read_b128 v[216:219], v190 offset:16384
	ds_read_b128 v[220:223], v190 offset:17408
	ds_read_b128 v[224:227], v190 offset:18432
	ds_read_b128 v[228:231], v190 offset:19456
	ds_read_b128 v[232:235], v190 offset:20480
	ds_read_b128 v[236:239], v190 offset:21504
	ds_read_b128 v[242:245], v190 offset:22528
	ds_read_b128 v[246:249], v190 offset:23552
	global_load_lds_dwordx4 v[176:177], off
	v_lshl_add_u64 v[182:183], s[44:45], 0, v[160:161]
	s_mov_b32 m0, s27
	s_addc_u32 s63, s45, 0
	global_load_lds_dwordx4 v[182:183], off
	v_lshl_add_u64 v[184:185], s[62:63], 0, v[156:157]
	s_mov_b32 m0, s33
	v_lshl_add_u64 v[186:187], s[48:49], 0, v[158:159]
	global_load_lds_dwordx4 v[184:185], off
	v_lshl_add_u64 v[184:185], s[62:63], 0, v[160:161]
	s_mov_b32 m0, s35
	s_nop 0
	global_load_lds_dwordx4 v[184:185], off
	v_lshl_add_u64 v[184:185], s[48:49], 0, v[154:155]
	s_mov_b32 m0, s8
	s_nop 0
	global_load_lds_dwordx4 v[184:185], off
	s_mov_b32 m0, s43
	s_nop 0
	global_load_lds_dwordx4 v[186:187], off
	s_waitcnt vmcnt(8)
	s_waitcnt lgkmcnt(0)
	s_barrier
	s_setprio 1
	s_waitcnt lgkmcnt(0)
	v_mfma_f32_16x16x128_f8f6f4 v[70:73], v[2:9], v[216:223], v[70:73]
	v_mfma_f32_16x16x128_f8f6f4 v[66:69], v[192:199], v[216:223], v[66:69]
	v_mfma_f32_16x16x128_f8f6f4 v[58:61], v[192:199], v[224:231], v[58:61]
	v_mfma_f32_16x16x128_f8f6f4 v[62:65], v[2:9], v[224:231], v[62:65]
	v_mfma_f32_16x16x128_f8f6f4 v[54:57], v[2:9], v[232:239], v[54:57]
	v_mfma_f32_16x16x128_f8f6f4 v[50:53], v[192:199], v[232:239], v[50:53]
	v_mfma_f32_16x16x128_f8f6f4 v[42:45], v[192:199], v[242:249], v[42:45]
	v_mfma_f32_16x16x128_f8f6f4 v[46:49], v[2:9], v[242:249], v[46:49]
	s_setprio 0
	s_setprio 1
	v_mfma_f32_16x16x128_f8f6f4 v[14:17], v[200:207], v[242:249], v[14:17]
	v_mfma_f32_16x16x128_f8f6f4 v[10:13], v[208:215], v[242:249], v[10:13]
	v_mfma_f32_16x16x128_f8f6f4 v[18:21], v[208:215], v[232:239], v[18:21]
	v_mfma_f32_16x16x128_f8f6f4 v[22:25], v[200:207], v[232:239], v[22:25]
	v_mfma_f32_16x16x128_f8f6f4 v[30:33], v[200:207], v[224:231], v[30:33]
	v_mfma_f32_16x16x128_f8f6f4 v[26:29], v[208:215], v[224:231], v[26:29]
	v_mfma_f32_16x16x128_f8f6f4 v[34:37], v[208:215], v[216:223], v[34:37]
	v_mfma_f32_16x16x128_f8f6f4 v[38:41], v[200:207], v[216:223], v[38:41]
	s_setprio 0
	s_barrier
	ds_read_b128 v[192:195], v189 offset:32768
	ds_read_b128 v[196:199], v189 offset:33792
	ds_read_b128 v[200:203], v189 offset:34816
	ds_read_b128 v[204:207], v189 offset:35840
	ds_read_b128 v[2:5], v189 offset:49152
	ds_read_b128 v[6:9], v189 offset:50176
	ds_read_b128 v[208:211], v189 offset:51200
	ds_read_b128 v[212:215], v189 offset:52224
	s_add_u32 s48, s48, 0x80000
	s_addc_u32 s49, s49, 0
	s_mov_b32 m0, s52
	v_lshl_add_u64 v[252:253], s[48:49], 0, v[154:155]
	ds_read_b128 v[216:219], v190 offset:32768
	ds_read_b128 v[220:223], v190 offset:33792
	ds_read_b128 v[224:227], v190 offset:34816
	ds_read_b128 v[228:231], v190 offset:35840
	ds_read_b128 v[232:235], v190 offset:36864
	ds_read_b128 v[236:239], v190 offset:37888
	ds_read_b128 v[242:245], v190 offset:38912
	ds_read_b128 v[246:249], v190 offset:39936
	global_load_lds_dwordx4 v[252:253], off
	v_lshl_add_u64 v[252:253], s[48:49], 0, v[158:159]
	s_mov_b32 m0, s53
	s_nop 0
	global_load_lds_dwordx4 v[252:253], off
	s_waitcnt vmcnt(8)
	s_waitcnt lgkmcnt(0)
	s_barrier
	s_setprio 1
	s_waitcnt lgkmcnt(0)
	v_mfma_f32_16x16x128_f8f6f4 v[134:137], v[192:199], v[216:223], v[134:137]
	v_mfma_f32_16x16x128_f8f6f4 v[130:133], v[200:207], v[216:223], v[130:133]
	v_mfma_f32_16x16x128_f8f6f4 v[122:125], v[200:207], v[224:231], v[122:125]
	v_mfma_f32_16x16x128_f8f6f4 v[126:129], v[192:199], v[224:231], v[126:129]
	v_mfma_f32_16x16x128_f8f6f4 v[118:121], v[192:199], v[232:239], v[118:121]
	v_mfma_f32_16x16x128_f8f6f4 v[114:117], v[200:207], v[232:239], v[114:117]
	v_mfma_f32_16x16x128_f8f6f4 v[106:109], v[200:207], v[242:249], v[106:109]
	v_mfma_f32_16x16x128_f8f6f4 v[110:113], v[192:199], v[242:249], v[110:113]
	s_setprio 0
	s_setprio 1
	v_mfma_f32_16x16x128_f8f6f4 v[78:81], v[2:9], v[242:249], v[78:81]
	v_mfma_f32_16x16x128_f8f6f4 v[74:77], v[208:215], v[242:249], v[74:77]
	v_mfma_f32_16x16x128_f8f6f4 v[82:85], v[208:215], v[232:239], v[82:85]
	v_mfma_f32_16x16x128_f8f6f4 v[86:89], v[2:9], v[232:239], v[86:89]
	v_mfma_f32_16x16x128_f8f6f4 v[94:97], v[2:9], v[224:231], v[94:97]
	v_mfma_f32_16x16x128_f8f6f4 v[90:93], v[208:215], v[224:231], v[90:93]
	v_mfma_f32_16x16x128_f8f6f4 v[98:101], v[208:215], v[216:223], v[98:101]
	v_mfma_f32_16x16x128_f8f6f4 v[102:105], v[2:9], v[216:223], v[102:105]
	s_setprio 0
	s_barrier
	s_mov_b32 m0, s70
	v_lshl_add_u64 v[176:177], v[176:177], 0, s[18:19]
	s_add_u32 s44, s44, 0x80080
	ds_read_b128 v[216:219], v190 offset:49152
	ds_read_b128 v[220:223], v190 offset:50176
	ds_read_b128 v[224:227], v190 offset:51200
	ds_read_b128 v[228:231], v190 offset:52224
	ds_read_b128 v[232:235], v190 offset:53248
	ds_read_b128 v[236:239], v190 offset:54272
	ds_read_b128 v[242:245], v190 offset:55296
	ds_read_b128 v[246:249], v190 offset:56320
	global_load_lds_dwordx4 v[176:177], off
	v_lshl_add_u64 v[176:177], v[182:183], 0, s[18:19]
	s_mov_b32 m0, s71
	s_addc_u32 s45, s45, 0
	global_load_lds_dwordx4 v[176:177], off
	v_lshl_add_u64 v[176:177], s[44:45], 0, v[156:157]
	s_mov_b32 m0, s74
	s_nop 0
	global_load_lds_dwordx4 v[176:177], off
	v_lshl_add_u64 v[176:177], s[44:45], 0, v[160:161]
	s_mov_b32 m0, s75
	s_nop 0
	global_load_lds_dwordx4 v[176:177], off
	v_lshl_add_u64 v[176:177], v[184:185], 0, s[18:19]
	s_mov_b32 m0, s72
	s_nop 0
	global_load_lds_dwordx4 v[176:177], off
	v_lshl_add_u64 v[176:177], v[186:187], 0, s[18:19]
	s_mov_b32 m0, s73
	s_nop 0
	global_load_lds_dwordx4 v[176:177], off
	s_waitcnt vmcnt(8)
	s_waitcnt lgkmcnt(0)
	s_barrier
	s_setprio 1
	s_waitcnt lgkmcnt(0)
	v_mfma_f32_16x16x128_f8f6f4 v[70:73], v[192:199], v[216:223], v[70:73]
	v_mfma_f32_16x16x128_f8f6f4 v[66:69], v[200:207], v[216:223], v[66:69]
	v_mfma_f32_16x16x128_f8f6f4 v[58:61], v[200:207], v[224:231], v[58:61]
	v_mfma_f32_16x16x128_f8f6f4 v[62:65], v[192:199], v[224:231], v[62:65]
	v_mfma_f32_16x16x128_f8f6f4 v[54:57], v[192:199], v[232:239], v[54:57]
	v_mfma_f32_16x16x128_f8f6f4 v[50:53], v[200:207], v[232:239], v[50:53]
	v_mfma_f32_16x16x128_f8f6f4 v[42:45], v[200:207], v[242:249], v[42:45]
	v_mfma_f32_16x16x128_f8f6f4 v[46:49], v[192:199], v[242:249], v[46:49]
	s_setprio 0
	s_setprio 1
	v_mfma_f32_16x16x128_f8f6f4 v[14:17], v[2:9], v[242:249], v[14:17]
	v_mfma_f32_16x16x128_f8f6f4 v[10:13], v[208:215], v[242:249], v[10:13]
	v_mfma_f32_16x16x128_f8f6f4 v[18:21], v[208:215], v[232:239], v[18:21]
	v_mfma_f32_16x16x128_f8f6f4 v[22:25], v[2:9], v[232:239], v[22:25]
	v_mfma_f32_16x16x128_f8f6f4 v[30:33], v[2:9], v[224:231], v[30:33]
	v_mfma_f32_16x16x128_f8f6f4 v[26:29], v[208:215], v[224:231], v[26:29]
	v_mfma_f32_16x16x128_f8f6f4 v[34:37], v[208:215], v[216:223], v[34:37]
	v_mfma_f32_16x16x128_f8f6f4 v[38:41], v[2:9], v[216:223], v[38:41]
	s_setprio 0
	s_barrier
	s_add_i32 s44, s51, 2
	s_add_u32 s46, s46, 0x100
	s_addc_u32 s47, s47, 0
	s_add_u32 s41, s41, 0x100
	s_addc_u32 s50, s50, 0
	s_cmp_ge_i32 s51, s86
	s_cbranch_scc1 .LBB0_796
	s_mov_b32 s51, s44
	s_cmp_eq_u32 s86, s51
	s_cselect_b64 s[44:45], -1, 0
	s_cmp_lg_u32 s86, s51
	s_cbranch_scc0 .LBB0_793
	s_branch .LBB0_794

.LBB0_946:
	s_ashr_i32 s37, s36, 31
	ds_read_b128 v[18:21], v192
	ds_read_b128 v[22:25], v192 offset:1024
	ds_read_b128 v[26:29], v192 offset:2048
	ds_read_b128 v[30:33], v192 offset:3072
	ds_read_b128 v[2:5], v192 offset:16384
	ds_read_b128 v[6:9], v192 offset:17408
	ds_read_b128 v[10:13], v192 offset:18432
	ds_read_b128 v[14:17], v192 offset:19456
	s_lshl_b64 s[38:39], s[36:37], 20
	s_add_u32 s38, s22, s38
	s_addc_u32 s39, s23, s39
	s_and_b64 s[40:41], s[2:3], exec
	s_cselect_b32 s37, s39, s47
	s_cselect_b32 s84, s38, s46
	s_ashr_i32 s27, s26, 31
	s_lshl_b64 s[40:41], s[26:27], 20
	s_add_u32 s40, s25, s40
	s_addc_u32 s41, s35, s41
	s_and_b64 s[48:49], s[2:3], exec
	s_cselect_b32 s27, s41, s45
	s_cselect_b32 s85, s40, s44
	s_add_u32 s48, s46, 0x80080
	s_addc_u32 s49, s47, 0
	s_mov_b32 m0, s80
	v_lshl_add_u64 v[218:219], s[48:49], 0, v[164:165]
	ds_read_b128 v[184:187], v193
	ds_read_b128 v[188:191], v193 offset:1024
	ds_read_b128 v[194:197], v193 offset:2048
	ds_read_b128 v[198:201], v193 offset:3072
	ds_read_b128 v[202:205], v193 offset:4096
	ds_read_b128 v[206:209], v193 offset:5120
	ds_read_b128 v[210:213], v193 offset:6144
	ds_read_b128 v[214:217], v193 offset:7168
	global_load_lds_dwordx4 v[218:219], off
	v_lshl_add_u64 v[218:219], s[48:49], 0, v[168:169]
	s_mov_b32 m0, s81
	s_nop 0
	global_load_lds_dwordx4 v[218:219], off
	s_waitcnt vmcnt(8)
	s_waitcnt lgkmcnt(0)
	s_barrier
	s_setprio 1
	s_waitcnt lgkmcnt(0)
	v_mfma_f32_16x16x128_f8f6f4 v[158:161], v[18:25], v[184:191], 0
	v_mfma_f32_16x16x128_f8f6f4 v[154:157], v[26:33], v[184:191], 0
	v_mfma_f32_16x16x128_f8f6f4 v[146:149], v[26:33], v[194:201], 0
	v_mfma_f32_16x16x128_f8f6f4 v[150:153], v[18:25], v[194:201], 0
	v_mfma_f32_16x16x128_f8f6f4 v[142:145], v[18:25], v[202:209], 0
	v_mfma_f32_16x16x128_f8f6f4 v[138:141], v[26:33], v[202:209], 0
	v_mfma_f32_16x16x128_f8f6f4 v[130:133], v[26:33], v[210:217], 0
	v_mfma_f32_16x16x128_f8f6f4 v[134:137], v[18:25], v[210:217], 0
	s_setprio 0
	s_setprio 1
	v_mfma_f32_16x16x128_f8f6f4 v[102:105], v[2:9], v[210:217], 0
	v_mfma_f32_16x16x128_f8f6f4 v[98:101], v[10:17], v[210:217], 0
	v_mfma_f32_16x16x128_f8f6f4 v[106:109], v[10:17], v[202:209], 0
	v_mfma_f32_16x16x128_f8f6f4 v[110:113], v[2:9], v[202:209], 0
	v_mfma_f32_16x16x128_f8f6f4 v[118:121], v[2:9], v[194:201], 0
	v_mfma_f32_16x16x128_f8f6f4 v[114:117], v[10:17], v[194:201], 0
	v_mfma_f32_16x16x128_f8f6f4 v[122:125], v[10:17], v[184:191], 0
	v_mfma_f32_16x16x128_f8f6f4 v[126:129], v[2:9], v[184:191], 0
	s_setprio 0
	s_barrier
	v_lshl_add_u64 v[184:185], s[44:45], 0, v[166:167]
	s_mov_b32 m0, s52
	v_lshl_add_u64 v[186:187], v[184:185], 0, s[14:15]
	ds_read_b128 v[194:197], v193 offset:16384
	ds_read_b128 v[198:201], v193 offset:17408
	ds_read_b128 v[202:205], v193 offset:18432
	ds_read_b128 v[206:209], v193 offset:19456
	ds_read_b128 v[210:213], v193 offset:20480
	ds_read_b128 v[214:217], v193 offset:21504
	ds_read_b128 v[218:221], v193 offset:22528
	ds_read_b128 v[222:225], v193 offset:23552
	global_load_lds_dwordx4 v[186:187], off
	v_lshl_add_u64 v[186:187], s[44:45], 0, v[170:171]
	s_add_u32 s48, s44, 0x80100
	v_lshl_add_u64 v[188:189], v[186:187], 0, s[14:15]
	s_mov_b32 m0, s53
	s_addc_u32 s49, s45, 0
	global_load_lds_dwordx4 v[188:189], off
	v_lshl_add_u64 v[188:189], s[48:49], 0, v[166:167]
	s_mov_b32 m0, s54
	s_nop 0
	global_load_lds_dwordx4 v[188:189], off
	v_lshl_add_u64 v[188:189], s[48:49], 0, v[170:171]
	s_mov_b32 m0, s55
	s_nop 0
	global_load_lds_dwordx4 v[188:189], off
	v_lshl_add_u64 v[188:189], s[46:47], 0, v[164:165]
	v_lshl_add_u64 v[190:191], v[188:189], 0, s[14:15]
	s_mov_b32 m0, s43
	s_nop 0
	global_load_lds_dwordx4 v[190:191], off
	v_lshl_add_u64 v[190:191], s[46:47], 0, v[168:169]
	v_lshl_add_u64 v[226:227], v[190:191], 0, s[14:15]
	s_mov_b32 m0, s61
	s_nop 0
	global_load_lds_dwordx4 v[226:227], off
	s_waitcnt vmcnt(8)
	s_waitcnt lgkmcnt(0)
	s_barrier
	s_setprio 1
	s_waitcnt lgkmcnt(0)
	v_mfma_f32_16x16x128_f8f6f4 v[94:97], v[18:25], v[194:201], 0
	v_mfma_f32_16x16x128_f8f6f4 v[90:93], v[26:33], v[194:201], 0
	v_mfma_f32_16x16x128_f8f6f4 v[82:85], v[26:33], v[202:209], 0
	v_mfma_f32_16x16x128_f8f6f4 v[86:89], v[18:25], v[202:209], 0
	v_mfma_f32_16x16x128_f8f6f4 v[78:81], v[18:25], v[210:217], 0
	v_mfma_f32_16x16x128_f8f6f4 v[74:77], v[26:33], v[210:217], 0
	v_mfma_f32_16x16x128_f8f6f4 v[66:69], v[26:33], v[218:225], 0
	v_mfma_f32_16x16x128_f8f6f4 v[70:73], v[18:25], v[218:225], 0
	s_setprio 0
	s_setprio 1
	v_mfma_f32_16x16x128_f8f6f4 v[38:41], v[2:9], v[218:225], 0
	v_mfma_f32_16x16x128_f8f6f4 v[34:37], v[10:17], v[218:225], 0
	v_mfma_f32_16x16x128_f8f6f4 v[42:45], v[10:17], v[210:217], 0
	v_mfma_f32_16x16x128_f8f6f4 v[46:49], v[2:9], v[210:217], 0
	v_mfma_f32_16x16x128_f8f6f4 v[54:57], v[2:9], v[202:209], 0
	v_mfma_f32_16x16x128_f8f6f4 v[50:53], v[10:17], v[202:209], 0
	v_mfma_f32_16x16x128_f8f6f4 v[58:61], v[10:17], v[194:201], 0
	v_mfma_f32_16x16x128_f8f6f4 v[62:65], v[2:9], v[194:201], 0
	s_setprio 0
	s_barrier
	ds_read_b128 v[18:21], v192 offset:32768
	ds_read_b128 v[22:25], v192 offset:33792
	ds_read_b128 v[26:29], v192 offset:34816
	ds_read_b128 v[30:33], v192 offset:35840
	ds_read_b128 v[2:5], v192 offset:49152
	ds_read_b128 v[6:9], v192 offset:50176
	ds_read_b128 v[10:13], v192 offset:51200
	ds_read_b128 v[14:17], v192 offset:52224
	s_add_u32 s48, s46, 0x80100
	s_addc_u32 s49, s47, 0
	s_mov_b32 m0, s68
	v_lshl_add_u64 v[226:227], s[48:49], 0, v[164:165]
	ds_read_b128 v[194:197], v193 offset:32768
	ds_read_b128 v[198:201], v193 offset:33792
	ds_read_b128 v[202:205], v193 offset:34816
	ds_read_b128 v[206:209], v193 offset:35840
	ds_read_b128 v[210:213], v193 offset:36864
	ds_read_b128 v[214:217], v193 offset:37888
	ds_read_b128 v[218:221], v193 offset:38912
	ds_read_b128 v[222:225], v193 offset:39936
	global_load_lds_dwordx4 v[226:227], off
	v_lshl_add_u64 v[226:227], s[48:49], 0, v[168:169]
	s_mov_b32 m0, s69
	s_nop 0
	global_load_lds_dwordx4 v[226:227], off
	s_waitcnt vmcnt(8)
	s_waitcnt lgkmcnt(0)
	s_barrier
	s_setprio 1
	s_waitcnt lgkmcnt(0)
	v_mfma_f32_16x16x128_f8f6f4 v[158:161], v[18:25], v[194:201], v[158:161]
	v_mfma_f32_16x16x128_f8f6f4 v[154:157], v[26:33], v[194:201], v[154:157]
	v_mfma_f32_16x16x128_f8f6f4 v[146:149], v[26:33], v[202:209], v[146:149]
	v_mfma_f32_16x16x128_f8f6f4 v[150:153], v[18:25], v[202:209], v[150:153]
	v_mfma_f32_16x16x128_f8f6f4 v[142:145], v[18:25], v[210:217], v[142:145]
	v_mfma_f32_16x16x128_f8f6f4 v[138:141], v[26:33], v[210:217], v[138:141]
	v_mfma_f32_16x16x128_f8f6f4 v[130:133], v[26:33], v[218:225], v[130:133]
	v_mfma_f32_16x16x128_f8f6f4 v[134:137], v[18:25], v[218:225], v[134:137]
	s_setprio 0
	s_setprio 1
	v_mfma_f32_16x16x128_f8f6f4 v[102:105], v[2:9], v[218:225], v[102:105]
	v_mfma_f32_16x16x128_f8f6f4 v[98:101], v[10:17], v[218:225], v[98:101]
	v_mfma_f32_16x16x128_f8f6f4 v[106:109], v[10:17], v[210:217], v[106:109]
	v_mfma_f32_16x16x128_f8f6f4 v[110:113], v[2:9], v[210:217], v[110:113]
	v_mfma_f32_16x16x128_f8f6f4 v[118:121], v[2:9], v[202:209], v[118:121]
	v_mfma_f32_16x16x128_f8f6f4 v[114:117], v[10:17], v[202:209], v[114:117]
	v_mfma_f32_16x16x128_f8f6f4 v[122:125], v[10:17], v[194:201], v[122:125]
	v_mfma_f32_16x16x128_f8f6f4 v[126:129], v[2:9], v[194:201], v[126:129]
	s_setprio 0
	s_barrier
	s_mov_b32 m0, s74
	v_lshl_add_u64 v[184:185], v[184:185], 0, s[18:19]
	s_add_u32 s48, s44, 0x80180
	ds_read_b128 v[194:197], v193 offset:49152
	ds_read_b128 v[198:201], v193 offset:50176
	ds_read_b128 v[202:205], v193 offset:51200
	ds_read_b128 v[206:209], v193 offset:52224
	ds_read_b128 v[210:213], v193 offset:53248
	ds_read_b128 v[214:217], v193 offset:54272
	ds_read_b128 v[218:221], v193 offset:55296
	ds_read_b128 v[222:225], v193 offset:56320
	global_load_lds_dwordx4 v[184:185], off
	v_lshl_add_u64 v[184:185], v[186:187], 0, s[18:19]
	s_mov_b32 m0, s75
	s_addc_u32 s49, s45, 0
	global_load_lds_dwordx4 v[184:185], off
	v_lshl_add_u64 v[184:185], s[48:49], 0, v[166:167]
	s_mov_b32 m0, s78
	s_nop 0
	global_load_lds_dwordx4 v[184:185], off
	v_lshl_add_u64 v[184:185], s[48:49], 0, v[170:171]
	s_mov_b32 m0, s79
	s_nop 0
	global_load_lds_dwordx4 v[184:185], off
	v_lshl_add_u64 v[184:185], v[188:189], 0, s[18:19]
	s_mov_b32 m0, s76
	s_nop 0
	global_load_lds_dwordx4 v[184:185], off
	v_lshl_add_u64 v[184:185], v[190:191], 0, s[18:19]
	s_mov_b32 m0, s77
	s_nop 0
	global_load_lds_dwordx4 v[184:185], off
	s_waitcnt vmcnt(8)
	s_waitcnt lgkmcnt(0)
	s_barrier
	s_setprio 1
	s_waitcnt lgkmcnt(0)
	v_mfma_f32_16x16x128_f8f6f4 v[94:97], v[18:25], v[194:201], v[94:97]
	v_mfma_f32_16x16x128_f8f6f4 v[90:93], v[26:33], v[194:201], v[90:93]
	v_mfma_f32_16x16x128_f8f6f4 v[82:85], v[26:33], v[202:209], v[82:85]
	v_mfma_f32_16x16x128_f8f6f4 v[86:89], v[18:25], v[202:209], v[86:89]
	v_mfma_f32_16x16x128_f8f6f4 v[78:81], v[18:25], v[210:217], v[78:81]
	v_mfma_f32_16x16x128_f8f6f4 v[74:77], v[26:33], v[210:217], v[74:77]
	v_mfma_f32_16x16x128_f8f6f4 v[66:69], v[26:33], v[218:225], v[66:69]
	v_mfma_f32_16x16x128_f8f6f4 v[70:73], v[18:25], v[218:225], v[70:73]
	s_setprio 0
	s_setprio 1
	v_mfma_f32_16x16x128_f8f6f4 v[38:41], v[2:9], v[218:225], v[38:41]
	v_mfma_f32_16x16x128_f8f6f4 v[34:37], v[10:17], v[218:225], v[34:37]
	v_mfma_f32_16x16x128_f8f6f4 v[42:45], v[10:17], v[210:217], v[42:45]
	v_mfma_f32_16x16x128_f8f6f4 v[46:49], v[2:9], v[210:217], v[46:49]
	v_mfma_f32_16x16x128_f8f6f4 v[54:57], v[2:9], v[202:209], v[54:57]
	v_mfma_f32_16x16x128_f8f6f4 v[50:53], v[10:17], v[202:209], v[50:53]
	v_mfma_f32_16x16x128_f8f6f4 v[58:61], v[10:17], v[194:201], v[58:61]
	v_mfma_f32_16x16x128_f8f6f4 v[62:65], v[2:9], v[194:201], v[62:65]
	s_setprio 0
	s_barrier
	s_add_u32 s46, s46, 0x80180
	s_addc_u32 s47, s47, 0
	s_add_u32 s62, s44, 0x200
	s_addc_u32 s63, s45, 0
	s_mov_b32 s86, 0
.LBB0_947:
	ds_read_b128 v[2:5], v192
	ds_read_b128 v[6:9], v192 offset:1024
	ds_read_b128 v[18:21], v192 offset:2048
	ds_read_b128 v[22:25], v192 offset:3072
	ds_read_b128 v[26:29], v192 offset:16384
	ds_read_b128 v[30:33], v192 offset:17408
	ds_read_b128 v[184:187], v192 offset:18432
	ds_read_b128 v[188:191], v192 offset:19456
	s_add_u32 s44, s46, 0xfff80080
	s_addc_u32 s45, s47, -1
	s_cmp_eq_u32 s86, 28
	s_cselect_b32 s49, s37, s45
	s_cselect_b32 s48, s84, s44
	s_cselect_b32 s45, s27, s63
	s_cselect_b32 s44, s85, s62
	s_mov_b32 m0, s80
	v_lshl_add_u64 v[218:219], s[46:47], 0, v[172:173]
	ds_read_b128 v[10:13], v193
	ds_read_b128 v[14:17], v193 offset:1024
	ds_read_b128 v[194:197], v193 offset:2048
	ds_read_b128 v[198:201], v193 offset:3072
	ds_read_b128 v[202:205], v193 offset:4096
	ds_read_b128 v[206:209], v193 offset:5120
	ds_read_b128 v[210:213], v193 offset:6144
	ds_read_b128 v[214:217], v193 offset:7168
	global_load_lds_dwordx4 v[218:219], off
	v_lshl_add_u64 v[218:219], s[46:47], 0, v[174:175]
	s_mov_b32 m0, s81
	s_nop 0
	global_load_lds_dwordx4 v[218:219], off
	s_waitcnt vmcnt(8)
	s_waitcnt lgkmcnt(0)
	s_barrier
	s_setprio 1
	s_waitcnt lgkmcnt(0)
	v_mfma_f32_16x16x128_f8f6f4 v[158:161], v[2:9], v[10:17], v[158:161]
	v_mfma_f32_16x16x128_f8f6f4 v[154:157], v[18:25], v[10:17], v[154:157]
	v_mfma_f32_16x16x128_f8f6f4 v[146:149], v[18:25], v[194:201], v[146:149]
	v_mfma_f32_16x16x128_f8f6f4 v[150:153], v[2:9], v[194:201], v[150:153]
	v_mfma_f32_16x16x128_f8f6f4 v[142:145], v[2:9], v[202:209], v[142:145]
	v_mfma_f32_16x16x128_f8f6f4 v[138:141], v[18:25], v[202:209], v[138:141]
	v_mfma_f32_16x16x128_f8f6f4 v[130:133], v[18:25], v[210:217], v[130:133]
	v_mfma_f32_16x16x128_f8f6f4 v[134:137], v[2:9], v[210:217], v[134:137]
	s_setprio 0
	s_setprio 1
	v_mfma_f32_16x16x128_f8f6f4 v[102:105], v[26:33], v[210:217], v[102:105]
	v_mfma_f32_16x16x128_f8f6f4 v[98:101], v[184:191], v[210:217], v[98:101]
	v_mfma_f32_16x16x128_f8f6f4 v[106:109], v[184:191], v[202:209], v[106:109]
	v_mfma_f32_16x16x128_f8f6f4 v[110:113], v[26:33], v[202:209], v[110:113]
	v_mfma_f32_16x16x128_f8f6f4 v[118:121], v[26:33], v[194:201], v[118:121]
	v_mfma_f32_16x16x128_f8f6f4 v[114:117], v[184:191], v[194:201], v[114:117]
	v_mfma_f32_16x16x128_f8f6f4 v[122:125], v[184:191], v[10:17], v[122:125]
	v_mfma_f32_16x16x128_f8f6f4 v[126:129], v[26:33], v[10:17], v[126:129]
	s_setprio 0
	s_barrier
	s_mov_b32 m0, s52
	v_lshl_add_u64 v[10:11], s[44:45], 0, v[166:167]
	s_add_u32 s88, s44, 0x80000
	ds_read_b128 v[194:197], v193 offset:16384
	ds_read_b128 v[198:201], v193 offset:17408
	ds_read_b128 v[202:205], v193 offset:18432
	ds_read_b128 v[206:209], v193 offset:19456
	ds_read_b128 v[210:213], v193 offset:20480
	ds_read_b128 v[214:217], v193 offset:21504
	ds_read_b128 v[218:221], v193 offset:22528
	ds_read_b128 v[222:225], v193 offset:23552
	global_load_lds_dwordx4 v[10:11], off
	v_lshl_add_u64 v[12:13], s[44:45], 0, v[170:171]
	s_mov_b32 m0, s53
	s_addc_u32 s89, s45, 0
	global_load_lds_dwordx4 v[12:13], off
	v_lshl_add_u64 v[14:15], s[88:89], 0, v[166:167]
	s_mov_b32 m0, s54
	v_lshl_add_u64 v[16:17], s[48:49], 0, v[168:169]
	global_load_lds_dwordx4 v[14:15], off
	v_lshl_add_u64 v[14:15], s[88:89], 0, v[170:171]
	s_mov_b32 m0, s55
	s_nop 0
	global_load_lds_dwordx4 v[14:15], off
	v_lshl_add_u64 v[14:15], s[48:49], 0, v[164:165]
	s_mov_b32 m0, s43
	s_nop 0
	global_load_lds_dwordx4 v[14:15], off
	s_mov_b32 m0, s61
	s_nop 0
	global_load_lds_dwordx4 v[16:17], off
	s_waitcnt vmcnt(8)
	s_waitcnt lgkmcnt(0)
	s_barrier
	s_setprio 1
	s_waitcnt lgkmcnt(0)
	v_mfma_f32_16x16x128_f8f6f4 v[94:97], v[2:9], v[194:201], v[94:97]
	v_mfma_f32_16x16x128_f8f6f4 v[90:93], v[18:25], v[194:201], v[90:93]
	v_mfma_f32_16x16x128_f8f6f4 v[82:85], v[18:25], v[202:209], v[82:85]
	v_mfma_f32_16x16x128_f8f6f4 v[86:89], v[2:9], v[202:209], v[86:89]
	v_mfma_f32_16x16x128_f8f6f4 v[78:81], v[2:9], v[210:217], v[78:81]
	v_mfma_f32_16x16x128_f8f6f4 v[74:77], v[18:25], v[210:217], v[74:77]
	v_mfma_f32_16x16x128_f8f6f4 v[66:69], v[18:25], v[218:225], v[66:69]
	v_mfma_f32_16x16x128_f8f6f4 v[70:73], v[2:9], v[218:225], v[70:73]
	s_setprio 0
	s_setprio 1
	v_mfma_f32_16x16x128_f8f6f4 v[38:41], v[26:33], v[218:225], v[38:41]
	v_mfma_f32_16x16x128_f8f6f4 v[34:37], v[184:191], v[218:225], v[34:37]
	v_mfma_f32_16x16x128_f8f6f4 v[42:45], v[184:191], v[210:217], v[42:45]
	v_mfma_f32_16x16x128_f8f6f4 v[46:49], v[26:33], v[210:217], v[46:49]
	v_mfma_f32_16x16x128_f8f6f4 v[54:57], v[26:33], v[202:209], v[54:57]
	v_mfma_f32_16x16x128_f8f6f4 v[50:53], v[184:191], v[202:209], v[50:53]
	v_mfma_f32_16x16x128_f8f6f4 v[58:61], v[184:191], v[194:201], v[58:61]
	v_mfma_f32_16x16x128_f8f6f4 v[62:65], v[26:33], v[194:201], v[62:65]
	s_setprio 0
	s_barrier
	ds_read_b128 v[18:21], v192 offset:32768
	ds_read_b128 v[22:25], v192 offset:33792
	ds_read_b128 v[26:29], v192 offset:34816
	ds_read_b128 v[30:33], v192 offset:35840
	ds_read_b128 v[2:5], v192 offset:49152
	ds_read_b128 v[6:9], v192 offset:50176
	ds_read_b128 v[184:187], v192 offset:51200
	ds_read_b128 v[188:191], v192 offset:52224
	s_add_u32 s48, s48, 0x80000
	s_addc_u32 s49, s49, 0
	s_mov_b32 m0, s68
	v_lshl_add_u64 v[226:227], s[48:49], 0, v[164:165]
	ds_read_b128 v[194:197], v193 offset:32768
	ds_read_b128 v[198:201], v193 offset:33792
	ds_read_b128 v[202:205], v193 offset:34816
	ds_read_b128 v[206:209], v193 offset:35840
	ds_read_b128 v[210:213], v193 offset:36864
	ds_read_b128 v[214:217], v193 offset:37888
	ds_read_b128 v[218:221], v193 offset:38912
	ds_read_b128 v[222:225], v193 offset:39936
	global_load_lds_dwordx4 v[226:227], off
	v_lshl_add_u64 v[226:227], s[48:49], 0, v[168:169]
	s_mov_b32 m0, s69
	s_nop 0
	global_load_lds_dwordx4 v[226:227], off
	s_waitcnt vmcnt(8)
	s_waitcnt lgkmcnt(0)
	s_barrier
	s_setprio 1
	s_waitcnt lgkmcnt(0)
	v_mfma_f32_16x16x128_f8f6f4 v[158:161], v[18:25], v[194:201], v[158:161]
	v_mfma_f32_16x16x128_f8f6f4 v[154:157], v[26:33], v[194:201], v[154:157]
	v_mfma_f32_16x16x128_f8f6f4 v[146:149], v[26:33], v[202:209], v[146:149]
	v_mfma_f32_16x16x128_f8f6f4 v[150:153], v[18:25], v[202:209], v[150:153]
	v_mfma_f32_16x16x128_f8f6f4 v[142:145], v[18:25], v[210:217], v[142:145]
	v_mfma_f32_16x16x128_f8f6f4 v[138:141], v[26:33], v[210:217], v[138:141]
	v_mfma_f32_16x16x128_f8f6f4 v[130:133], v[26:33], v[218:225], v[130:133]
	v_mfma_f32_16x16x128_f8f6f4 v[134:137], v[18:25], v[218:225], v[134:137]
	s_setprio 0
	s_setprio 1
	v_mfma_f32_16x16x128_f8f6f4 v[102:105], v[2:9], v[218:225], v[102:105]
	v_mfma_f32_16x16x128_f8f6f4 v[98:101], v[184:191], v[218:225], v[98:101]
	v_mfma_f32_16x16x128_f8f6f4 v[106:109], v[184:191], v[210:217], v[106:109]
	v_mfma_f32_16x16x128_f8f6f4 v[110:113], v[2:9], v[210:217], v[110:113]
	v_mfma_f32_16x16x128_f8f6f4 v[118:121], v[2:9], v[202:209], v[118:121]
	v_mfma_f32_16x16x128_f8f6f4 v[114:117], v[184:191], v[202:209], v[114:117]
	v_mfma_f32_16x16x128_f8f6f4 v[122:125], v[184:191], v[194:201], v[122:125]
	v_mfma_f32_16x16x128_f8f6f4 v[126:129], v[2:9], v[194:201], v[126:129]
	s_setprio 0
	s_barrier
	s_mov_b32 m0, s74
	v_lshl_add_u64 v[10:11], v[10:11], 0, s[4:5]
	s_add_u32 s44, s44, 0x80080
	ds_read_b128 v[194:197], v193 offset:49152
	ds_read_b128 v[198:201], v193 offset:50176
	ds_read_b128 v[202:205], v193 offset:51200
	ds_read_b128 v[206:209], v193 offset:52224
	ds_read_b128 v[210:213], v193 offset:53248
	ds_read_b128 v[214:217], v193 offset:54272
	ds_read_b128 v[218:221], v193 offset:55296
	ds_read_b128 v[222:225], v193 offset:56320
	global_load_lds_dwordx4 v[10:11], off
	v_lshl_add_u64 v[10:11], v[12:13], 0, s[4:5]
	s_mov_b32 m0, s75
	s_addc_u32 s45, s45, 0
	global_load_lds_dwordx4 v[10:11], off
	v_lshl_add_u64 v[10:11], s[44:45], 0, v[166:167]
	s_mov_b32 m0, s78
	s_nop 0
	global_load_lds_dwordx4 v[10:11], off
	v_lshl_add_u64 v[10:11], s[44:45], 0, v[170:171]
	s_mov_b32 m0, s79
	s_nop 0
	global_load_lds_dwordx4 v[10:11], off
	v_lshl_add_u64 v[10:11], v[14:15], 0, s[4:5]
	s_mov_b32 m0, s76
	s_nop 0
	global_load_lds_dwordx4 v[10:11], off
	v_lshl_add_u64 v[10:11], v[16:17], 0, s[4:5]
	s_mov_b32 m0, s77
	s_nop 0
	global_load_lds_dwordx4 v[10:11], off
	s_waitcnt vmcnt(8)
	s_waitcnt lgkmcnt(0)
	s_barrier
	s_setprio 1
	s_waitcnt lgkmcnt(0)
	v_mfma_f32_16x16x128_f8f6f4 v[94:97], v[18:25], v[194:201], v[94:97]
	v_mfma_f32_16x16x128_f8f6f4 v[90:93], v[26:33], v[194:201], v[90:93]
	v_mfma_f32_16x16x128_f8f6f4 v[82:85], v[26:33], v[202:209], v[82:85]
	v_mfma_f32_16x16x128_f8f6f4 v[86:89], v[18:25], v[202:209], v[86:89]
	v_mfma_f32_16x16x128_f8f6f4 v[78:81], v[18:25], v[210:217], v[78:81]
	v_mfma_f32_16x16x128_f8f6f4 v[74:77], v[26:33], v[210:217], v[74:77]
	v_mfma_f32_16x16x128_f8f6f4 v[66:69], v[26:33], v[218:225], v[66:69]
	v_mfma_f32_16x16x128_f8f6f4 v[70:73], v[18:25], v[218:225], v[70:73]
	s_setprio 0
	s_setprio 1
	v_mfma_f32_16x16x128_f8f6f4 v[38:41], v[2:9], v[218:225], v[38:41]
	v_mfma_f32_16x16x128_f8f6f4 v[34:37], v[184:191], v[218:225], v[34:37]
	v_mfma_f32_16x16x128_f8f6f4 v[42:45], v[184:191], v[210:217], v[42:45]
	v_mfma_f32_16x16x128_f8f6f4 v[46:49], v[2:9], v[210:217], v[46:49]
	v_mfma_f32_16x16x128_f8f6f4 v[54:57], v[2:9], v[202:209], v[54:57]
	v_mfma_f32_16x16x128_f8f6f4 v[50:53], v[184:191], v[202:209], v[50:53]
	v_mfma_f32_16x16x128_f8f6f4 v[58:61], v[184:191], v[194:201], v[58:61]
	v_mfma_f32_16x16x128_f8f6f4 v[62:65], v[2:9], v[194:201], v[62:65]
	s_setprio 0
	s_barrier
	s_add_i32 s86, s86, 2
	s_add_u32 s46, s46, 0x100
	s_addc_u32 s47, s47, 0
	s_add_u32 s62, s62, 0x100
	s_addc_u32 s63, s63, 0
	s_cmp_gt_u32 s86, 29
	s_cbranch_scc0 .LBB0_947
	s_and_b64 vcc, exec, s[6:7]
	s_cbranch_vccz .LBB0_950
	s_barrier

.LBB0_1031:
	ds_read_b128 v[2:5], v189
	ds_read_b128 v[6:9], v189 offset:1024
	ds_read_b128 v[192:195], v189 offset:2048
	ds_read_b128 v[196:199], v189 offset:3072
	ds_read_b128 v[200:203], v189 offset:16384
	ds_read_b128 v[204:207], v189 offset:17408
	ds_read_b128 v[208:211], v189 offset:18432
	ds_read_b128 v[212:215], v189 offset:19456
	s_add_u32 s25, s36, 0x100
	s_addc_u32 s83, s37, 0
	s_and_b64 s[40:41], s[38:39], exec
	s_cselect_b32 s41, s1, s83
	s_cselect_b32 s40, s0, s25
	s_add_u32 s25, s26, 0x100
	s_addc_u32 s83, s27, 0
	s_and_b64 s[38:39], s[38:39], exec
	s_cselect_b32 s39, s5, s83
	s_cselect_b32 s38, s4, s25
	s_add_u32 s84, s36, 0x158080
	s_addc_u32 s85, s37, 0
	s_add_i32 s25, s23, 0xc000
	v_lshl_add_u64 v[174:175], s[84:85], 0, v[154:155]
	s_mov_b32 m0, s25
	s_add_i32 s83, s23, 0xe000
	ds_read_b128 v[216:219], v190
	ds_read_b128 v[220:223], v190 offset:1024
	ds_read_b128 v[224:227], v190 offset:2048
	ds_read_b128 v[228:231], v190 offset:3072
	ds_read_b128 v[232:235], v190 offset:4096
	ds_read_b128 v[236:239], v190 offset:5120
	ds_read_b128 v[240:243], v190 offset:6144
	ds_read_b128 v[244:247], v190 offset:7168
	global_load_lds_dwordx4 v[174:175], off
	v_lshl_add_u64 v[174:175], s[84:85], 0, v[158:159]
	s_mov_b32 m0, s83
	s_nop 0
	global_load_lds_dwordx4 v[174:175], off
	s_waitcnt vmcnt(8)
	s_waitcnt lgkmcnt(0)
	s_barrier
	s_setprio 1
	s_waitcnt lgkmcnt(0)
	v_mfma_f32_16x16x128_f8f6f4 v[134:137], v[2:9], v[216:223], 0
	v_mfma_f32_16x16x128_f8f6f4 v[130:133], v[192:199], v[216:223], 0
	v_mfma_f32_16x16x128_f8f6f4 v[122:125], v[192:199], v[224:231], 0
	v_mfma_f32_16x16x128_f8f6f4 v[126:129], v[2:9], v[224:231], 0
	v_mfma_f32_16x16x128_f8f6f4 v[118:121], v[2:9], v[232:239], 0
	v_mfma_f32_16x16x128_f8f6f4 v[114:117], v[192:199], v[232:239], 0
	v_mfma_f32_16x16x128_f8f6f4 v[106:109], v[192:199], v[240:247], 0
	v_mfma_f32_16x16x128_f8f6f4 v[110:113], v[2:9], v[240:247], 0
	s_setprio 0
	s_setprio 1
	v_mfma_f32_16x16x128_f8f6f4 v[78:81], v[200:207], v[240:247], 0
	v_mfma_f32_16x16x128_f8f6f4 v[74:77], v[208:215], v[240:247], 0
	v_mfma_f32_16x16x128_f8f6f4 v[82:85], v[208:215], v[232:239], 0
	v_mfma_f32_16x16x128_f8f6f4 v[86:89], v[200:207], v[232:239], 0
	v_mfma_f32_16x16x128_f8f6f4 v[94:97], v[200:207], v[224:231], 0
	v_mfma_f32_16x16x128_f8f6f4 v[90:93], v[208:215], v[224:231], 0
	v_mfma_f32_16x16x128_f8f6f4 v[98:101], v[208:215], v[216:223], 0
	v_mfma_f32_16x16x128_f8f6f4 v[102:105], v[200:207], v[216:223], 0
	s_setprio 0
	s_barrier
	s_mov_b32 m0, s33
	v_lshl_add_u64 v[174:175], s[38:39], 0, v[156:157]
	s_add_u32 s84, s38, 0x158000
	ds_read_b128 v[216:219], v190 offset:16384
	ds_read_b128 v[220:223], v190 offset:17408
	ds_read_b128 v[224:227], v190 offset:18432
	ds_read_b128 v[228:231], v190 offset:19456
	ds_read_b128 v[232:235], v190 offset:20480
	ds_read_b128 v[236:239], v190 offset:21504
	ds_read_b128 v[240:243], v190 offset:22528
	ds_read_b128 v[244:247], v190 offset:23552
	global_load_lds_dwordx4 v[174:175], off
	v_lshl_add_u64 v[176:177], s[38:39], 0, v[160:161]
	s_mov_b32 m0, s35
	s_addc_u32 s85, s39, 0
	global_load_lds_dwordx4 v[176:177], off
	v_lshl_add_u64 v[182:183], s[84:85], 0, v[156:157]
	s_mov_b32 m0, s42
	v_lshl_add_u64 v[184:185], s[40:41], 0, v[158:159]
	global_load_lds_dwordx4 v[182:183], off
	v_lshl_add_u64 v[182:183], s[84:85], 0, v[160:161]
	s_mov_b32 m0, s43
	s_nop 0
	global_load_lds_dwordx4 v[182:183], off
	v_lshl_add_u64 v[182:183], s[40:41], 0, v[154:155]
	s_mov_b32 m0, s23
	s_nop 0
	global_load_lds_dwordx4 v[182:183], off
	s_mov_b32 m0, s44
	s_nop 0
	global_load_lds_dwordx4 v[184:185], off
	s_waitcnt vmcnt(8)
	s_waitcnt lgkmcnt(0)
	s_barrier
	s_setprio 1
	s_waitcnt lgkmcnt(0)
	v_mfma_f32_16x16x128_f8f6f4 v[70:73], v[2:9], v[216:223], 0
	v_mfma_f32_16x16x128_f8f6f4 v[66:69], v[192:199], v[216:223], 0
	v_mfma_f32_16x16x128_f8f6f4 v[58:61], v[192:199], v[224:231], 0
	v_mfma_f32_16x16x128_f8f6f4 v[62:65], v[2:9], v[224:231], 0
	v_mfma_f32_16x16x128_f8f6f4 v[54:57], v[2:9], v[232:239], 0
	v_mfma_f32_16x16x128_f8f6f4 v[50:53], v[192:199], v[232:239], 0
	v_mfma_f32_16x16x128_f8f6f4 v[42:45], v[192:199], v[240:247], 0
	v_mfma_f32_16x16x128_f8f6f4 v[46:49], v[2:9], v[240:247], 0
	s_setprio 0
	s_setprio 1
	v_mfma_f32_16x16x128_f8f6f4 v[14:17], v[200:207], v[240:247], 0
	v_mfma_f32_16x16x128_f8f6f4 v[10:13], v[208:215], v[240:247], 0
	v_mfma_f32_16x16x128_f8f6f4 v[18:21], v[208:215], v[232:239], 0
	v_mfma_f32_16x16x128_f8f6f4 v[22:25], v[200:207], v[232:239], 0
	v_mfma_f32_16x16x128_f8f6f4 v[30:33], v[200:207], v[224:231], 0
	v_mfma_f32_16x16x128_f8f6f4 v[26:29], v[208:215], v[224:231], 0
	v_mfma_f32_16x16x128_f8f6f4 v[34:37], v[208:215], v[216:223], 0
	v_mfma_f32_16x16x128_f8f6f4 v[38:41], v[200:207], v[216:223], 0
	s_setprio 0
	s_barrier
	ds_read_b128 v[2:5], v189 offset:32768
	ds_read_b128 v[6:9], v189 offset:33792
	ds_read_b128 v[192:195], v189 offset:34816
	ds_read_b128 v[196:199], v189 offset:35840
	ds_read_b128 v[200:203], v189 offset:49152
	ds_read_b128 v[204:207], v189 offset:50176
	ds_read_b128 v[208:211], v189 offset:51200
	ds_read_b128 v[212:215], v189 offset:52224
	s_add_u32 s40, s40, 0x158000
	s_addc_u32 s41, s41, 0
	s_mov_b32 m0, s45
	v_lshl_add_u64 v[186:187], s[40:41], 0, v[154:155]
	ds_read_b128 v[216:219], v190 offset:32768
	ds_read_b128 v[220:223], v190 offset:33792
	ds_read_b128 v[224:227], v190 offset:34816
	ds_read_b128 v[228:231], v190 offset:35840
	ds_read_b128 v[232:235], v190 offset:36864
	ds_read_b128 v[236:239], v190 offset:37888
	ds_read_b128 v[240:243], v190 offset:38912
	ds_read_b128 v[244:247], v190 offset:39936
	global_load_lds_dwordx4 v[186:187], off
	v_lshl_add_u64 v[186:187], s[40:41], 0, v[158:159]
	s_mov_b32 m0, s46
	s_nop 0
	global_load_lds_dwordx4 v[186:187], off
	s_waitcnt vmcnt(8)
	s_waitcnt lgkmcnt(0)
	s_barrier
	s_setprio 1
	s_waitcnt lgkmcnt(0)
	v_mfma_f32_16x16x128_f8f6f4 v[134:137], v[2:9], v[216:223], v[134:137]
	v_mfma_f32_16x16x128_f8f6f4 v[130:133], v[192:199], v[216:223], v[130:133]
	v_mfma_f32_16x16x128_f8f6f4 v[122:125], v[192:199], v[224:231], v[122:125]
	v_mfma_f32_16x16x128_f8f6f4 v[126:129], v[2:9], v[224:231], v[126:129]
	v_mfma_f32_16x16x128_f8f6f4 v[118:121], v[2:9], v[232:239], v[118:121]
	v_mfma_f32_16x16x128_f8f6f4 v[114:117], v[192:199], v[232:239], v[114:117]
	v_mfma_f32_16x16x128_f8f6f4 v[106:109], v[192:199], v[240:247], v[106:109]
	v_mfma_f32_16x16x128_f8f6f4 v[110:113], v[2:9], v[240:247], v[110:113]
	s_setprio 0
	s_setprio 1
	v_mfma_f32_16x16x128_f8f6f4 v[78:81], v[200:207], v[240:247], v[78:81]
	v_mfma_f32_16x16x128_f8f6f4 v[74:77], v[208:215], v[240:247], v[74:77]
	v_mfma_f32_16x16x128_f8f6f4 v[82:85], v[208:215], v[232:239], v[82:85]
	v_mfma_f32_16x16x128_f8f6f4 v[86:89], v[200:207], v[232:239], v[86:89]
	v_mfma_f32_16x16x128_f8f6f4 v[94:97], v[200:207], v[224:231], v[94:97]
	v_mfma_f32_16x16x128_f8f6f4 v[90:93], v[208:215], v[224:231], v[90:93]
	v_mfma_f32_16x16x128_f8f6f4 v[98:101], v[208:215], v[216:223], v[98:101]
	v_mfma_f32_16x16x128_f8f6f4 v[102:105], v[200:207], v[216:223], v[102:105]
	s_setprio 0
	s_barrier
	s_mov_b32 m0, s52
	v_lshl_add_u64 v[174:175], v[174:175], 0, s[14:15]
	s_add_u32 s38, s38, 0x158080
	ds_read_b128 v[216:219], v190 offset:49152
	ds_read_b128 v[220:223], v190 offset:50176
	ds_read_b128 v[224:227], v190 offset:51200
	ds_read_b128 v[228:231], v190 offset:52224
	ds_read_b128 v[232:235], v190 offset:53248
	ds_read_b128 v[236:239], v190 offset:54272
	ds_read_b128 v[240:243], v190 offset:55296
	ds_read_b128 v[244:247], v190 offset:56320
	global_load_lds_dwordx4 v[174:175], off
	v_lshl_add_u64 v[174:175], v[176:177], 0, s[14:15]
	s_mov_b32 m0, s53
	s_addc_u32 s39, s39, 0
	global_load_lds_dwordx4 v[174:175], off
	v_lshl_add_u64 v[174:175], s[38:39], 0, v[156:157]
	s_mov_b32 m0, s56
	s_nop 0
	global_load_lds_dwordx4 v[174:175], off
	v_lshl_add_u64 v[174:175], s[38:39], 0, v[160:161]
	s_mov_b32 m0, s57
	s_nop 0
	global_load_lds_dwordx4 v[174:175], off
	v_lshl_add_u64 v[174:175], v[182:183], 0, s[14:15]
	s_mov_b32 m0, s54
	s_nop 0
	global_load_lds_dwordx4 v[174:175], off
	v_lshl_add_u64 v[174:175], v[184:185], 0, s[14:15]
	s_mov_b32 m0, s55
	s_nop 0
	global_load_lds_dwordx4 v[174:175], off
	s_waitcnt vmcnt(8)
	s_waitcnt lgkmcnt(0)
	s_barrier
	s_setprio 1
	s_waitcnt lgkmcnt(0)
	v_mfma_f32_16x16x128_f8f6f4 v[70:73], v[2:9], v[216:223], v[70:73]
	v_mfma_f32_16x16x128_f8f6f4 v[66:69], v[192:199], v[216:223], v[66:69]
	v_mfma_f32_16x16x128_f8f6f4 v[58:61], v[192:199], v[224:231], v[58:61]
	v_mfma_f32_16x16x128_f8f6f4 v[62:65], v[2:9], v[224:231], v[62:65]
	v_mfma_f32_16x16x128_f8f6f4 v[54:57], v[2:9], v[232:239], v[54:57]
	v_mfma_f32_16x16x128_f8f6f4 v[50:53], v[192:199], v[232:239], v[50:53]
	v_mfma_f32_16x16x128_f8f6f4 v[42:45], v[192:199], v[240:247], v[42:45]
	v_mfma_f32_16x16x128_f8f6f4 v[46:49], v[2:9], v[240:247], v[46:49]
	s_setprio 0
	s_setprio 1
	v_mfma_f32_16x16x128_f8f6f4 v[14:17], v[200:207], v[240:247], v[14:17]
	v_mfma_f32_16x16x128_f8f6f4 v[10:13], v[208:215], v[240:247], v[10:13]
	v_mfma_f32_16x16x128_f8f6f4 v[18:21], v[208:215], v[232:239], v[18:21]
	v_mfma_f32_16x16x128_f8f6f4 v[22:25], v[200:207], v[232:239], v[22:25]
	v_mfma_f32_16x16x128_f8f6f4 v[30:33], v[200:207], v[224:231], v[30:33]
	v_mfma_f32_16x16x128_f8f6f4 v[26:29], v[208:215], v[224:231], v[26:29]
	v_mfma_f32_16x16x128_f8f6f4 v[34:37], v[208:215], v[216:223], v[34:37]
	v_mfma_f32_16x16x128_f8f6f4 v[38:41], v[200:207], v[216:223], v[38:41]
	s_setprio 0
	s_barrier
	s_cmp_lt_u32 s82, 3
	s_cbranch_scc1 .LBB0_1036
	s_add_u32 s38, s48, s63
	s_addc_u32 s39, s49, s62
	s_add_u32 s36, s36, 0x158180
	s_addc_u32 s37, s37, 0
	s_add_u32 s40, s26, 0x200
	v_lshl_add_u64 v[174:175], v[172:173], 2, s[38:39]
	s_addc_u32 s41, s27, 0
	s_mov_b32 s84, 4
	s_cmp_eq_u32 s82, s84
	s_cselect_b64 s[26:27], -1, 0
	s_cmp_lg_u32 s82, s84
	s_cbranch_scc1 .LBB0_1034

.LBB0_1034:
	ds_read_b128 v[2:5], v189
	ds_read_b128 v[6:9], v189 offset:1024
	ds_read_b128 v[192:195], v189 offset:2048
	ds_read_b128 v[196:199], v189 offset:3072
	ds_read_b128 v[200:203], v189 offset:16384
	ds_read_b128 v[204:207], v189 offset:17408
	ds_read_b128 v[208:211], v189 offset:18432
	ds_read_b128 v[212:215], v189 offset:19456
	s_add_u32 s38, s36, 0xffea8080
	s_addc_u32 s39, s37, -1
	s_and_b64 s[26:27], s[26:27], exec
	s_cselect_b32 s26, s4, s40
	s_cselect_b32 s39, s1, s39
	s_cselect_b32 s38, s0, s38
	s_cselect_b32 s27, s5, s41
	s_mov_b32 m0, s25
	v_lshl_add_u64 v[176:177], s[36:37], 0, v[162:163]
	ds_read_b128 v[216:219], v190
	ds_read_b128 v[220:223], v190 offset:1024
	ds_read_b128 v[224:227], v190 offset:2048
	ds_read_b128 v[228:231], v190 offset:3072
	ds_read_b128 v[232:235], v190 offset:4096
	ds_read_b128 v[236:239], v190 offset:5120
	ds_read_b128 v[240:243], v190 offset:6144
	ds_read_b128 v[244:247], v190 offset:7168
	global_load_lds_dwordx4 v[176:177], off
	v_lshl_add_u64 v[176:177], s[36:37], 0, v[164:165]
	s_mov_b32 m0, s83
	s_nop 0
	global_load_lds_dwordx4 v[176:177], off
	s_waitcnt vmcnt(8)
	s_waitcnt lgkmcnt(0)
	s_barrier
	s_setprio 1
	s_waitcnt lgkmcnt(0)
	v_mfma_f32_16x16x128_f8f6f4 v[134:137], v[2:9], v[216:223], v[134:137]
	v_mfma_f32_16x16x128_f8f6f4 v[130:133], v[192:199], v[216:223], v[130:133]
	v_mfma_f32_16x16x128_f8f6f4 v[122:125], v[192:199], v[224:231], v[122:125]
	v_mfma_f32_16x16x128_f8f6f4 v[126:129], v[2:9], v[224:231], v[126:129]
	v_mfma_f32_16x16x128_f8f6f4 v[118:121], v[2:9], v[232:239], v[118:121]
	v_mfma_f32_16x16x128_f8f6f4 v[114:117], v[192:199], v[232:239], v[114:117]
	v_mfma_f32_16x16x128_f8f6f4 v[106:109], v[192:199], v[240:247], v[106:109]
	v_mfma_f32_16x16x128_f8f6f4 v[110:113], v[2:9], v[240:247], v[110:113]
	s_setprio 0
	s_setprio 1
	v_mfma_f32_16x16x128_f8f6f4 v[78:81], v[200:207], v[240:247], v[78:81]
	v_mfma_f32_16x16x128_f8f6f4 v[74:77], v[208:215], v[240:247], v[74:77]
	v_mfma_f32_16x16x128_f8f6f4 v[82:85], v[208:215], v[232:239], v[82:85]
	v_mfma_f32_16x16x128_f8f6f4 v[86:89], v[200:207], v[232:239], v[86:89]
	v_mfma_f32_16x16x128_f8f6f4 v[94:97], v[200:207], v[224:231], v[94:97]
	v_mfma_f32_16x16x128_f8f6f4 v[90:93], v[208:215], v[224:231], v[90:93]
	v_mfma_f32_16x16x128_f8f6f4 v[98:101], v[208:215], v[216:223], v[98:101]
	v_mfma_f32_16x16x128_f8f6f4 v[102:105], v[200:207], v[216:223], v[102:105]
	s_setprio 0
	s_barrier
	s_mov_b32 m0, s33
	v_lshl_add_u64 v[176:177], s[26:27], 0, v[156:157]
	s_add_u32 s62, s26, 0x158000
	ds_read_b128 v[216:219], v190 offset:16384
	ds_read_b128 v[220:223], v190 offset:17408
	ds_read_b128 v[224:227], v190 offset:18432
	ds_read_b128 v[228:231], v190 offset:19456
	ds_read_b128 v[232:235], v190 offset:20480
	ds_read_b128 v[236:239], v190 offset:21504
	ds_read_b128 v[240:243], v190 offset:22528
	ds_read_b128 v[244:247], v190 offset:23552
	global_load_lds_dwordx4 v[176:177], off
	v_lshl_add_u64 v[182:183], s[26:27], 0, v[160:161]
	s_mov_b32 m0, s35
	s_addc_u32 s63, s27, 0
	global_load_lds_dwordx4 v[182:183], off
	v_lshl_add_u64 v[184:185], s[62:63], 0, v[156:157]
	s_mov_b32 m0, s42
	v_lshl_add_u64 v[186:187], s[38:39], 0, v[158:159]
	global_load_lds_dwordx4 v[184:185], off
	v_lshl_add_u64 v[184:185], s[62:63], 0, v[160:161]
	s_mov_b32 m0, s43
	s_nop 0
	global_load_lds_dwordx4 v[184:185], off
	v_lshl_add_u64 v[184:185], s[38:39], 0, v[154:155]
	s_mov_b32 m0, s23
	s_nop 0
	global_load_lds_dwordx4 v[184:185], off
	s_mov_b32 m0, s44
	s_nop 0
	global_load_lds_dwordx4 v[186:187], off
	s_waitcnt vmcnt(8)
	s_waitcnt lgkmcnt(0)
	s_barrier
	s_setprio 1
	s_waitcnt lgkmcnt(0)
	v_mfma_f32_16x16x128_f8f6f4 v[70:73], v[2:9], v[216:223], v[70:73]
	v_mfma_f32_16x16x128_f8f6f4 v[66:69], v[192:199], v[216:223], v[66:69]
	v_mfma_f32_16x16x128_f8f6f4 v[58:61], v[192:199], v[224:231], v[58:61]
	v_mfma_f32_16x16x128_f8f6f4 v[62:65], v[2:9], v[224:231], v[62:65]
	v_mfma_f32_16x16x128_f8f6f4 v[54:57], v[2:9], v[232:239], v[54:57]
	v_mfma_f32_16x16x128_f8f6f4 v[50:53], v[192:199], v[232:239], v[50:53]
	v_mfma_f32_16x16x128_f8f6f4 v[42:45], v[192:199], v[240:247], v[42:45]
	v_mfma_f32_16x16x128_f8f6f4 v[46:49], v[2:9], v[240:247], v[46:49]
	s_setprio 0
	s_setprio 1
	v_mfma_f32_16x16x128_f8f6f4 v[14:17], v[200:207], v[240:247], v[14:17]
	v_mfma_f32_16x16x128_f8f6f4 v[10:13], v[208:215], v[240:247], v[10:13]
	v_mfma_f32_16x16x128_f8f6f4 v[18:21], v[208:215], v[232:239], v[18:21]
	v_mfma_f32_16x16x128_f8f6f4 v[22:25], v[200:207], v[232:239], v[22:25]
	v_mfma_f32_16x16x128_f8f6f4 v[30:33], v[200:207], v[224:231], v[30:33]
	v_mfma_f32_16x16x128_f8f6f4 v[26:29], v[208:215], v[224:231], v[26:29]
	v_mfma_f32_16x16x128_f8f6f4 v[34:37], v[208:215], v[216:223], v[34:37]
	v_mfma_f32_16x16x128_f8f6f4 v[38:41], v[200:207], v[216:223], v[38:41]
	s_setprio 0
	s_barrier
	ds_read_b128 v[192:195], v189 offset:32768
	ds_read_b128 v[196:199], v189 offset:33792
	ds_read_b128 v[200:203], v189 offset:34816
	ds_read_b128 v[204:207], v189 offset:35840
	ds_read_b128 v[2:5], v189 offset:49152
	ds_read_b128 v[6:9], v189 offset:50176
	ds_read_b128 v[208:211], v189 offset:51200
	ds_read_b128 v[212:215], v189 offset:52224
	s_add_u32 s38, s38, 0x158000
	s_addc_u32 s39, s39, 0
	s_mov_b32 m0, s45
	v_lshl_add_u64 v[248:249], s[38:39], 0, v[154:155]
	ds_read_b128 v[216:219], v190 offset:32768
	ds_read_b128 v[220:223], v190 offset:33792
	ds_read_b128 v[224:227], v190 offset:34816
	ds_read_b128 v[228:231], v190 offset:35840
	ds_read_b128 v[232:235], v190 offset:36864
	ds_read_b128 v[236:239], v190 offset:37888
	ds_read_b128 v[240:243], v190 offset:38912
	ds_read_b128 v[244:247], v190 offset:39936
	global_load_lds_dwordx4 v[248:249], off
	v_lshl_add_u64 v[248:249], s[38:39], 0, v[158:159]
	s_mov_b32 m0, s46
	s_nop 0
	global_load_lds_dwordx4 v[248:249], off
	s_waitcnt vmcnt(8)
	s_waitcnt lgkmcnt(0)
	s_barrier
	s_setprio 1
	s_waitcnt lgkmcnt(0)
	v_mfma_f32_16x16x128_f8f6f4 v[134:137], v[192:199], v[216:223], v[134:137]
	v_mfma_f32_16x16x128_f8f6f4 v[130:133], v[200:207], v[216:223], v[130:133]
	v_mfma_f32_16x16x128_f8f6f4 v[122:125], v[200:207], v[224:231], v[122:125]
	v_mfma_f32_16x16x128_f8f6f4 v[126:129], v[192:199], v[224:231], v[126:129]
	v_mfma_f32_16x16x128_f8f6f4 v[118:121], v[192:199], v[232:239], v[118:121]
	v_mfma_f32_16x16x128_f8f6f4 v[114:117], v[200:207], v[232:239], v[114:117]
	v_mfma_f32_16x16x128_f8f6f4 v[106:109], v[200:207], v[240:247], v[106:109]
	v_mfma_f32_16x16x128_f8f6f4 v[110:113], v[192:199], v[240:247], v[110:113]
	s_setprio 0
	s_setprio 1
	v_mfma_f32_16x16x128_f8f6f4 v[78:81], v[2:9], v[240:247], v[78:81]
	v_mfma_f32_16x16x128_f8f6f4 v[74:77], v[208:215], v[240:247], v[74:77]
	v_mfma_f32_16x16x128_f8f6f4 v[82:85], v[208:215], v[232:239], v[82:85]
	v_mfma_f32_16x16x128_f8f6f4 v[86:89], v[2:9], v[232:239], v[86:89]
	v_mfma_f32_16x16x128_f8f6f4 v[94:97], v[2:9], v[224:231], v[94:97]
	v_mfma_f32_16x16x128_f8f6f4 v[90:93], v[208:215], v[224:231], v[90:93]
	v_mfma_f32_16x16x128_f8f6f4 v[98:101], v[208:215], v[216:223], v[98:101]
	v_mfma_f32_16x16x128_f8f6f4 v[102:105], v[2:9], v[216:223], v[102:105]
	s_setprio 0
	s_barrier
	s_mov_b32 m0, s52
	v_lshl_add_u64 v[176:177], v[176:177], 0, s[14:15]
	s_add_u32 s26, s26, 0x158080
	ds_read_b128 v[216:219], v190 offset:49152
	ds_read_b128 v[220:223], v190 offset:50176
	ds_read_b128 v[224:227], v190 offset:51200
	ds_read_b128 v[228:231], v190 offset:52224
	ds_read_b128 v[232:235], v190 offset:53248
	ds_read_b128 v[236:239], v190 offset:54272
	ds_read_b128 v[240:243], v190 offset:55296
	ds_read_b128 v[244:247], v190 offset:56320
	global_load_lds_dwordx4 v[176:177], off
	v_lshl_add_u64 v[176:177], v[182:183], 0, s[14:15]
	s_mov_b32 m0, s53
	s_addc_u32 s27, s27, 0
	global_load_lds_dwordx4 v[176:177], off
	v_lshl_add_u64 v[176:177], s[26:27], 0, v[156:157]
	s_mov_b32 m0, s56
	s_nop 0
	global_load_lds_dwordx4 v[176:177], off
	v_lshl_add_u64 v[176:177], s[26:27], 0, v[160:161]
	s_mov_b32 m0, s57
	s_nop 0
	global_load_lds_dwordx4 v[176:177], off
	v_lshl_add_u64 v[176:177], v[184:185], 0, s[14:15]
	s_mov_b32 m0, s54
	s_nop 0
	global_load_lds_dwordx4 v[176:177], off
	v_lshl_add_u64 v[176:177], v[186:187], 0, s[14:15]
	s_mov_b32 m0, s55
	s_nop 0
	global_load_lds_dwordx4 v[176:177], off
	s_waitcnt vmcnt(8)
	s_waitcnt lgkmcnt(0)
	s_barrier
	s_setprio 1
	s_waitcnt lgkmcnt(0)
	v_mfma_f32_16x16x128_f8f6f4 v[70:73], v[192:199], v[216:223], v[70:73]
	v_mfma_f32_16x16x128_f8f6f4 v[66:69], v[200:207], v[216:223], v[66:69]
	v_mfma_f32_16x16x128_f8f6f4 v[58:61], v[200:207], v[224:231], v[58:61]
	v_mfma_f32_16x16x128_f8f6f4 v[62:65], v[192:199], v[224:231], v[62:65]
	v_mfma_f32_16x16x128_f8f6f4 v[54:57], v[192:199], v[232:239], v[54:57]
	v_mfma_f32_16x16x128_f8f6f4 v[50:53], v[200:207], v[232:239], v[50:53]
	v_mfma_f32_16x16x128_f8f6f4 v[42:45], v[200:207], v[240:247], v[42:45]
	v_mfma_f32_16x16x128_f8f6f4 v[46:49], v[192:199], v[240:247], v[46:49]
	s_setprio 0
	s_setprio 1
	v_mfma_f32_16x16x128_f8f6f4 v[14:17], v[2:9], v[240:247], v[14:17]
	v_mfma_f32_16x16x128_f8f6f4 v[10:13], v[208:215], v[240:247], v[10:13]
	v_mfma_f32_16x16x128_f8f6f4 v[18:21], v[208:215], v[232:239], v[18:21]
	v_mfma_f32_16x16x128_f8f6f4 v[22:25], v[2:9], v[232:239], v[22:25]
	v_mfma_f32_16x16x128_f8f6f4 v[30:33], v[2:9], v[224:231], v[30:33]
	v_mfma_f32_16x16x128_f8f6f4 v[26:29], v[208:215], v[224:231], v[26:29]
	v_mfma_f32_16x16x128_f8f6f4 v[34:37], v[208:215], v[216:223], v[34:37]
	v_mfma_f32_16x16x128_f8f6f4 v[38:41], v[2:9], v[216:223], v[38:41]
	s_setprio 0
	s_barrier
	s_add_i32 s26, s84, 2
	s_add_u32 s36, s36, 0x100
	s_addc_u32 s37, s37, 0
	s_add_u32 s40, s40, 0x100
	s_addc_u32 s41, s41, 0
	s_cmp_ge_i32 s84, s82
	s_cbranch_scc1 .LBB0_1036
	s_mov_b32 s84, s26
	s_cmp_eq_u32 s82, s84
	s_cselect_b64 s[26:27], -1, 0
	s_cmp_lg_u32 s82, s84
	s_cbranch_scc0 .LBB0_1033
	s_branch .LBB0_1034
